# 1.0/x in sigmoid/silu: hipcc IEEE division expansion (11 VALU incl. div_scale/div_fmas/div_fixup) replaced by v_rcp_f32 (f32, 1 ulp), 323 sites
# speedup vs baseline: 1.0842x; 1.0286x over previous
.LBB0_322:
	s_cmp_gt_i32 s25, 5
	s_mov_b64 s[0:1], -1
	s_cbranch_scc0 .LBB0_328
	s_cmp_lg_u32 s25, 6
	v_ashrrev_i32_e32 v151, 31, v150
	s_cbranch_scc0 .LBB0_325
	v_readlane_b32 s28, v254, 34
	v_lshlrev_b64 v[154:155], 13, v[150:151]
	v_readlane_b32 s29, v254, 35
	v_mul_f32_e32 v128, 0xbfb8aa3b, v60
	s_nop 0
	v_lshl_add_u64 v[158:159], s[28:29], 0, v[154:155]
	v_exp_f32_e32 v154, v128
	v_mul_f32_e32 v128, 0xbfb8aa3b, v61
	v_exp_f32_e32 v155, v128
	s_nop 0
	v_pk_add_f32 v[154:155], v[154:155], 1.0 op_sel_hi:[1,0]
	s_nop 0
	s_nop 0
	v_rcp_f32_e32 v128, v155
	s_nop 0
	s_nop 0
	v_rcp_f32_e32 v153, v154
	s_nop 0
	v_mul_f32_e32 v154, 0xbfb8aa3b, v62
	v_mul_f32_e32 v155, 0xbfb8aa3b, v63
	v_exp_f32_e32 v154, v154
	v_exp_f32_e32 v155, v155
	s_nop 0
	v_pk_add_f32 v[154:155], v[154:155], 1.0 op_sel_hi:[1,0]
	s_nop 0
	s_nop 0
	v_rcp_f32_e32 v155, v155
	s_nop 0
	s_movk_i32 s0, 0x9000
	s_mov_b32 s1, -1
	v_cvt_pk_bf16_f32 v160, v153, v128
	v_mul_f32_e32 v128, 0xbfb8aa3b, v56
	v_exp_f32_e32 v162, v128
	v_mul_f32_e32 v128, 0xbfb8aa3b, v57
	v_exp_f32_e32 v163, v128
	v_ashrrev_i32_e32 v153, 31, v152
	v_rcp_f32_e32 v154, v154
	s_nop 0
	v_lshlrev_b64 v[156:157], 1, v[152:153]
	v_pk_add_f32 v[162:163], v[162:163], 1.0 op_sel_hi:[1,0]
	v_cvt_pk_bf16_f32 v161, v154, v155
	v_lshl_add_u64 v[154:155], v[156:157], 0, s[0:1]
	v_lshl_add_u64 v[164:165], v[158:159], 0, v[154:155]
	v_rcp_f32_e32 v128, v163
	s_nop 0
	s_nop 0
	v_rcp_f32_e32 v153, v162
	s_nop 0
	v_mul_f32_e32 v162, 0xbfb8aa3b, v58
	v_mul_f32_e32 v163, 0xbfb8aa3b, v59
	v_exp_f32_e32 v162, v162
	v_exp_f32_e32 v163, v163
	s_nop 0
	v_pk_add_f32 v[162:163], v[162:163], 1.0 op_sel_hi:[1,0]
	s_nop 0
	s_nop 0
	v_rcp_f32_e32 v163, v163
	s_nop 0
	s_nop 0
	v_rcp_f32_e32 v166, v162
	s_nop 0
	v_cvt_pk_bf16_f32 v162, v153, v128
	v_cvt_pk_bf16_f32 v163, v166, v163
	v_mul_f32_e32 v128, 0xbfb8aa3b, v124
	global_store_dwordx4 v[164:165], v[160:163], off
	s_nop 1
	v_exp_f32_e32 v160, v128
	v_mul_f32_e32 v128, 0xbfb8aa3b, v125
	v_exp_f32_e32 v161, v128
	s_nop 0
	v_pk_add_f32 v[160:161], v[160:161], 1.0 op_sel_hi:[1,0]
	s_nop 0
	s_nop 0
	v_rcp_f32_e32 v128, v161
	s_nop 0
	s_nop 0
	v_rcp_f32_e32 v153, v160
	s_nop 0
	v_mul_f32_e32 v160, 0xbfb8aa3b, v126
	v_mul_f32_e32 v161, 0xbfb8aa3b, v127
	v_exp_f32_e32 v160, v160
	v_exp_f32_e32 v161, v161
	s_nop 0
	v_pk_add_f32 v[160:161], v[160:161], 1.0 op_sel_hi:[1,0]
	s_nop 0
	s_nop 0
	v_rcp_f32_e32 v161, v161
	s_nop 0
	s_movk_i32 s0, 0x9100
	s_mov_b32 s1, -1
	v_lshl_add_u64 v[156:157], v[156:157], 0, s[0:1]
	v_rcp_f32_e32 v162, v160
	s_nop 0
	v_cvt_pk_bf16_f32 v160, v153, v128
	v_mul_f32_e32 v128, 0xbfb8aa3b, v120
	v_cvt_pk_bf16_f32 v161, v162, v161
	v_exp_f32_e32 v162, v128
	v_mul_f32_e32 v128, 0xbfb8aa3b, v121
	v_exp_f32_e32 v163, v128
	v_lshl_add_u64 v[164:165], v[158:159], 0, v[156:157]
	v_pk_add_f32 v[162:163], v[162:163], 1.0 op_sel_hi:[1,0]
	s_nop 0
	s_nop 0
	v_rcp_f32_e32 v128, v163
	s_nop 0
	s_nop 0
	v_rcp_f32_e32 v153, v162
	s_nop 0
	v_mul_f32_e32 v162, 0xbfb8aa3b, v122
	v_mul_f32_e32 v163, 0xbfb8aa3b, v123
	v_exp_f32_e32 v162, v162
	v_exp_f32_e32 v163, v163
	s_nop 0
	v_pk_add_f32 v[162:163], v[162:163], 1.0 op_sel_hi:[1,0]
	s_nop 0
	s_nop 0
	v_rcp_f32_e32 v163, v163
	s_nop 0
	s_nop 0
	v_rcp_f32_e32 v166, v162
	s_nop 0
	v_cvt_pk_bf16_f32 v162, v153, v128
	v_cvt_pk_bf16_f32 v163, v166, v163
	v_mul_f32_e32 v128, 0xbfb8aa3b, v52
	global_store_dwordx4 v[164:165], v[160:163], off
	s_nop 1
	v_exp_f32_e32 v162, v128
	v_mul_f32_e32 v128, 0xbfb8aa3b, v53
	v_exp_f32_e32 v163, v128
	v_or_b32_e32 v160, 16, v150
	v_ashrrev_i32_e32 v161, 31, v160
	v_lshlrev_b64 v[160:161], 13, v[160:161]
	v_pk_add_f32 v[162:163], v[162:163], 1.0 op_sel_hi:[1,0]
	v_lshl_add_u64 v[160:161], s[28:29], 0, v[160:161]
	s_nop 0
	v_rcp_f32_e32 v128, v163
	s_nop 0
	s_nop 0
	v_rcp_f32_e32 v153, v162
	s_nop 0
	v_mul_f32_e32 v162, 0xbfb8aa3b, v54
	v_mul_f32_e32 v163, 0xbfb8aa3b, v55
	v_exp_f32_e32 v162, v162
	v_exp_f32_e32 v163, v163
	s_nop 0
	v_pk_add_f32 v[162:163], v[162:163], 1.0 op_sel_hi:[1,0]
	s_nop 0
	s_nop 0
	v_rcp_f32_e32 v163, v163
	s_nop 0
	s_nop 0
	v_rcp_f32_e32 v164, v162
	s_nop 0
	v_cvt_pk_bf16_f32 v162, v153, v128
	v_mul_f32_e32 v128, 0xbfb8aa3b, v48
	v_cvt_pk_bf16_f32 v163, v164, v163
	v_exp_f32_e32 v164, v128
	v_mul_f32_e32 v128, 0xbfb8aa3b, v49
	v_exp_f32_e32 v165, v128
	v_lshl_add_u64 v[166:167], v[160:161], 0, v[154:155]
	v_lshl_add_u64 v[160:161], v[160:161], 0, v[156:157]
	v_pk_add_f32 v[164:165], v[164:165], 1.0 op_sel_hi:[1,0]
	s_nop 0
	s_nop 0
	v_rcp_f32_e32 v128, v165
	s_nop 0
	s_nop 0
	v_rcp_f32_e32 v153, v164
	s_nop 0
	v_mul_f32_e32 v164, 0xbfb8aa3b, v50
	v_mul_f32_e32 v165, 0xbfb8aa3b, v51
	v_exp_f32_e32 v164, v164
	v_exp_f32_e32 v165, v165
	s_nop 0
	v_pk_add_f32 v[164:165], v[164:165], 1.0 op_sel_hi:[1,0]
	s_nop 0
	s_nop 0
	v_rcp_f32_e32 v165, v165
	s_nop 0
	s_nop 0
	v_rcp_f32_e32 v168, v164
	s_nop 0
	v_cvt_pk_bf16_f32 v164, v153, v128
	v_cvt_pk_bf16_f32 v165, v168, v165
	v_mul_f32_e32 v128, 0xbfb8aa3b, v116
	global_store_dwordx4 v[166:167], v[162:165], off
	s_nop 1
	v_exp_f32_e32 v162, v128
	v_mul_f32_e32 v128, 0xbfb8aa3b, v117
	v_exp_f32_e32 v163, v128
	s_nop 0
	v_pk_add_f32 v[162:163], v[162:163], 1.0 op_sel_hi:[1,0]
	s_nop 0
	s_nop 0
	v_rcp_f32_e32 v128, v163
	s_nop 0
	s_nop 0
	v_rcp_f32_e32 v153, v162
	s_nop 0
	v_mul_f32_e32 v162, 0xbfb8aa3b, v118
	v_mul_f32_e32 v163, 0xbfb8aa3b, v119
	v_exp_f32_e32 v162, v162
	v_exp_f32_e32 v163, v163
	s_nop 0
	v_pk_add_f32 v[162:163], v[162:163], 1.0 op_sel_hi:[1,0]
	s_nop 0
	s_nop 0
	v_rcp_f32_e32 v163, v163
	s_nop 0
	s_nop 0
	v_rcp_f32_e32 v164, v162
	s_nop 0
	v_cvt_pk_bf16_f32 v162, v153, v128
	v_mul_f32_e32 v128, 0xbfb8aa3b, v112
	v_cvt_pk_bf16_f32 v163, v164, v163
	v_exp_f32_e32 v164, v128
	v_mul_f32_e32 v128, 0xbfb8aa3b, v113
	v_exp_f32_e32 v165, v128
	s_nop 0
	v_pk_add_f32 v[164:165], v[164:165], 1.0 op_sel_hi:[1,0]
	s_nop 0
	s_nop 0
	v_rcp_f32_e32 v128, v165
	s_nop 0
	s_nop 0
	v_rcp_f32_e32 v153, v164
	s_nop 0
	v_mul_f32_e32 v164, 0xbfb8aa3b, v114
	v_mul_f32_e32 v165, 0xbfb8aa3b, v115
	v_exp_f32_e32 v164, v164
	v_exp_f32_e32 v165, v165
	s_nop 0
	v_pk_add_f32 v[164:165], v[164:165], 1.0 op_sel_hi:[1,0]
	s_nop 0
	s_nop 0
	v_rcp_f32_e32 v165, v165
	s_nop 0
	s_nop 0
	v_rcp_f32_e32 v166, v164
	s_nop 0
	v_cvt_pk_bf16_f32 v164, v153, v128
	v_cvt_pk_bf16_f32 v165, v166, v165
	v_mul_f32_e32 v128, 0xbfb8aa3b, v44
	global_store_dwordx4 v[160:161], v[162:165], off
	v_or_b32_e32 v160, 32, v150
	v_ashrrev_i32_e32 v161, 31, v160
	v_exp_f32_e32 v162, v128
	v_mul_f32_e32 v128, 0xbfb8aa3b, v45
	v_exp_f32_e32 v163, v128
	v_lshlrev_b64 v[160:161], 13, v[160:161]
	v_lshl_add_u64 v[160:161], s[28:29], 0, v[160:161]
	v_pk_add_f32 v[162:163], v[162:163], 1.0 op_sel_hi:[1,0]
	s_nop 0
	s_nop 0
	v_rcp_f32_e32 v128, v163
	s_nop 0
	s_nop 0
	v_rcp_f32_e32 v153, v162
	s_nop 0
	v_mul_f32_e32 v162, 0xbfb8aa3b, v46
	v_mul_f32_e32 v163, 0xbfb8aa3b, v47
	v_exp_f32_e32 v162, v162
	v_exp_f32_e32 v163, v163
	s_nop 0
	v_pk_add_f32 v[162:163], v[162:163], 1.0 op_sel_hi:[1,0]
	s_nop 0
	s_nop 0
	v_rcp_f32_e32 v163, v163
	s_nop 0
	s_nop 0
	v_rcp_f32_e32 v164, v162
	s_nop 0
	v_cvt_pk_bf16_f32 v162, v153, v128
	v_mul_f32_e32 v128, 0xbfb8aa3b, v40
	v_cvt_pk_bf16_f32 v163, v164, v163
	v_exp_f32_e32 v164, v128
	v_mul_f32_e32 v128, 0xbfb8aa3b, v41
	v_exp_f32_e32 v165, v128
	v_lshl_add_u64 v[166:167], v[160:161], 0, v[154:155]
	v_lshl_add_u64 v[160:161], v[160:161], 0, v[156:157]
	v_pk_add_f32 v[164:165], v[164:165], 1.0 op_sel_hi:[1,0]
	s_nop 0
	s_nop 0
	v_rcp_f32_e32 v128, v165
	s_nop 0
	s_nop 0
	v_rcp_f32_e32 v153, v164
	s_nop 0
	v_mul_f32_e32 v164, 0xbfb8aa3b, v42
	v_mul_f32_e32 v165, 0xbfb8aa3b, v43
	v_exp_f32_e32 v164, v164
	v_exp_f32_e32 v165, v165
	s_nop 0
	v_pk_add_f32 v[164:165], v[164:165], 1.0 op_sel_hi:[1,0]
	s_nop 0
	s_nop 0
	v_rcp_f32_e32 v165, v165
	s_nop 0
	s_nop 0
	v_rcp_f32_e32 v168, v164
	s_nop 0
	v_cvt_pk_bf16_f32 v164, v153, v128
	v_cvt_pk_bf16_f32 v165, v168, v165
	v_mul_f32_e32 v128, 0xbfb8aa3b, v108
	global_store_dwordx4 v[166:167], v[162:165], off
	s_nop 1
	v_exp_f32_e32 v162, v128
	v_mul_f32_e32 v128, 0xbfb8aa3b, v109
	v_exp_f32_e32 v163, v128
	s_nop 0
	v_pk_add_f32 v[162:163], v[162:163], 1.0 op_sel_hi:[1,0]
	s_nop 0
	s_nop 0
	v_rcp_f32_e32 v128, v163
	s_nop 0
	s_nop 0
	v_rcp_f32_e32 v153, v162
	s_nop 0
	v_mul_f32_e32 v162, 0xbfb8aa3b, v110
	v_mul_f32_e32 v163, 0xbfb8aa3b, v111
	v_exp_f32_e32 v162, v162
	v_exp_f32_e32 v163, v163
	s_nop 0
	v_pk_add_f32 v[162:163], v[162:163], 1.0 op_sel_hi:[1,0]
	s_nop 0
	s_nop 0
	v_rcp_f32_e32 v163, v163
	s_nop 0
	s_nop 0
	v_rcp_f32_e32 v164, v162
	s_nop 0
	v_cvt_pk_bf16_f32 v162, v153, v128
	v_mul_f32_e32 v128, 0xbfb8aa3b, v104
	v_cvt_pk_bf16_f32 v163, v164, v163
	v_exp_f32_e32 v164, v128
	v_mul_f32_e32 v128, 0xbfb8aa3b, v105
	v_exp_f32_e32 v165, v128
	s_nop 0
	v_pk_add_f32 v[164:165], v[164:165], 1.0 op_sel_hi:[1,0]
	s_nop 0
	s_nop 0
	v_rcp_f32_e32 v128, v165
	s_nop 0
	s_nop 0
	v_rcp_f32_e32 v153, v164
	s_nop 0
	v_mul_f32_e32 v164, 0xbfb8aa3b, v106
	v_mul_f32_e32 v165, 0xbfb8aa3b, v107
	v_exp_f32_e32 v164, v164
	v_exp_f32_e32 v165, v165
	s_nop 0
	v_pk_add_f32 v[164:165], v[164:165], 1.0 op_sel_hi:[1,0]
	s_nop 0
	s_nop 0
	v_rcp_f32_e32 v165, v165
	s_nop 0
	s_nop 0
	v_rcp_f32_e32 v166, v164
	s_nop 0
	v_cvt_pk_bf16_f32 v164, v153, v128
	v_cvt_pk_bf16_f32 v165, v166, v165
	v_mul_f32_e32 v128, 0xbfb8aa3b, v36
	global_store_dwordx4 v[160:161], v[162:165], off
	v_or_b32_e32 v160, 48, v150
	v_ashrrev_i32_e32 v161, 31, v160
	v_exp_f32_e32 v162, v128
	v_mul_f32_e32 v128, 0xbfb8aa3b, v37
	v_exp_f32_e32 v163, v128
	v_lshlrev_b64 v[160:161], 13, v[160:161]
	v_lshl_add_u64 v[160:161], s[28:29], 0, v[160:161]
	v_pk_add_f32 v[162:163], v[162:163], 1.0 op_sel_hi:[1,0]
	s_nop 0
	s_nop 0
	v_rcp_f32_e32 v128, v163
	s_nop 0
	s_nop 0
	v_rcp_f32_e32 v153, v162
	s_nop 0
	v_mul_f32_e32 v162, 0xbfb8aa3b, v38
	v_mul_f32_e32 v163, 0xbfb8aa3b, v39
	v_exp_f32_e32 v162, v162
	v_exp_f32_e32 v163, v163
	s_nop 0
	v_pk_add_f32 v[162:163], v[162:163], 1.0 op_sel_hi:[1,0]
	s_nop 0
	s_nop 0
	v_rcp_f32_e32 v163, v163
	s_nop 0
	s_nop 0
	v_rcp_f32_e32 v164, v162
	s_nop 0
	v_cvt_pk_bf16_f32 v162, v153, v128
	v_mul_f32_e32 v128, 0xbfb8aa3b, v32
	v_cvt_pk_bf16_f32 v163, v164, v163
	v_exp_f32_e32 v164, v128
	v_mul_f32_e32 v128, 0xbfb8aa3b, v33
	v_exp_f32_e32 v165, v128
	v_lshl_add_u64 v[166:167], v[160:161], 0, v[154:155]
	v_lshl_add_u64 v[160:161], v[160:161], 0, v[156:157]
	v_pk_add_f32 v[164:165], v[164:165], 1.0 op_sel_hi:[1,0]
	s_nop 0
	s_nop 0
	v_rcp_f32_e32 v128, v165
	s_nop 0
	s_nop 0
	v_rcp_f32_e32 v153, v164
	s_nop 0
	v_mul_f32_e32 v164, 0xbfb8aa3b, v34
	v_mul_f32_e32 v165, 0xbfb8aa3b, v35
	v_exp_f32_e32 v164, v164
	v_exp_f32_e32 v165, v165
	s_nop 0
	v_pk_add_f32 v[164:165], v[164:165], 1.0 op_sel_hi:[1,0]
	s_nop 0
	s_nop 0
	v_rcp_f32_e32 v165, v165
	s_nop 0
	s_nop 0
	v_rcp_f32_e32 v168, v164
	s_nop 0
	v_cvt_pk_bf16_f32 v164, v153, v128
	v_cvt_pk_bf16_f32 v165, v168, v165
	v_mul_f32_e32 v128, 0xbfb8aa3b, v100
	global_store_dwordx4 v[166:167], v[162:165], off
	s_nop 1
	v_exp_f32_e32 v162, v128
	v_mul_f32_e32 v128, 0xbfb8aa3b, v101
	v_exp_f32_e32 v163, v128
	s_nop 0
	v_pk_add_f32 v[162:163], v[162:163], 1.0 op_sel_hi:[1,0]
	s_nop 0
	s_nop 0
	v_rcp_f32_e32 v128, v163
	s_nop 0
	s_nop 0
	v_rcp_f32_e32 v153, v162
	s_nop 0
	v_mul_f32_e32 v162, 0xbfb8aa3b, v102
	v_mul_f32_e32 v163, 0xbfb8aa3b, v103
	v_exp_f32_e32 v162, v162
	v_exp_f32_e32 v163, v163
	s_nop 0
	v_pk_add_f32 v[162:163], v[162:163], 1.0 op_sel_hi:[1,0]
	s_nop 0
	s_nop 0
	v_rcp_f32_e32 v163, v163
	s_nop 0
	s_nop 0
	v_rcp_f32_e32 v164, v162
	s_nop 0
	v_cvt_pk_bf16_f32 v162, v153, v128
	v_mul_f32_e32 v128, 0xbfb8aa3b, v96
	v_cvt_pk_bf16_f32 v163, v164, v163
	v_exp_f32_e32 v164, v128
	v_mul_f32_e32 v128, 0xbfb8aa3b, v97
	v_exp_f32_e32 v165, v128
	s_nop 0
	v_pk_add_f32 v[164:165], v[164:165], 1.0 op_sel_hi:[1,0]
	s_nop 0
	s_nop 0
	v_rcp_f32_e32 v128, v165
	s_nop 0
	s_nop 0
	v_rcp_f32_e32 v153, v164
	s_nop 0
	v_mul_f32_e32 v164, 0xbfb8aa3b, v98
	v_mul_f32_e32 v165, 0xbfb8aa3b, v99
	v_exp_f32_e32 v164, v164
	v_exp_f32_e32 v165, v165
	s_nop 0
	v_pk_add_f32 v[164:165], v[164:165], 1.0 op_sel_hi:[1,0]
	s_nop 0
	s_nop 0
	v_rcp_f32_e32 v165, v165
	s_nop 0
	s_mov_b64 s[0:1], 0x100000
	v_rcp_f32_e32 v166, v164
	s_nop 0
	v_cvt_pk_bf16_f32 v164, v153, v128
	v_cvt_pk_bf16_f32 v165, v166, v165
	v_mul_f32_e32 v128, 0xbfb8aa3b, v28
	global_store_dwordx4 v[160:161], v[162:165], off
	v_lshl_add_u64 v[160:161], v[158:159], 0, s[0:1]
	s_nop 0
	v_exp_f32_e32 v162, v128
	v_mul_f32_e32 v128, 0xbfb8aa3b, v29
	v_exp_f32_e32 v163, v128
	s_nop 0
	v_pk_add_f32 v[162:163], v[162:163], 1.0 op_sel_hi:[1,0]
	s_nop 0
	s_nop 0
	v_rcp_f32_e32 v128, v163
	s_nop 0
	s_nop 0
	v_rcp_f32_e32 v153, v162
	s_nop 0
	v_mul_f32_e32 v162, 0xbfb8aa3b, v30
	v_mul_f32_e32 v163, 0xbfb8aa3b, v31
	v_exp_f32_e32 v162, v162
	v_exp_f32_e32 v163, v163
	s_nop 0
	v_pk_add_f32 v[162:163], v[162:163], 1.0 op_sel_hi:[1,0]
	s_nop 0
	s_nop 0
	v_rcp_f32_e32 v163, v163
	s_nop 0
	s_nop 0
	v_rcp_f32_e32 v164, v162
	s_nop 0
	v_cvt_pk_bf16_f32 v162, v153, v128
	v_mul_f32_e32 v128, 0xbfb8aa3b, v24
	v_cvt_pk_bf16_f32 v163, v164, v163
	v_exp_f32_e32 v164, v128
	v_mul_f32_e32 v128, 0xbfb8aa3b, v25
	v_exp_f32_e32 v165, v128
	v_lshl_add_u64 v[166:167], v[160:161], 0, v[154:155]
	v_lshl_add_u64 v[160:161], v[160:161], 0, v[156:157]
	v_pk_add_f32 v[164:165], v[164:165], 1.0 op_sel_hi:[1,0]
	s_nop 0
	s_nop 0
	v_rcp_f32_e32 v128, v165
	s_nop 0
	s_nop 0
	v_rcp_f32_e32 v153, v164
	s_nop 0
	v_mul_f32_e32 v164, 0xbfb8aa3b, v26
	v_mul_f32_e32 v165, 0xbfb8aa3b, v27
	v_exp_f32_e32 v164, v164
	v_exp_f32_e32 v165, v165
	s_nop 0
	v_pk_add_f32 v[164:165], v[164:165], 1.0 op_sel_hi:[1,0]
	s_nop 0
	s_nop 0
	v_rcp_f32_e32 v165, v165
	s_nop 0
	s_nop 0
	v_rcp_f32_e32 v168, v164
	s_nop 0
	v_cvt_pk_bf16_f32 v164, v153, v128
	v_cvt_pk_bf16_f32 v165, v168, v165
	v_mul_f32_e32 v128, 0xbfb8aa3b, v92
	global_store_dwordx4 v[166:167], v[162:165], off
	s_nop 1
	v_exp_f32_e32 v162, v128
	v_mul_f32_e32 v128, 0xbfb8aa3b, v93
	v_exp_f32_e32 v163, v128
	s_nop 0
	v_pk_add_f32 v[162:163], v[162:163], 1.0 op_sel_hi:[1,0]
	s_nop 0
	s_nop 0
	v_rcp_f32_e32 v128, v163
	s_nop 0
	s_nop 0
	v_rcp_f32_e32 v153, v162
	s_nop 0
	v_mul_f32_e32 v162, 0xbfb8aa3b, v94
	v_mul_f32_e32 v163, 0xbfb8aa3b, v95
	v_exp_f32_e32 v162, v162
	v_exp_f32_e32 v163, v163
	s_nop 0
	v_pk_add_f32 v[162:163], v[162:163], 1.0 op_sel_hi:[1,0]
	s_nop 0
	s_nop 0
	v_rcp_f32_e32 v163, v163
	s_nop 0
	s_nop 0
	v_rcp_f32_e32 v164, v162
	s_nop 0
	v_cvt_pk_bf16_f32 v162, v153, v128
	v_mul_f32_e32 v128, 0xbfb8aa3b, v88
	v_cvt_pk_bf16_f32 v163, v164, v163
	v_exp_f32_e32 v164, v128
	v_mul_f32_e32 v128, 0xbfb8aa3b, v89
	v_exp_f32_e32 v165, v128
	s_nop 0
	v_pk_add_f32 v[164:165], v[164:165], 1.0 op_sel_hi:[1,0]
	s_nop 0
	s_nop 0
	v_rcp_f32_e32 v128, v165
	s_nop 0
	s_nop 0
	v_rcp_f32_e32 v153, v164
	s_nop 0
	v_mul_f32_e32 v164, 0xbfb8aa3b, v90
	v_mul_f32_e32 v165, 0xbfb8aa3b, v91
	v_exp_f32_e32 v164, v164
	v_exp_f32_e32 v165, v165
	s_nop 0
	v_pk_add_f32 v[164:165], v[164:165], 1.0 op_sel_hi:[1,0]
	s_nop 0
	s_nop 0
	v_rcp_f32_e32 v165, v165
	s_nop 0
	s_mov_b64 s[0:1], 0x120000
	v_rcp_f32_e32 v166, v164
	s_nop 0
	v_cvt_pk_bf16_f32 v164, v153, v128
	v_cvt_pk_bf16_f32 v165, v166, v165
	v_mul_f32_e32 v128, 0xbfb8aa3b, v20
	global_store_dwordx4 v[160:161], v[162:165], off
	v_lshl_add_u64 v[160:161], v[158:159], 0, s[0:1]
	s_nop 0
	v_exp_f32_e32 v162, v128
	v_mul_f32_e32 v128, 0xbfb8aa3b, v21
	v_exp_f32_e32 v163, v128
	s_nop 0
	v_pk_add_f32 v[162:163], v[162:163], 1.0 op_sel_hi:[1,0]
	s_nop 0
	s_nop 0
	v_rcp_f32_e32 v128, v163
	s_nop 0
	s_nop 0
	v_rcp_f32_e32 v153, v162
	s_nop 0
	v_mul_f32_e32 v162, 0xbfb8aa3b, v22
	v_mul_f32_e32 v163, 0xbfb8aa3b, v23
	v_exp_f32_e32 v162, v162
	v_exp_f32_e32 v163, v163
	s_nop 0
	v_pk_add_f32 v[162:163], v[162:163], 1.0 op_sel_hi:[1,0]
	s_nop 0
	s_nop 0
	v_rcp_f32_e32 v163, v163
	s_nop 0
	s_nop 0
	v_rcp_f32_e32 v164, v162
	s_nop 0
	v_cvt_pk_bf16_f32 v162, v153, v128
	v_mul_f32_e32 v128, 0xbfb8aa3b, v16
	v_cvt_pk_bf16_f32 v163, v164, v163
	v_exp_f32_e32 v164, v128
	v_mul_f32_e32 v128, 0xbfb8aa3b, v17
	v_exp_f32_e32 v165, v128
	v_lshl_add_u64 v[166:167], v[160:161], 0, v[154:155]
	v_lshl_add_u64 v[160:161], v[160:161], 0, v[156:157]
	v_pk_add_f32 v[164:165], v[164:165], 1.0 op_sel_hi:[1,0]
	s_nop 0
	s_nop 0
	v_rcp_f32_e32 v128, v165
	s_nop 0
	s_nop 0
	v_rcp_f32_e32 v153, v164
	s_nop 0
	v_mul_f32_e32 v164, 0xbfb8aa3b, v18
	v_mul_f32_e32 v165, 0xbfb8aa3b, v19
	v_exp_f32_e32 v164, v164
	v_exp_f32_e32 v165, v165
	s_nop 0
	v_pk_add_f32 v[164:165], v[164:165], 1.0 op_sel_hi:[1,0]
	s_nop 0
	s_nop 0
	v_rcp_f32_e32 v165, v165
	s_nop 0
	s_nop 0
	v_rcp_f32_e32 v168, v164
	s_nop 0
	v_cvt_pk_bf16_f32 v164, v153, v128
	v_cvt_pk_bf16_f32 v165, v168, v165
	v_mul_f32_e32 v128, 0xbfb8aa3b, v84
	global_store_dwordx4 v[166:167], v[162:165], off
	s_nop 1
	v_exp_f32_e32 v162, v128
	v_mul_f32_e32 v128, 0xbfb8aa3b, v85
	v_exp_f32_e32 v163, v128
	s_nop 0
	v_pk_add_f32 v[162:163], v[162:163], 1.0 op_sel_hi:[1,0]
	s_nop 0
	s_nop 0
	v_rcp_f32_e32 v128, v163
	s_nop 0
	s_nop 0
	v_rcp_f32_e32 v153, v162
	s_nop 0
	v_mul_f32_e32 v162, 0xbfb8aa3b, v86
	v_mul_f32_e32 v163, 0xbfb8aa3b, v87
	v_exp_f32_e32 v162, v162
	v_exp_f32_e32 v163, v163
	s_nop 0
	v_pk_add_f32 v[162:163], v[162:163], 1.0 op_sel_hi:[1,0]
	s_nop 0
	s_nop 0
	v_rcp_f32_e32 v163, v163
	s_nop 0
	s_nop 0
	v_rcp_f32_e32 v164, v162
	s_nop 0
	v_cvt_pk_bf16_f32 v162, v153, v128
	v_mul_f32_e32 v128, 0xbfb8aa3b, v80
	v_cvt_pk_bf16_f32 v163, v164, v163
	v_exp_f32_e32 v164, v128
	v_mul_f32_e32 v128, 0xbfb8aa3b, v81
	v_exp_f32_e32 v165, v128
	s_nop 0
	v_pk_add_f32 v[164:165], v[164:165], 1.0 op_sel_hi:[1,0]
	s_nop 0
	s_nop 0
	v_rcp_f32_e32 v128, v165
	s_nop 0
	s_nop 0
	v_rcp_f32_e32 v153, v164
	s_nop 0
	v_mul_f32_e32 v164, 0xbfb8aa3b, v82
	v_mul_f32_e32 v165, 0xbfb8aa3b, v83
	v_exp_f32_e32 v164, v164
	v_exp_f32_e32 v165, v165
	s_nop 0
	v_pk_add_f32 v[164:165], v[164:165], 1.0 op_sel_hi:[1,0]
	s_nop 0
	s_nop 0
	v_rcp_f32_e32 v165, v165
	s_nop 0
	s_mov_b64 s[0:1], 0x140000
	v_rcp_f32_e32 v166, v164
	s_nop 0
	v_cvt_pk_bf16_f32 v164, v153, v128
	v_cvt_pk_bf16_f32 v165, v166, v165
	v_mul_f32_e32 v128, 0xbfb8aa3b, v12
	global_store_dwordx4 v[160:161], v[162:165], off
	v_lshl_add_u64 v[160:161], v[158:159], 0, s[0:1]
	s_nop 0
	v_exp_f32_e32 v162, v128
	v_mul_f32_e32 v128, 0xbfb8aa3b, v13
	v_exp_f32_e32 v163, v128
	s_nop 0
	v_pk_add_f32 v[162:163], v[162:163], 1.0 op_sel_hi:[1,0]
	s_nop 0
	s_nop 0
	v_rcp_f32_e32 v128, v163
	s_nop 0
	s_nop 0
	v_rcp_f32_e32 v153, v162
	s_nop 0
	v_mul_f32_e32 v162, 0xbfb8aa3b, v14
	v_mul_f32_e32 v163, 0xbfb8aa3b, v15
	v_exp_f32_e32 v162, v162
	v_exp_f32_e32 v163, v163
	s_nop 0
	v_pk_add_f32 v[162:163], v[162:163], 1.0 op_sel_hi:[1,0]
	s_nop 0
	s_nop 0
	v_rcp_f32_e32 v163, v163
	s_nop 0
	s_nop 0
	v_rcp_f32_e32 v164, v162
	s_nop 0
	v_cvt_pk_bf16_f32 v162, v153, v128
	v_mul_f32_e32 v128, 0xbfb8aa3b, v8
	v_cvt_pk_bf16_f32 v163, v164, v163
	v_exp_f32_e32 v164, v128
	v_mul_f32_e32 v128, 0xbfb8aa3b, v9
	v_exp_f32_e32 v165, v128
	v_lshl_add_u64 v[166:167], v[160:161], 0, v[154:155]
	v_lshl_add_u64 v[160:161], v[160:161], 0, v[156:157]
	v_pk_add_f32 v[164:165], v[164:165], 1.0 op_sel_hi:[1,0]
	s_nop 0
	s_nop 0
	v_rcp_f32_e32 v128, v165
	s_nop 0
	s_nop 0
	v_rcp_f32_e32 v153, v164
	s_nop 0
	v_mul_f32_e32 v164, 0xbfb8aa3b, v10
	v_mul_f32_e32 v165, 0xbfb8aa3b, v11
	v_exp_f32_e32 v164, v164
	v_exp_f32_e32 v165, v165
	s_nop 0
	v_pk_add_f32 v[164:165], v[164:165], 1.0 op_sel_hi:[1,0]
	s_nop 0
	s_nop 0
	v_rcp_f32_e32 v165, v165
	s_nop 0
	s_nop 0
	v_rcp_f32_e32 v168, v164
	s_nop 0
	v_cvt_pk_bf16_f32 v164, v153, v128
	v_cvt_pk_bf16_f32 v165, v168, v165
	v_mul_f32_e32 v128, 0xbfb8aa3b, v76
	global_store_dwordx4 v[166:167], v[162:165], off
	s_nop 1
	v_exp_f32_e32 v162, v128
	v_mul_f32_e32 v128, 0xbfb8aa3b, v77
	v_exp_f32_e32 v163, v128
	s_nop 0
	v_pk_add_f32 v[162:163], v[162:163], 1.0 op_sel_hi:[1,0]
	s_nop 0
	s_nop 0
	v_rcp_f32_e32 v128, v163
	s_nop 0
	s_nop 0
	v_rcp_f32_e32 v153, v162
	s_nop 0
	v_mul_f32_e32 v162, 0xbfb8aa3b, v78
	v_mul_f32_e32 v163, 0xbfb8aa3b, v79
	v_exp_f32_e32 v162, v162
	v_exp_f32_e32 v163, v163
	s_nop 0
	v_pk_add_f32 v[162:163], v[162:163], 1.0 op_sel_hi:[1,0]
	s_nop 0
	s_nop 0
	v_rcp_f32_e32 v163, v163
	s_nop 0
	s_nop 0
	v_rcp_f32_e32 v164, v162
	s_nop 0
	v_cvt_pk_bf16_f32 v162, v153, v128
	v_mul_f32_e32 v128, 0xbfb8aa3b, v72
	v_cvt_pk_bf16_f32 v163, v164, v163
	v_exp_f32_e32 v164, v128
	v_mul_f32_e32 v128, 0xbfb8aa3b, v73
	v_exp_f32_e32 v165, v128
	s_nop 0
	v_pk_add_f32 v[164:165], v[164:165], 1.0 op_sel_hi:[1,0]
	s_nop 0
	s_nop 0
	v_rcp_f32_e32 v128, v165
	s_nop 0
	s_nop 0
	v_rcp_f32_e32 v153, v164
	s_nop 0
	v_mul_f32_e32 v164, 0xbfb8aa3b, v74
	v_mul_f32_e32 v165, 0xbfb8aa3b, v75
	v_exp_f32_e32 v164, v164
	v_exp_f32_e32 v165, v165
	s_nop 0
	v_pk_add_f32 v[164:165], v[164:165], 1.0 op_sel_hi:[1,0]
	s_nop 0
	s_nop 0
	v_rcp_f32_e32 v165, v165
	s_nop 0
	s_mov_b64 s[0:1], 0x160000
	v_lshl_add_u64 v[158:159], v[158:159], 0, s[0:1]
	v_lshl_add_u64 v[154:155], v[158:159], 0, v[154:155]
	v_rcp_f32_e32 v166, v164
	s_nop 0
	v_cvt_pk_bf16_f32 v164, v153, v128
	v_cvt_pk_bf16_f32 v165, v166, v165
	v_mul_f32_e32 v128, 0xbfb8aa3b, v4
	global_store_dwordx4 v[160:161], v[162:165], off
	v_exp_f32_e32 v160, v128
	v_mul_f32_e32 v128, 0xbfb8aa3b, v5
	v_exp_f32_e32 v161, v128
	v_lshl_add_u64 v[158:159], v[158:159], 0, v[156:157]
	v_pk_add_f32 v[160:161], v[160:161], 1.0 op_sel_hi:[1,0]
	s_nop 0
	s_nop 0
	v_rcp_f32_e32 v128, v161
	s_nop 0
	s_nop 0
	v_rcp_f32_e32 v153, v160
	s_nop 0
	v_mul_f32_e32 v160, 0xbfb8aa3b, v6
	v_mul_f32_e32 v161, 0xbfb8aa3b, v7
	v_exp_f32_e32 v160, v160
	v_exp_f32_e32 v161, v161
	s_nop 0
	v_pk_add_f32 v[160:161], v[160:161], 1.0 op_sel_hi:[1,0]
	s_nop 0
	s_nop 0
	v_rcp_f32_e32 v161, v161
	s_nop 0
	s_nop 0
	v_rcp_f32_e32 v162, v160
	s_nop 0
	v_cvt_pk_bf16_f32 v160, v153, v128
	v_mul_f32_e32 v128, 0xbfb8aa3b, v0
	v_cvt_pk_bf16_f32 v161, v162, v161
	v_exp_f32_e32 v162, v128
	v_mul_f32_e32 v128, 0xbfb8aa3b, v1
	v_exp_f32_e32 v163, v128
	s_nop 0
	v_pk_add_f32 v[162:163], v[162:163], 1.0 op_sel_hi:[1,0]
	s_nop 0
	s_nop 0
	v_rcp_f32_e32 v128, v163
	s_nop 0
	s_nop 0
	v_rcp_f32_e32 v153, v162
	s_nop 0
	v_mul_f32_e32 v162, 0xbfb8aa3b, v2
	v_mul_f32_e32 v163, 0xbfb8aa3b, v3
	v_exp_f32_e32 v162, v162
	v_exp_f32_e32 v163, v163
	s_nop 0
	v_pk_add_f32 v[162:163], v[162:163], 1.0 op_sel_hi:[1,0]
	s_nop 0
	s_nop 0
	v_rcp_f32_e32 v163, v163
	s_nop 0
	s_nop 0
	v_rcp_f32_e32 v164, v162
	s_nop 0
	v_cvt_pk_bf16_f32 v162, v153, v128
	v_cvt_pk_bf16_f32 v163, v164, v163
	v_mul_f32_e32 v128, 0xbfb8aa3b, v68
	global_store_dwordx4 v[154:155], v[160:163], off
	v_exp_f32_e32 v154, v128
	v_mul_f32_e32 v128, 0xbfb8aa3b, v69
	v_exp_f32_e32 v155, v128
	s_nop 0
	v_pk_add_f32 v[154:155], v[154:155], 1.0 op_sel_hi:[1,0]
	s_nop 0
	s_nop 0
	v_rcp_f32_e32 v128, v155
	s_nop 0
	s_nop 0
	v_rcp_f32_e32 v153, v154
	s_nop 0
	v_mul_f32_e32 v154, 0xbfb8aa3b, v70
	v_mul_f32_e32 v155, 0xbfb8aa3b, v71
	v_exp_f32_e32 v154, v154
	v_exp_f32_e32 v155, v155
	s_nop 0
	v_pk_add_f32 v[154:155], v[154:155], 1.0 op_sel_hi:[1,0]
	s_nop 0
	s_nop 0
	v_rcp_f32_e32 v155, v155
	s_nop 0
	s_nop 0
	v_rcp_f32_e32 v160, v154
	s_nop 0
	v_cvt_pk_bf16_f32 v154, v153, v128
	v_mul_f32_e32 v128, 0xbfb8aa3b, v64
	v_exp_f32_e32 v156, v128
	v_mul_f32_e32 v128, 0xbfb8aa3b, v65
	v_exp_f32_e32 v157, v128
	v_cvt_pk_bf16_f32 v155, v160, v155
	v_pk_add_f32 v[156:157], v[156:157], 1.0 op_sel_hi:[1,0]
	s_nop 0
	s_nop 0
	v_rcp_f32_e32 v128, v157
	s_nop 0
	s_nop 0
	v_rcp_f32_e32 v153, v156
	s_nop 0
	v_mul_f32_e32 v156, 0xbfb8aa3b, v66
	v_mul_f32_e32 v157, 0xbfb8aa3b, v67
	v_exp_f32_e32 v156, v156
	v_exp_f32_e32 v157, v157
	s_nop 0
	v_pk_add_f32 v[156:157], v[156:157], 1.0 op_sel_hi:[1,0]
	s_nop 0
	s_nop 0
	v_rcp_f32_e32 v157, v157
	s_nop 0
	s_mov_b64 s[0:1], 0
	v_rcp_f32_e32 v160, v156
	s_nop 0
	v_cvt_pk_bf16_f32 v156, v153, v128
	v_cvt_pk_bf16_f32 v157, v160, v157
	global_store_dwordx4 v[158:159], v[154:157], off

.LBB0_773:
	s_or_b64 exec, exec, s[40:41]
	v_readlane_b32 s40, v254, 46
	v_mov_b32_e32 v4, s14
	v_readlane_b32 s41, v254, 47
	s_waitcnt vmcnt(0)
	v_mul_f32_e32 v2, 0xbfb8aa3b, v2
	v_exp_f32_e32 v2, v2
	v_readlane_b32 s42, v254, 48
	v_readlane_b32 s43, v254, 49
	v_readlane_b32 s44, v254, 50
	global_load_dword v4, v4, s[40:41]
	v_add_f32_e32 v2, 1.0, v2
	v_readlane_b32 s45, v254, 51
	v_readlane_b32 s46, v254, 52
	v_readlane_b32 s47, v254, 53
	v_readlane_b32 s48, v254, 54
	v_readlane_b32 s49, v254, 55
	v_readlane_b32 s50, v254, 56
	v_readlane_b32 s51, v254, 57
	v_readlane_b32 s52, v254, 58
	v_readlane_b32 s53, v254, 59
	v_readlane_b32 s54, v254, 60
	v_readlane_b32 s55, v254, 61
	s_waitcnt vmcnt(0)
	v_mul_f32_e32 v4, 0x3fb8aa3b, v4
	v_exp_f32_e32 v4, v4
	s_nop 0
	v_mul_f32_e64 v3, v3, -v4
	s_nop 0
	v_rcp_f32_e32 v2, v2
	s_nop 0

.LBB0_776:
	s_or_b64 exec, exec, s[36:37]
	s_waitcnt vmcnt(0)
	v_lshlrev_b32_e32 v2, 4, v0
	v_ashrrev_i32_e32 v82, 3, v0
	v_and_b32_e32 v107, 0x70, v2
	v_cmp_lt_i32_e64 s[36:37], 15, v82
	v_cmp_gt_i32_e32 vcc, 16, v82
	v_mov_b32_e32 v122, 0
	v_lshlrev_b32_e32 v104, 1, v107
	v_mov_b32_e32 v123, 0
	v_mov_b32_e32 v118, 0
	v_mov_b32_e32 v119, 0
	v_mov_b32_e32 v120, 0
	v_mov_b32_e32 v121, 0
	v_mov_b32_e32 v116, 0
	v_mov_b32_e32 v117, 0
	v_mov_b32_e32 v114, 0
	v_mov_b32_e32 v115, 0
	v_mov_b32_e32 v102, 0
	v_mov_b32_e32 v103, 0
	v_mov_b32_e32 v112, 0
	v_mov_b32_e32 v113, 0
	v_mov_b32_e32 v100, 0
	v_mov_b32_e32 v101, 0
	v_mov_b32_e32 v88, 0
	v_mov_b32_e32 v89, 0
	v_mov_b32_e32 v84, 0
	v_mov_b32_e32 v85, 0
	v_mov_b32_e32 v92, 0
	v_mov_b32_e32 v93, 0
	v_mov_b32_e32 v86, 0
	v_mov_b32_e32 v87, 0
	v_mov_b32_e32 v96, 0
	v_mov_b32_e32 v97, 0
	v_mov_b32_e32 v90, 0
	v_mov_b32_e32 v91, 0
	v_mov_b32_e32 v98, 0
	v_mov_b32_e32 v99, 0
	v_mov_b32_e32 v94, 0
	v_mov_b32_e32 v95, 0
	s_waitcnt lgkmcnt(0)
	s_barrier
	s_and_saveexec_b64 s[0:1], vcc
	s_cbranch_execz .LBB0_778
	v_mul_lo_u32 v2, v82, s23
	v_lshl_add_u32 v54, v107, 2, 0
	v_add3_u32 v74, 0, v104, v2
	v_add_u32_e32 v47, 0x1ca00, v54
	ds_read_b128 v[26:29], v74 offset:35328
	ds_read_b128 v[2:5], v74 offset:35344
	ds_read_b128 v[56:59], v47
	ds_read_b128 v[30:33], v47 offset:16
	ds_read_b128 v[14:17], v47 offset:32
	ds_read_b128 v[6:9], v47 offset:48
	s_waitcnt lgkmcnt(4)
	v_lshlrev_b32_e32 v10, 16, v5
	s_waitcnt lgkmcnt(0)
	v_mul_f32_e32 v46, v8, v10
	ds_read_b128 v[38:41], v74 offset:36112
	ds_read_b128 v[10:13], v74 offset:36128
	ds_read_b128 v[60:63], v47 offset:512
	ds_read_b128 v[42:45], v47 offset:528
	ds_read_b128 v[22:25], v47 offset:544
	ds_read_b128 v[18:21], v47 offset:560
	v_and_b32_e32 v34, 0xffff0000, v5
	s_waitcnt lgkmcnt(4)
	v_lshlrev_b32_e32 v8, 16, v13
	s_waitcnt lgkmcnt(0)
	v_mul_f32_e32 v48, v20, v8
	v_and_b32_e32 v35, 0xffff0000, v13
	v_mov_b32_e32 v20, v9
	v_pk_mul_f32 v[50:51], v[20:21], v[34:35]
	ds_read_b128 v[64:67], v74 offset:36896
	ds_read_b128 v[34:37], v74 offset:36912
	ds_read_b128 v[68:71], v47 offset:1024
	ds_read_b128 v[76:79], v47 offset:1040
	ds_read_b128 v[84:87], v47 offset:1056
	ds_read_b128 v[88:91], v47 offset:1072
	ds_read_b128 v[92:95], v74 offset:37680
	ds_read_b128 v[96:99], v74 offset:37696
	ds_read_b128 v[100:103], v47 offset:1536
	ds_read_b128 v[112:115], v47 offset:1552
	ds_read_b128 v[116:119], v47 offset:1568
	ds_read_b128 v[120:123], v47 offset:1584
	v_lshlrev_b32_e32 v20, 16, v38
	s_waitcnt lgkmcnt(10)
	v_lshlrev_b32_e32 v5, 16, v37
	s_waitcnt lgkmcnt(6)
	v_mul_f32_e32 v52, v90, v5
	s_waitcnt lgkmcnt(4)
	v_lshlrev_b32_e32 v5, 16, v99
	s_waitcnt lgkmcnt(0)
	v_mul_f32_e32 v72, v122, v5
	v_and_b32_e32 v9, 0xffff0000, v99
	v_and_b32_e32 v8, 0xffff0000, v37
	v_mov_b32_e32 v122, v91
	v_pk_mul_f32 v[80:81], v[122:123], v[8:9]
	v_lshlrev_b32_e32 v8, 16, v26
	v_and_b32_e32 v9, 0xffff0000, v26
	v_pk_fma_f32 v[8:9], v[56:57], v[8:9], 0 op_sel_hi:[1,1,0]
	v_and_b32_e32 v21, 0xffff0000, v38
	v_pk_fma_f32 v[8:9], v[60:61], v[20:21], v[8:9]
	v_lshlrev_b32_e32 v20, 16, v64
	v_and_b32_e32 v21, 0xffff0000, v64
	v_pk_fma_f32 v[8:9], v[68:69], v[20:21], v[8:9]
	v_lshlrev_b32_e32 v20, 16, v92
	v_and_b32_e32 v21, 0xffff0000, v92
	v_pk_fma_f32 v[8:9], v[100:101], v[20:21], v[8:9]
	v_lshlrev_b32_e32 v20, 16, v27
	v_and_b32_e32 v21, 0xffff0000, v27
	v_pk_fma_f32 v[20:21], v[58:59], v[20:21], 0 op_sel_hi:[1,1,0]
	v_lshlrev_b32_e32 v26, 16, v39
	v_and_b32_e32 v27, 0xffff0000, v39
	v_pk_fma_f32 v[20:21], v[62:63], v[26:27], v[20:21]
	v_lshlrev_b32_e32 v26, 16, v65
	v_and_b32_e32 v27, 0xffff0000, v65
	v_pk_fma_f32 v[20:21], v[70:71], v[26:27], v[20:21]
	v_lshlrev_b32_e32 v26, 16, v93
	v_and_b32_e32 v27, 0xffff0000, v93
	v_pk_fma_f32 v[20:21], v[102:103], v[26:27], v[20:21]
	v_lshlrev_b32_e32 v26, 16, v28
	v_and_b32_e32 v27, 0xffff0000, v28
	v_lshlrev_b32_e32 v28, 16, v29
	v_and_b32_e32 v29, 0xffff0000, v29
	v_pk_fma_f32 v[28:29], v[32:33], v[28:29], 0 op_sel_hi:[1,1,0]
	v_lshlrev_b32_e32 v32, 16, v41
	v_and_b32_e32 v33, 0xffff0000, v41
	v_pk_fma_f32 v[28:29], v[44:45], v[32:33], v[28:29]
	v_lshlrev_b32_e32 v32, 16, v67
	v_and_b32_e32 v33, 0xffff0000, v67
	v_pk_fma_f32 v[28:29], v[78:79], v[32:33], v[28:29]
	v_lshlrev_b32_e32 v32, 16, v95
	v_and_b32_e32 v33, 0xffff0000, v95
	v_pk_fma_f32 v[28:29], v[114:115], v[32:33], v[28:29]
	v_lshlrev_b32_e32 v32, 16, v2
	v_and_b32_e32 v33, 0xffff0000, v2
	v_pk_fma_f32 v[14:15], v[14:15], v[32:33], 0 op_sel_hi:[1,1,0]
	v_lshlrev_b32_e32 v32, 16, v10
	v_and_b32_e32 v33, 0xffff0000, v10
	v_pk_fma_f32 v[14:15], v[22:23], v[32:33], v[14:15]
	v_lshlrev_b32_e32 v22, 16, v34
	v_and_b32_e32 v23, 0xffff0000, v34
	v_pk_fma_f32 v[14:15], v[84:85], v[22:23], v[14:15]
	v_lshlrev_b32_e32 v22, 16, v96
	v_and_b32_e32 v23, 0xffff0000, v96
	v_mul_f32_e32 v5, 0xbfb8aa3b, v8
	v_pk_fma_f32 v[26:27], v[30:31], v[26:27], 0 op_sel_hi:[1,1,0]
	v_lshlrev_b32_e32 v30, 16, v40
	v_and_b32_e32 v31, 0xffff0000, v40
	v_pk_fma_f32 v[14:15], v[116:117], v[22:23], v[14:15]
	v_exp_f32_e32 v56, v5
	v_mul_f32_e32 v5, 0xbfb8aa3b, v9
	v_pk_fma_f32 v[26:27], v[42:43], v[30:31], v[26:27]
	v_lshlrev_b32_e32 v30, 16, v66
	v_and_b32_e32 v31, 0xffff0000, v66
	v_mul_f32_e32 v2, 0xbfb8aa3b, v14
	v_exp_f32_e32 v57, v5
	v_mul_f32_e32 v5, 0xbfb8aa3b, v20
	v_pk_fma_f32 v[26:27], v[76:77], v[30:31], v[26:27]
	v_lshlrev_b32_e32 v30, 16, v94
	v_and_b32_e32 v31, 0xffff0000, v94
	v_exp_f32_e32 v22, v2
	v_mul_f32_e32 v2, 0xbfb8aa3b, v15
	v_exp_f32_e32 v38, v5
	v_mul_f32_e32 v5, 0xbfb8aa3b, v21
	v_pk_fma_f32 v[26:27], v[112:113], v[30:31], v[26:27]
	v_exp_f32_e32 v23, v2
	v_lshlrev_b32_e32 v2, 16, v3
	v_and_b32_e32 v3, 0xffff0000, v3
	v_exp_f32_e32 v39, v5
	v_mul_f32_e32 v5, 0xbfb8aa3b, v26
	v_pk_fma_f32 v[2:3], v[16:17], v[2:3], 0 op_sel_hi:[1,1,0]
	v_lshlrev_b32_e32 v10, 16, v11
	v_and_b32_e32 v11, 0xffff0000, v11
	v_exp_f32_e32 v30, v5
	v_mul_f32_e32 v5, 0xbfb8aa3b, v27
	v_pk_fma_f32 v[2:3], v[24:25], v[10:11], v[2:3]
	v_lshlrev_b32_e32 v10, 16, v35
	v_and_b32_e32 v11, 0xffff0000, v35
	v_exp_f32_e32 v31, v5
	v_mul_f32_e32 v5, 0xbfb8aa3b, v28
	v_pk_fma_f32 v[2:3], v[86:87], v[10:11], v[2:3]
	v_lshlrev_b32_e32 v10, 16, v97
	v_and_b32_e32 v11, 0xffff0000, v97
	v_exp_f32_e32 v40, v5
	v_mul_f32_e32 v5, 0xbfb8aa3b, v29
	v_pk_fma_f32 v[2:3], v[118:119], v[10:11], v[2:3]
	v_exp_f32_e32 v41, v5
	v_mul_f32_e32 v5, 0xbfb8aa3b, v2
	v_exp_f32_e32 v10, v5
	v_mul_f32_e32 v5, 0xbfb8aa3b, v3
	v_lshlrev_b32_e32 v16, 16, v4
	v_and_b32_e32 v17, 0xffff0000, v4
	v_exp_f32_e32 v11, v5
	v_pk_fma_f32 v[4:5], v[6:7], v[16:17], 0 op_sel_hi:[1,1,0]
	v_lshlrev_b32_e32 v6, 16, v12
	v_and_b32_e32 v7, 0xffff0000, v12
	v_pk_fma_f32 v[4:5], v[18:19], v[6:7], v[4:5]
	v_lshlrev_b32_e32 v6, 16, v36
	v_and_b32_e32 v7, 0xffff0000, v36
	v_pk_fma_f32 v[4:5], v[88:89], v[6:7], v[4:5]
	v_lshlrev_b32_e32 v6, 16, v98
	v_and_b32_e32 v7, 0xffff0000, v98
	v_pk_fma_f32 v[4:5], v[120:121], v[6:7], v[4:5]
	v_mov_b32_e32 v47, v50
	v_mul_f32_e32 v6, 0xbfb8aa3b, v4
	v_exp_f32_e32 v12, v6
	v_mul_f32_e32 v6, 0xbfb8aa3b, v5
	v_exp_f32_e32 v13, v6
	v_pk_add_f32 v[6:7], v[46:47], 0 op_sel_hi:[1,0]
	v_mov_b32_e32 v49, v51
	v_pk_add_f32 v[6:7], v[6:7], v[48:49]
	v_mov_b32_e32 v53, v80
	v_pk_add_f32 v[6:7], v[6:7], v[52:53]
	v_mov_b32_e32 v73, v81
	v_pk_add_f32 v[6:7], v[6:7], v[72:73]
	v_pk_add_f32 v[32:33], v[10:11], 1.0 op_sel_hi:[1,0]
	v_mul_f32_e32 v16, 0xbfb8aa3b, v6
	v_mul_f32_e32 v17, 0xbfb8aa3b, v7
	v_exp_f32_e32 v16, v16
	v_exp_f32_e32 v17, v17
	v_pk_add_f32 v[10:11], v[12:13], 1.0 op_sel_hi:[1,0]
	v_pk_add_f32 v[34:35], v[38:39], 1.0 op_sel_hi:[1,0]
	v_pk_add_f32 v[24:25], v[40:41], 1.0 op_sel_hi:[1,0]
	v_pk_add_f32 v[18:19], v[16:17], 1.0 op_sel_hi:[1,0]
	v_pk_add_f32 v[16:17], v[22:23], 1.0 op_sel_hi:[1,0]
	v_pk_add_f32 v[22:23], v[30:31], 1.0 op_sel_hi:[1,0]
	v_pk_add_f32 v[30:31], v[56:57], 1.0 op_sel_hi:[1,0]
	v_add_u32_e32 v47, 0x1d200, v54
	v_rcp_f32_e32 v13, v19
	s_nop 0
	s_nop 0
	v_rcp_f32_e32 v12, v18
	s_nop 0
	v_pk_mul_f32 v[94:95], v[6:7], v[12:13]
	v_rcp_f32_e32 v19, v35
	s_nop 0
	s_nop 0
	v_rcp_f32_e32 v18, v34
	s_nop 0
	v_pk_mul_f32 v[84:85], v[20:21], v[18:19]
	v_rcp_f32_e32 v25, v25
	s_nop 0
	s_nop 0
	v_rcp_f32_e32 v24, v24
	s_nop 0
	v_pk_mul_f32 v[86:87], v[28:29], v[24:25]
	v_rcp_f32_e32 v33, v33
	s_nop 0
	s_nop 0
	v_rcp_f32_e32 v32, v32
	s_nop 0
	v_pk_mul_f32 v[90:91], v[2:3], v[32:33]
	v_rcp_f32_e32 v31, v31
	s_nop 0
	s_nop 0
	v_rcp_f32_e32 v30, v30
	s_nop 0
	v_pk_mul_f32 v[88:89], v[8:9], v[30:31]
	v_rcp_f32_e32 v23, v23
	s_nop 0
	s_nop 0
	v_rcp_f32_e32 v22, v22
	s_nop 0
	v_pk_mul_f32 v[92:93], v[26:27], v[22:23]
	v_rcp_f32_e32 v17, v17
	s_nop 0
	s_nop 0
	v_rcp_f32_e32 v16, v16
	s_nop 0
	v_pk_mul_f32 v[96:97], v[14:15], v[16:17]
	v_rcp_f32_e32 v11, v11
	s_nop 0
	s_nop 0
	v_rcp_f32_e32 v10, v10
	s_nop 0
	v_pk_mul_f32 v[98:99], v[4:5], v[10:11]
	ds_read_b128 v[22:25], v74 offset:35584
	ds_read_b128 v[2:5], v74 offset:35600
	ds_read_b128 v[56:59], v47
	ds_read_b128 v[34:37], v47 offset:16
	ds_read_b128 v[14:17], v47 offset:32
	ds_read_b128 v[6:9], v47 offset:48
	s_waitcnt lgkmcnt(4)
	v_lshlrev_b32_e32 v10, 16, v5
	s_waitcnt lgkmcnt(0)
	v_mul_f32_e32 v46, v8, v10
	ds_read_b128 v[38:41], v74 offset:36368
	ds_read_b128 v[10:13], v74 offset:36384
	ds_read_b128 v[60:63], v47 offset:512
	ds_read_b128 v[42:45], v47 offset:528
	ds_read_b128 v[26:29], v47 offset:544
	ds_read_b128 v[18:21], v47 offset:560
	v_and_b32_e32 v30, 0xffff0000, v5
	s_waitcnt lgkmcnt(4)
	v_lshlrev_b32_e32 v8, 16, v13
	s_waitcnt lgkmcnt(0)
	v_mul_f32_e32 v48, v20, v8
	v_and_b32_e32 v31, 0xffff0000, v13
	v_mov_b32_e32 v20, v9
	v_pk_mul_f32 v[50:51], v[20:21], v[30:31]
	ds_read_b128 v[64:67], v74 offset:37152
	ds_read_b128 v[30:33], v74 offset:37168
	ds_read_b128 v[68:71], v47 offset:1024
	ds_read_b128 v[76:79], v47 offset:1040
	ds_read_b128 v[100:103], v47 offset:1056
	ds_read_b128 v[112:115], v47 offset:1072
	ds_read_b128 v[116:119], v74 offset:37936
	ds_read_b128 v[120:123], v74 offset:37952
	ds_read_b128 v[134:137], v47 offset:1536
	ds_read_b128 v[138:141], v47 offset:1552
	ds_read_b128 v[142:145], v47 offset:1568
	ds_read_b128 v[146:149], v47 offset:1584
	v_lshlrev_b32_e32 v20, 16, v38
	s_waitcnt lgkmcnt(10)
	v_lshlrev_b32_e32 v5, 16, v33
	s_waitcnt lgkmcnt(6)
	v_mul_f32_e32 v52, v114, v5
	s_waitcnt lgkmcnt(4)
	v_lshlrev_b32_e32 v5, 16, v123
	s_waitcnt lgkmcnt(0)
	v_mul_f32_e32 v72, v148, v5
	v_and_b32_e32 v9, 0xffff0000, v123
	v_and_b32_e32 v8, 0xffff0000, v33
	v_mov_b32_e32 v148, v115
	v_pk_mul_f32 v[80:81], v[148:149], v[8:9]
	v_lshlrev_b32_e32 v8, 16, v22
	v_and_b32_e32 v9, 0xffff0000, v22
	v_pk_fma_f32 v[8:9], v[56:57], v[8:9], 0 op_sel_hi:[1,1,0]
	v_and_b32_e32 v21, 0xffff0000, v38
	v_pk_fma_f32 v[8:9], v[60:61], v[20:21], v[8:9]
	v_lshlrev_b32_e32 v20, 16, v64
	v_and_b32_e32 v21, 0xffff0000, v64
	v_pk_fma_f32 v[8:9], v[68:69], v[20:21], v[8:9]
	v_lshlrev_b32_e32 v20, 16, v116
	v_and_b32_e32 v21, 0xffff0000, v116
	v_pk_fma_f32 v[8:9], v[134:135], v[20:21], v[8:9]
	v_lshlrev_b32_e32 v20, 16, v23
	v_and_b32_e32 v21, 0xffff0000, v23
	v_pk_fma_f32 v[20:21], v[58:59], v[20:21], 0 op_sel_hi:[1,1,0]
	v_lshlrev_b32_e32 v22, 16, v39
	v_and_b32_e32 v23, 0xffff0000, v39
	v_pk_fma_f32 v[20:21], v[62:63], v[22:23], v[20:21]
	v_lshlrev_b32_e32 v22, 16, v65
	v_and_b32_e32 v23, 0xffff0000, v65
	v_pk_fma_f32 v[20:21], v[70:71], v[22:23], v[20:21]
	v_lshlrev_b32_e32 v22, 16, v117
	v_and_b32_e32 v23, 0xffff0000, v117
	v_pk_fma_f32 v[20:21], v[136:137], v[22:23], v[20:21]
	v_lshlrev_b32_e32 v22, 16, v24
	v_and_b32_e32 v23, 0xffff0000, v24
	v_lshlrev_b32_e32 v24, 16, v25
	v_and_b32_e32 v25, 0xffff0000, v25
	v_pk_fma_f32 v[22:23], v[34:35], v[22:23], 0 op_sel_hi:[1,1,0]
	v_lshlrev_b32_e32 v34, 16, v40
	v_and_b32_e32 v35, 0xffff0000, v40
	v_pk_fma_f32 v[24:25], v[36:37], v[24:25], 0 op_sel_hi:[1,1,0]
	v_lshlrev_b32_e32 v36, 16, v41
	v_and_b32_e32 v37, 0xffff0000, v41
	v_lshlrev_b32_e32 v40, 16, v2
	v_and_b32_e32 v41, 0xffff0000, v2
	v_pk_fma_f32 v[14:15], v[14:15], v[40:41], 0 op_sel_hi:[1,1,0]
	v_lshlrev_b32_e32 v40, 16, v10
	v_and_b32_e32 v41, 0xffff0000, v10
	v_pk_fma_f32 v[14:15], v[26:27], v[40:41], v[14:15]
	v_lshlrev_b32_e32 v26, 16, v30
	v_and_b32_e32 v27, 0xffff0000, v30
	v_pk_fma_f32 v[14:15], v[100:101], v[26:27], v[14:15]
	v_lshlrev_b32_e32 v26, 16, v120
	v_and_b32_e32 v27, 0xffff0000, v120
	v_mul_f32_e32 v5, 0xbfb8aa3b, v8
	v_pk_fma_f32 v[14:15], v[142:143], v[26:27], v[14:15]
	v_exp_f32_e32 v56, v5
	v_mul_f32_e32 v5, 0xbfb8aa3b, v9
	v_pk_fma_f32 v[22:23], v[42:43], v[34:35], v[22:23]
	v_lshlrev_b32_e32 v34, 16, v66
	v_and_b32_e32 v35, 0xffff0000, v66
	v_mul_f32_e32 v2, 0xbfb8aa3b, v14
	v_exp_f32_e32 v57, v5
	v_mul_f32_e32 v5, 0xbfb8aa3b, v20
	v_pk_fma_f32 v[22:23], v[76:77], v[34:35], v[22:23]
	v_lshlrev_b32_e32 v34, 16, v118
	v_and_b32_e32 v35, 0xffff0000, v118
	v_exp_f32_e32 v26, v2
	v_mul_f32_e32 v2, 0xbfb8aa3b, v15
	v_exp_f32_e32 v38, v5
	v_mul_f32_e32 v5, 0xbfb8aa3b, v21
	v_pk_fma_f32 v[22:23], v[138:139], v[34:35], v[22:23]
	v_pk_fma_f32 v[24:25], v[44:45], v[36:37], v[24:25]
	v_lshlrev_b32_e32 v36, 16, v67
	v_and_b32_e32 v37, 0xffff0000, v67
	v_exp_f32_e32 v27, v2
	v_lshlrev_b32_e32 v2, 16, v3
	v_and_b32_e32 v3, 0xffff0000, v3
	v_exp_f32_e32 v39, v5
	v_mul_f32_e32 v5, 0xbfb8aa3b, v22
	v_pk_fma_f32 v[24:25], v[78:79], v[36:37], v[24:25]
	v_lshlrev_b32_e32 v36, 16, v119
	v_and_b32_e32 v37, 0xffff0000, v119
	v_pk_fma_f32 v[2:3], v[16:17], v[2:3], 0 op_sel_hi:[1,1,0]
	v_lshlrev_b32_e32 v10, 16, v11
	v_and_b32_e32 v11, 0xffff0000, v11
	v_exp_f32_e32 v34, v5
	v_mul_f32_e32 v5, 0xbfb8aa3b, v23
	v_pk_fma_f32 v[24:25], v[140:141], v[36:37], v[24:25]
	v_pk_fma_f32 v[2:3], v[28:29], v[10:11], v[2:3]
	v_lshlrev_b32_e32 v10, 16, v31
	v_and_b32_e32 v11, 0xffff0000, v31
	v_exp_f32_e32 v35, v5
	v_mul_f32_e32 v5, 0xbfb8aa3b, v24
	v_pk_fma_f32 v[2:3], v[102:103], v[10:11], v[2:3]
	v_lshlrev_b32_e32 v10, 16, v121
	v_and_b32_e32 v11, 0xffff0000, v121
	v_exp_f32_e32 v36, v5
	v_mul_f32_e32 v5, 0xbfb8aa3b, v25
	v_pk_fma_f32 v[2:3], v[144:145], v[10:11], v[2:3]
	v_exp_f32_e32 v37, v5
	v_mul_f32_e32 v5, 0xbfb8aa3b, v2
	v_exp_f32_e32 v10, v5
	v_mul_f32_e32 v5, 0xbfb8aa3b, v3
	v_lshlrev_b32_e32 v16, 16, v4
	v_and_b32_e32 v17, 0xffff0000, v4
	v_exp_f32_e32 v11, v5
	v_pk_fma_f32 v[4:5], v[6:7], v[16:17], 0 op_sel_hi:[1,1,0]
	v_lshlrev_b32_e32 v6, 16, v12
	v_and_b32_e32 v7, 0xffff0000, v12
	v_pk_fma_f32 v[4:5], v[18:19], v[6:7], v[4:5]
	v_lshlrev_b32_e32 v6, 16, v32
	v_and_b32_e32 v7, 0xffff0000, v32
	v_pk_fma_f32 v[4:5], v[112:113], v[6:7], v[4:5]
	v_lshlrev_b32_e32 v6, 16, v122
	v_and_b32_e32 v7, 0xffff0000, v122
	v_pk_fma_f32 v[4:5], v[146:147], v[6:7], v[4:5]
	v_mov_b32_e32 v47, v50
	v_mul_f32_e32 v6, 0xbfb8aa3b, v4
	v_exp_f32_e32 v12, v6
	v_mul_f32_e32 v6, 0xbfb8aa3b, v5
	v_exp_f32_e32 v13, v6
	v_pk_add_f32 v[6:7], v[46:47], 0 op_sel_hi:[1,0]
	v_mov_b32_e32 v49, v51
	v_pk_add_f32 v[6:7], v[6:7], v[48:49]
	v_mov_b32_e32 v53, v80
	v_pk_add_f32 v[6:7], v[6:7], v[52:53]
	v_mov_b32_e32 v73, v81
	v_pk_add_f32 v[6:7], v[6:7], v[72:73]
	v_pk_add_f32 v[32:33], v[10:11], 1.0 op_sel_hi:[1,0]
	v_mul_f32_e32 v16, 0xbfb8aa3b, v6
	v_mul_f32_e32 v17, 0xbfb8aa3b, v7
	v_exp_f32_e32 v16, v16
	v_exp_f32_e32 v17, v17
	v_pk_add_f32 v[10:11], v[12:13], 1.0 op_sel_hi:[1,0]
	v_pk_add_f32 v[28:29], v[36:37], 1.0 op_sel_hi:[1,0]
	v_pk_add_f32 v[36:37], v[38:39], 1.0 op_sel_hi:[1,0]
	v_pk_add_f32 v[18:19], v[16:17], 1.0 op_sel_hi:[1,0]
	v_pk_add_f32 v[16:17], v[26:27], 1.0 op_sel_hi:[1,0]
	v_pk_add_f32 v[26:27], v[34:35], 1.0 op_sel_hi:[1,0]
	v_pk_add_f32 v[30:31], v[56:57], 1.0 op_sel_hi:[1,0]
	v_rcp_f32_e32 v13, v19
	s_nop 0
	s_nop 0
	v_rcp_f32_e32 v12, v18
	s_nop 0
	v_pk_mul_f32 v[100:101], v[6:7], v[12:13]
	v_rcp_f32_e32 v19, v37
	s_nop 0
	s_nop 0
	v_rcp_f32_e32 v18, v36
	s_nop 0
	v_pk_mul_f32 v[118:119], v[20:21], v[18:19]
	v_rcp_f32_e32 v29, v29
	s_nop 0
	s_nop 0
	v_rcp_f32_e32 v28, v28
	s_nop 0
	v_pk_mul_f32 v[116:117], v[24:25], v[28:29]
	v_rcp_f32_e32 v33, v33
	s_nop 0
	s_nop 0
	v_rcp_f32_e32 v32, v32
	s_nop 0
	v_pk_mul_f32 v[102:103], v[2:3], v[32:33]
	v_rcp_f32_e32 v31, v31
	s_nop 0
	s_nop 0
	v_rcp_f32_e32 v30, v30
	s_nop 0
	v_pk_mul_f32 v[122:123], v[8:9], v[30:31]
	v_add_u32_e32 v30, 0x1da00, v54
	v_rcp_f32_e32 v27, v27
	s_nop 0
	s_nop 0
	v_rcp_f32_e32 v26, v26
	s_nop 0
	v_pk_mul_f32 v[120:121], v[22:23], v[26:27]
	v_rcp_f32_e32 v17, v17
	s_nop 0
	s_nop 0
	v_rcp_f32_e32 v16, v16
	s_nop 0
	v_pk_mul_f32 v[114:115], v[14:15], v[16:17]
	v_rcp_f32_e32 v11, v11
	s_nop 0
	s_nop 0
	v_rcp_f32_e32 v10, v10
	s_nop 0
	v_pk_mul_f32 v[112:113], v[4:5], v[10:11]
	ds_read_b128 v[54:57], v74 offset:35840
	ds_read_b128 v[6:9], v74 offset:35856
	ds_read_b128 v[134:137], v30
	ds_read_b128 v[50:53], v30 offset:16
	ds_read_b128 v[34:37], v30 offset:32
	ds_read_b128 v[2:5], v30 offset:48
	ds_read_b128 v[62:65], v74 offset:36624
	ds_read_b128 v[14:17], v74 offset:36640
	ds_read_b128 v[138:141], v30 offset:512
	ds_read_b128 v[58:61], v30 offset:528
	ds_read_b128 v[38:41], v30 offset:544
	ds_read_b128 v[10:13], v30 offset:560
	ds_read_b128 v[70:73], v74 offset:37408
	ds_read_b128 v[22:25], v74 offset:37424
	ds_read_b128 v[142:145], v30 offset:1024
	ds_read_b128 v[66:69], v30 offset:1040
	ds_read_b128 v[42:45], v30 offset:1056
	ds_read_b128 v[18:21], v30 offset:1072
	ds_read_b128 v[78:81], v74 offset:38192
	ds_read_b128 v[26:29], v74 offset:38208
	ds_read_b128 v[146:149], v30 offset:1536
	ds_read_b128 v[74:77], v30 offset:1552
	ds_read_b128 v[46:49], v30 offset:1568
	ds_read_b128 v[30:33], v30 offset:1584
	s_waitcnt lgkmcnt(14)
	v_lshlrev_b32_e32 v124, 16, v54
	v_and_b32_e32 v125, 0xffff0000, v54
	v_pk_fma_f32 v[124:125], v[134:135], v[124:125], 0 op_sel_hi:[1,1,0]
	v_lshlrev_b32_e32 v134, 16, v62
	v_and_b32_e32 v135, 0xffff0000, v62
	v_pk_fma_f32 v[124:125], v[138:139], v[134:135], v[124:125]
	s_waitcnt lgkmcnt(11)
	v_lshlrev_b32_e32 v134, 16, v70
	v_and_b32_e32 v135, 0xffff0000, v70
	s_waitcnt lgkmcnt(9)
	v_pk_fma_f32 v[124:125], v[142:143], v[134:135], v[124:125]
	s_waitcnt lgkmcnt(5)
	v_lshlrev_b32_e32 v134, 16, v78
	v_and_b32_e32 v135, 0xffff0000, v78
	s_waitcnt lgkmcnt(3)
	v_pk_fma_f32 v[124:125], v[146:147], v[134:135], v[124:125]
	s_nop 0
	v_mul_f32_e32 v54, 0xbfb8aa3b, v124
	v_exp_f32_e32 v134, v54
	v_mul_f32_e32 v54, 0xbfb8aa3b, v125
	v_exp_f32_e32 v135, v54
	s_nop 0
	v_pk_add_f32 v[134:135], v[134:135], 1.0 op_sel_hi:[1,0]
	s_nop 0
	s_nop 0
	v_rcp_f32_e32 v135, v135
	s_nop 0
	s_nop 0
	v_rcp_f32_e32 v134, v134
	s_nop 0
	v_lshlrev_b32_e32 v54, 16, v55
	v_and_b32_e32 v55, 0xffff0000, v55
	v_pk_fma_f32 v[54:55], v[136:137], v[54:55], 0 op_sel_hi:[1,1,0]
	v_lshlrev_b32_e32 v62, 16, v63
	v_and_b32_e32 v63, 0xffff0000, v63
	v_pk_fma_f32 v[54:55], v[140:141], v[62:63], v[54:55]
	v_lshlrev_b32_e32 v62, 16, v71
	v_and_b32_e32 v63, 0xffff0000, v71
	v_pk_fma_f32 v[54:55], v[144:145], v[62:63], v[54:55]
	v_lshlrev_b32_e32 v62, 16, v79
	v_and_b32_e32 v63, 0xffff0000, v79
	v_pk_fma_f32 v[54:55], v[148:149], v[62:63], v[54:55]
	v_pk_mul_f32 v[124:125], v[124:125], v[134:135]
	v_mul_f32_e32 v62, 0xbfb8aa3b, v54
	v_mul_f32_e32 v63, 0xbfb8aa3b, v55
	v_exp_f32_e32 v62, v62
	v_exp_f32_e32 v63, v63
	s_nop 0
	v_pk_add_f32 v[62:63], v[62:63], 1.0 op_sel_hi:[1,0]
	s_nop 0
	s_nop 0
	v_rcp_f32_e32 v63, v63
	s_nop 0
	s_nop 0
	v_rcp_f32_e32 v62, v62
	s_nop 0
	v_pk_mul_f32 v[54:55], v[54:55], v[62:63]
	v_lshlrev_b32_e32 v62, 16, v56
	v_and_b32_e32 v63, 0xffff0000, v56
	v_pk_fma_f32 v[50:51], v[50:51], v[62:63], 0 op_sel_hi:[1,1,0]
	v_lshlrev_b32_e32 v62, 16, v64
	v_and_b32_e32 v63, 0xffff0000, v64
	v_pk_fma_f32 v[50:51], v[58:59], v[62:63], v[50:51]
	v_lshlrev_b32_e32 v58, 16, v72
	v_and_b32_e32 v59, 0xffff0000, v72
	v_pk_fma_f32 v[50:51], v[66:67], v[58:59], v[50:51]
	v_lshlrev_b32_e32 v58, 16, v80
	v_and_b32_e32 v59, 0xffff0000, v80
	s_waitcnt lgkmcnt(2)
	v_pk_fma_f32 v[50:51], v[74:75], v[58:59], v[50:51]
	s_nop 0
	v_mul_f32_e32 v56, 0xbfb8aa3b, v50
	v_exp_f32_e32 v58, v56
	v_mul_f32_e32 v56, 0xbfb8aa3b, v51
	v_exp_f32_e32 v59, v56
	s_nop 0
	v_pk_add_f32 v[58:59], v[58:59], 1.0 op_sel_hi:[1,0]
	s_nop 0
	s_nop 0
	v_rcp_f32_e32 v59, v59
	s_nop 0
	s_nop 0
	v_rcp_f32_e32 v58, v58
	s_nop 0
	v_lshlrev_b32_e32 v56, 16, v57
	v_and_b32_e32 v57, 0xffff0000, v57
	v_pk_fma_f32 v[52:53], v[52:53], v[56:57], 0 op_sel_hi:[1,1,0]
	v_lshlrev_b32_e32 v56, 16, v65
	v_and_b32_e32 v57, 0xffff0000, v65
	v_pk_fma_f32 v[52:53], v[60:61], v[56:57], v[52:53]
	v_lshlrev_b32_e32 v56, 16, v73
	v_and_b32_e32 v57, 0xffff0000, v73
	v_pk_fma_f32 v[52:53], v[68:69], v[56:57], v[52:53]
	v_lshlrev_b32_e32 v56, 16, v81
	v_and_b32_e32 v57, 0xffff0000, v81
	v_pk_fma_f32 v[52:53], v[76:77], v[56:57], v[52:53]
	v_pk_mul_f32 v[50:51], v[50:51], v[58:59]
	v_mul_f32_e32 v56, 0xbfb8aa3b, v52
	v_mul_f32_e32 v57, 0xbfb8aa3b, v53
	v_exp_f32_e32 v56, v56
	v_exp_f32_e32 v57, v57
	s_nop 0
	v_pk_add_f32 v[56:57], v[56:57], 1.0 op_sel_hi:[1,0]
	s_nop 0
	s_nop 0
	v_rcp_f32_e32 v57, v57
	s_nop 0
	s_nop 0
	v_rcp_f32_e32 v56, v56
	s_nop 0
	v_pk_mul_f32 v[52:53], v[52:53], v[56:57]
	v_lshlrev_b32_e32 v56, 16, v6
	v_and_b32_e32 v57, 0xffff0000, v6
	v_pk_fma_f32 v[34:35], v[34:35], v[56:57], 0 op_sel_hi:[1,1,0]
	v_lshlrev_b32_e32 v56, 16, v14
	v_and_b32_e32 v57, 0xffff0000, v14
	v_pk_fma_f32 v[34:35], v[38:39], v[56:57], v[34:35]
	v_lshlrev_b32_e32 v38, 16, v22
	v_and_b32_e32 v39, 0xffff0000, v22
	v_pk_fma_f32 v[34:35], v[42:43], v[38:39], v[34:35]
	v_lshlrev_b32_e32 v38, 16, v26
	v_and_b32_e32 v39, 0xffff0000, v26
	s_waitcnt lgkmcnt(1)
	v_pk_fma_f32 v[34:35], v[46:47], v[38:39], v[34:35]
	s_nop 0
	v_mul_f32_e32 v6, 0xbfb8aa3b, v34
	v_exp_f32_e32 v38, v6
	v_mul_f32_e32 v6, 0xbfb8aa3b, v35
	v_exp_f32_e32 v39, v6
	s_nop 0
	v_pk_add_f32 v[38:39], v[38:39], 1.0 op_sel_hi:[1,0]
	s_nop 0
	s_nop 0
	v_rcp_f32_e32 v39, v39
	s_nop 0
	s_nop 0
	v_rcp_f32_e32 v38, v38
	s_nop 0
	v_lshlrev_b32_e32 v6, 16, v7
	v_and_b32_e32 v7, 0xffff0000, v7
	v_pk_fma_f32 v[6:7], v[36:37], v[6:7], 0 op_sel_hi:[1,1,0]
	v_lshlrev_b32_e32 v14, 16, v15
	v_and_b32_e32 v15, 0xffff0000, v15
	v_pk_fma_f32 v[6:7], v[40:41], v[14:15], v[6:7]
	v_lshlrev_b32_e32 v14, 16, v23
	v_and_b32_e32 v15, 0xffff0000, v23
	v_pk_fma_f32 v[6:7], v[44:45], v[14:15], v[6:7]
	v_lshlrev_b32_e32 v14, 16, v27
	v_and_b32_e32 v15, 0xffff0000, v27
	v_pk_fma_f32 v[6:7], v[48:49], v[14:15], v[6:7]
	v_pk_mul_f32 v[34:35], v[34:35], v[38:39]
	v_mul_f32_e32 v14, 0xbfb8aa3b, v6
	v_mul_f32_e32 v15, 0xbfb8aa3b, v7
	v_exp_f32_e32 v14, v14
	v_exp_f32_e32 v15, v15
	s_nop 0
	v_pk_add_f32 v[14:15], v[14:15], 1.0 op_sel_hi:[1,0]
	s_nop 0
	s_nop 0
	v_rcp_f32_e32 v15, v15
	s_nop 0
	s_nop 0
	v_rcp_f32_e32 v14, v14
	s_nop 0
	v_pk_mul_f32 v[6:7], v[6:7], v[14:15]
	v_lshlrev_b32_e32 v14, 16, v8
	v_and_b32_e32 v15, 0xffff0000, v8
	v_pk_fma_f32 v[2:3], v[2:3], v[14:15], 0 op_sel_hi:[1,1,0]
	v_lshlrev_b32_e32 v14, 16, v16
	v_and_b32_e32 v15, 0xffff0000, v16
	v_pk_fma_f32 v[2:3], v[10:11], v[14:15], v[2:3]
	v_lshlrev_b32_e32 v10, 16, v24
	v_and_b32_e32 v11, 0xffff0000, v24
	v_pk_fma_f32 v[2:3], v[18:19], v[10:11], v[2:3]
	v_lshlrev_b32_e32 v10, 16, v28
	v_and_b32_e32 v11, 0xffff0000, v28
	s_waitcnt lgkmcnt(0)
	v_pk_fma_f32 v[2:3], v[30:31], v[10:11], v[2:3]
	s_nop 0
	v_mul_f32_e32 v8, 0xbfb8aa3b, v2
	v_exp_f32_e32 v10, v8
	v_mul_f32_e32 v8, 0xbfb8aa3b, v3
	v_exp_f32_e32 v11, v8
	s_nop 0
	v_pk_add_f32 v[10:11], v[10:11], 1.0 op_sel_hi:[1,0]
	s_nop 0
	s_nop 0
	v_rcp_f32_e32 v11, v11
	s_nop 0
	s_nop 0
	v_rcp_f32_e32 v10, v10
	s_nop 0
	v_lshlrev_b32_e32 v8, 16, v9
	v_and_b32_e32 v9, 0xffff0000, v9
	v_pk_fma_f32 v[4:5], v[4:5], v[8:9], 0 op_sel_hi:[1,1,0]
	v_lshlrev_b32_e32 v8, 16, v17
	v_and_b32_e32 v9, 0xffff0000, v17
	v_pk_fma_f32 v[4:5], v[12:13], v[8:9], v[4:5]
	v_lshlrev_b32_e32 v8, 16, v25
	v_and_b32_e32 v9, 0xffff0000, v25
	v_pk_fma_f32 v[4:5], v[20:21], v[8:9], v[4:5]
	v_lshlrev_b32_e32 v8, 16, v29
	v_and_b32_e32 v9, 0xffff0000, v29
	v_pk_fma_f32 v[4:5], v[32:33], v[8:9], v[4:5]
	v_pk_mul_f32 v[2:3], v[2:3], v[10:11]
	v_mul_f32_e32 v8, 0xbfb8aa3b, v4
	v_mul_f32_e32 v9, 0xbfb8aa3b, v5
	v_exp_f32_e32 v8, v8
	v_exp_f32_e32 v9, v9
	s_nop 0
	v_pk_add_f32 v[8:9], v[8:9], 1.0 op_sel_hi:[1,0]
	s_nop 0
	s_nop 0
	v_rcp_f32_e32 v9, v9
	s_nop 0
	s_nop 0
	v_rcp_f32_e32 v8, v8
	s_nop 0
	v_pk_mul_f32 v[4:5], v[4:5], v[8:9]

.LBB0_880:
	s_or_b64 exec, exec, s[0:1]
	v_mad_u64_u32 v[36:37], s[0:1], v36, s29, v[40:41]
	s_waitcnt vmcnt(0)
	ds_write_b128 v36, v[32:35]
	v_or_b32_e32 v32, s6, v107
	v_ashrrev_i32_e32 v33, 31, v32
	v_lshlrev_b64 v[32:33], 13, v[32:33]
	v_lshl_add_u64 v[32:33], s[10:11], 0, v[32:33]
	s_lshl_b32 s14, s8, 2
	v_lshl_add_u64 v[32:33], v[32:33], 0, s[14:15]
	v_lshl_add_u64 v[48:49], v[116:117], 2, v[32:33]
	global_load_dwordx4 v[32:35], v[48:49], off offset:48
	global_load_dwordx4 v[36:39], v[48:49], off offset:32
	global_load_dwordx4 v[40:43], v[48:49], off offset:16
	global_load_dwordx4 v[44:47], v[48:49], off
	v_cmp_lt_u32_e32 vcc, 15, v122
	s_lshl_b32 s5, s5, 6
	s_waitcnt vmcnt(3)
	v_cndmask_b32_e64 v33, v33, 0, vcc
	s_waitcnt vmcnt(2)
	v_cndmask_b32_e64 v37, v37, 0, vcc
	s_waitcnt vmcnt(1)
	v_cndmask_b32_e64 v41, v41, 0, vcc
	s_waitcnt vmcnt(0)
	v_cndmask_b32_e64 v45, v45, 0, vcc
	v_cndmask_b32_e64 v44, v44, 0, vcc
	v_cndmask_b32_e64 v40, v40, 0, vcc
	v_cndmask_b32_e64 v36, v36, 0, vcc
	v_cndmask_b32_e64 v32, v32, 0, vcc
	v_cndmask_b32_e64 v47, v47, 0, vcc
	v_cndmask_b32_e64 v46, v46, 0, vcc
	v_cvt_pk_bf16_f32 v44, v44, v45
	v_cndmask_b32_e64 v43, v43, 0, vcc
	v_cndmask_b32_e64 v42, v42, 0, vcc
	v_cvt_pk_bf16_f32 v40, v40, v41
	v_cndmask_b32_e64 v39, v39, 0, vcc
	v_cndmask_b32_e64 v38, v38, 0, vcc
	v_cvt_pk_bf16_f32 v36, v36, v37
	v_cndmask_b32_e64 v35, v35, 0, vcc
	v_cndmask_b32_e64 v34, v34, 0, vcc
	v_cvt_pk_bf16_f32 v32, v32, v33
	v_cvt_pk_bf16_f32 v45, v46, v47
	ds_write_b16 v137, v44 offset:33792
	ds_write_b16_d16_hi v137, v44 offset:33936
	ds_write_b16 v137, v45 offset:34080
	ds_write_b16_d16_hi v137, v45 offset:34224
	v_cvt_pk_bf16_f32 v41, v42, v43
	ds_write_b16 v137, v40 offset:34368
	ds_write_b16_d16_hi v137, v40 offset:34512
	ds_write_b16 v137, v41 offset:34656
	ds_write_b16_d16_hi v137, v41 offset:34800
	v_cvt_pk_bf16_f32 v37, v38, v39
	ds_write_b16 v137, v36 offset:34944
	ds_write_b16_d16_hi v137, v36 offset:35088
	ds_write_b16 v137, v37 offset:35232
	ds_write_b16_d16_hi v137, v37 offset:35376
	v_cvt_pk_bf16_f32 v33, v34, v35
	ds_write_b16 v137, v32 offset:35520
	ds_write_b16_d16_hi v137, v32 offset:35664
	ds_write_b16 v137, v33 offset:35808
	ds_write_b16_d16_hi v137, v33 offset:35952
	global_load_dwordx4 v[32:35], v[48:49], off offset:112
	global_load_dwordx4 v[36:39], v[48:49], off offset:96
	global_load_dwordx4 v[40:43], v[48:49], off offset:80
	global_load_dwordx4 v[44:47], v[48:49], off offset:64
	s_waitcnt vmcnt(3)
	v_cndmask_b32_e64 v35, v35, 0, vcc
	s_waitcnt vmcnt(2)
	v_cndmask_b32_e64 v39, v39, 0, vcc
	s_waitcnt vmcnt(1)
	v_cndmask_b32_e64 v43, v43, 0, vcc
	s_waitcnt vmcnt(0)
	v_cndmask_b32_e64 v47, v47, 0, vcc
	v_cndmask_b32_e64 v46, v46, 0, vcc
	v_cndmask_b32_e64 v45, v45, 0, vcc
	v_cndmask_b32_e64 v44, v44, 0, vcc
	v_cndmask_b32_e64 v42, v42, 0, vcc
	v_cndmask_b32_e64 v41, v41, 0, vcc
	v_cndmask_b32_e64 v40, v40, 0, vcc
	v_cndmask_b32_e64 v38, v38, 0, vcc
	v_cndmask_b32_e64 v37, v37, 0, vcc
	v_cndmask_b32_e64 v36, v36, 0, vcc
	v_cndmask_b32_e64 v34, v34, 0, vcc
	v_cndmask_b32_e64 v33, v33, 0, vcc
	v_cndmask_b32_e64 v32, v32, 0, vcc
	v_cvt_pk_bf16_f32 v44, v44, v45
	v_cvt_pk_bf16_f32 v45, v46, v47
	v_cvt_pk_bf16_f32 v40, v40, v41
	v_cvt_pk_bf16_f32 v41, v42, v43
	v_cvt_pk_bf16_f32 v36, v36, v37
	v_cvt_pk_bf16_f32 v37, v38, v39
	v_cvt_pk_bf16_f32 v32, v32, v33
	v_cvt_pk_bf16_f32 v33, v34, v35
	ds_write_b16 v137, v44 offset:36096
	ds_write_b16_d16_hi v137, v44 offset:36240
	ds_write_b16 v137, v45 offset:36384
	ds_write_b16_d16_hi v137, v45 offset:36528
	ds_write_b16 v137, v40 offset:36672
	ds_write_b16_d16_hi v137, v40 offset:36816
	ds_write_b16 v137, v41 offset:36960
	ds_write_b16_d16_hi v137, v41 offset:37104
	ds_write_b16 v137, v36 offset:37248
	ds_write_b16_d16_hi v137, v36 offset:37392
	ds_write_b16 v137, v37 offset:37536
	ds_write_b16_d16_hi v137, v37 offset:37680
	ds_write_b16 v137, v32 offset:37824
	ds_write_b16_d16_hi v137, v32 offset:37968
	ds_write_b16 v137, v33 offset:38112
	ds_write_b16_d16_hi v137, v33 offset:38256
	s_waitcnt lgkmcnt(0)
	s_barrier
	ds_read_b128 v[32:35], v136
	ds_read_b128 v[36:39], v136 offset:64
	ds_read_b128 v[40:43], v136 offset:128
	ds_read_b128 v[44:47], v136 offset:192
	s_waitcnt lgkmcnt(3)
	v_mfma_f32_16x16x32_bf16 v[0:3], v[32:35], v[0:3], 0
	s_waitcnt lgkmcnt(2)
	v_mfma_f32_16x16x32_bf16 v[0:3], v[36:39], v[4:7], v[0:3]
	s_waitcnt lgkmcnt(1)
	v_mfma_f32_16x16x32_bf16 v[0:3], v[40:43], v[8:11], v[0:3]
	s_waitcnt lgkmcnt(0)
	v_mfma_f32_16x16x32_bf16 v[0:3], v[44:47], v[12:15], v[0:3]
	v_cvt_f32_i32_e32 v4, v135
	s_nop 6
	v_mov_b32_e32 v114, v0
	v_xad_u32 v0, v134, -1, v107
	v_cvt_f32_i32_e32 v0, v0
	v_and_b32_e32 v109, 0x7fffffff, v4
	v_pk_mul_f32 v[4:5], v[114:115], v[108:109]
	v_mov_b32_e32 v114, v1
	v_and_b32_e32 v109, 0x7fffffff, v0
	v_pk_mul_f32 v[0:1], v[114:115], v[108:109]
	v_mov_b32_e32 v114, v2
	v_sub_f32_e32 v6, v0, v1
	v_add_u32_e32 v0, -2, v135
	v_cvt_f32_i32_e32 v0, v0
	v_sub_f32_e32 v4, v4, v5
	v_max_f32_e32 v5, 0xff800000, v4
	v_and_b32_e32 v109, 0x7fffffff, v0
	v_pk_mul_f32 v[0:1], v[114:115], v[108:109]
	v_mov_b32_e32 v114, v3
	v_sub_f32_e32 v2, v0, v1
	v_add_u32_e32 v0, -3, v135
	v_cvt_f32_i32_e32 v0, v0
	v_max3_f32 v5, v5, v6, v2
	v_and_b32_e32 v109, 0x7fffffff, v0
	v_pk_mul_f32 v[0:1], v[114:115], v[108:109]
	s_nop 0
	v_sub_f32_e32 v0, v0, v1
	v_max3_f32 v1, v5, v0, s25
	ds_bpermute_b32 v3, v124, v1
	s_waitcnt lgkmcnt(0)
	v_max_f32_e32 v3, v3, v3
	v_max_f32_e32 v1, v1, v3
	ds_bpermute_b32 v3, v125, v1
	s_waitcnt lgkmcnt(0)
	v_max3_f32 v1, v96, v1, v3
	v_sub_f32_e32 v4, v4, v1
	v_exp_f32_e32 v32, v4
	v_sub_f32_e32 v5, v6, v1
	v_exp_f32_e32 v33, v5
	v_sub_f32_e32 v2, v2, v1
	v_exp_f32_e32 v34, v2
	v_sub_f32_e32 v0, v0, v1
	v_sub_f32_e32 v3, v96, v1
	v_exp_f32_e32 v35, v0
	v_sub_f32_e32 v1, 0xff800000, v1
	v_add_f32_e32 v4, 0, v32
	v_exp_f32_e32 v36, v1
	v_add_f32_e32 v4, v33, v4
	v_add_f32_e32 v2, v34, v4
	v_add_f32_e32 v0, v35, v2
	v_add_f32_e32 v0, v36, v0
	v_add_f32_e32 v0, v36, v0
	v_add_f32_e32 v0, v36, v0
	v_add_f32_e32 v0, v36, v0
	v_add_f32_e32 v0, v36, v0
	v_add_f32_e32 v0, v36, v0
	v_add_f32_e32 v0, v36, v0
	v_add_f32_e32 v0, v36, v0
	v_add_f32_e32 v0, v36, v0
	v_exp_f32_e32 v12, v3
	v_add_f32_e32 v0, v36, v0
	v_add_f32_e32 v0, v36, v0
	v_add_f32_e32 v52, v36, v0
	v_fmac_f32_e32 v52, v97, v12
	v_pk_mul_f32 v[2:3], v[30:31], v[12:13] op_sel_hi:[1,0]
	v_pk_mul_f32 v[0:1], v[28:29], v[12:13] op_sel_hi:[1,0]
	v_pk_mul_f32 v[6:7], v[26:27], v[12:13] op_sel_hi:[1,0]
	v_pk_mul_f32 v[4:5], v[24:25], v[12:13] op_sel_hi:[1,0]
	v_pk_mul_f32 v[10:11], v[22:23], v[12:13] op_sel_hi:[1,0]
	v_pk_mul_f32 v[8:9], v[20:21], v[12:13] op_sel_hi:[1,0]
	v_pk_mul_f32 v[14:15], v[18:19], v[12:13] op_sel_hi:[1,0]
	v_pk_mul_f32 v[12:13], v[16:17], v[12:13] op_sel_hi:[1,0]
	v_cvt_pk_bf16_f32 v16, v32, v33
	v_cvt_pk_bf16_f32 v17, v34, v35
	v_cvt_pk_bf16_f32 v18, v36, v36
	ds_read2_b64 v[20:23], v98 offset0:128 offset1:132
	ds_read2_b64 v[24:27], v99 offset0:160 offset1:164
	ds_read2_b64 v[28:31], v100 offset0:192 offset1:196
	ds_read2_b64 v[32:35], v101 offset0:128 offset1:132
	ds_read2_b64 v[36:39], v98 offset0:136 offset1:140
	ds_read2_b64 v[40:43], v99 offset0:168 offset1:172
	ds_read2_b64 v[44:47], v100 offset0:200 offset1:204
	ds_read2_b64 v[48:51], v101 offset0:136 offset1:140
	v_mov_b32_e32 v19, v18
	s_waitcnt lgkmcnt(7)
	s_nop 0
	v_mfma_f32_16x16x32_bf16 v[0:3], v[20:23], v[16:19], v[0:3]
	s_waitcnt lgkmcnt(6)
	v_mfma_f32_16x16x32_bf16 v[4:7], v[24:27], v[16:19], v[4:7]
	s_waitcnt lgkmcnt(5)
	v_mfma_f32_16x16x32_bf16 v[8:11], v[28:31], v[16:19], v[8:11]
	s_waitcnt lgkmcnt(4)
	v_mfma_f32_16x16x32_bf16 v[12:15], v[32:35], v[16:19], v[12:15]
	v_mov_b32_e32 v16, v18
	v_mov_b32_e32 v17, v18
	s_waitcnt lgkmcnt(3)
	s_nop 0
	v_mfma_f32_16x16x32_bf16 v[0:3], v[36:39], v[16:19], v[0:3]
	s_waitcnt lgkmcnt(2)
	v_mfma_f32_16x16x32_bf16 v[4:7], v[40:43], v[16:19], v[4:7]
	s_waitcnt lgkmcnt(1)
	v_mfma_f32_16x16x32_bf16 v[20:23], v[44:47], v[16:19], v[8:11]
	s_waitcnt lgkmcnt(0)
	v_mfma_f32_16x16x32_bf16 v[16:19], v[48:51], v[16:19], v[12:15]
	s_nop 0
	ds_bpermute_b32 v8, v124, v52
	s_cmp_eq_u32 s4, 0
	s_cselect_b64 s[38:39], -1, 0
	s_waitcnt lgkmcnt(0)
	s_barrier
	v_add_f32_e32 v8, v52, v8
	ds_bpermute_b32 v9, v125, v8
	s_waitcnt lgkmcnt(0)
	v_add_f32_e32 v8, v8, v9
	v_rcp_f32_e32 v24, v8
	s_nop 0
	v_pk_mul_f32 v[12:13], v[2:3], v[24:25] op_sel_hi:[1,0]
	v_pk_mul_f32 v[2:3], v[16:17], v[24:25] op_sel_hi:[1,0]
	v_or_b32_e32 v16, s5, v134
	v_pk_mul_f32 v[14:15], v[0:1], v[24:25] op_sel_hi:[1,0]
	v_pk_mul_f32 v[8:9], v[6:7], v[24:25] op_sel_hi:[1,0]
	v_pk_mul_f32 v[10:11], v[4:5], v[24:25] op_sel_hi:[1,0]
	v_pk_mul_f32 v[4:5], v[22:23], v[24:25] op_sel_hi:[1,0]
	v_pk_mul_f32 v[6:7], v[20:21], v[24:25] op_sel_hi:[1,0]
	v_pk_mul_f32 v[0:1], v[18:19], v[24:25] op_sel_hi:[1,0]
	s_and_b64 vcc, exec, s[38:39]
	v_lshlrev_b32_e32 v17, 2, v107
	v_lshlrev_b32_e32 v18, 6, v16
	s_cbranch_vccnz .LBB0_882
	v_add3_u32 v19, 0, v17, v18
	v_add_u32_e32 v20, 0x400, v19
	ds_write2_b32 v19, v14, v15 offset1:16
	ds_write2_b32 v19, v12, v13 offset0:32 offset1:48
	ds_write2_b32 v20, v10, v11 offset1:16
	ds_write2_b32 v20, v8, v9 offset0:32 offset1:48
	v_add_u32_e32 v20, 0x800, v19
	v_add_u32_e32 v19, 0xc00, v19
	ds_write2_b32 v20, v6, v7 offset1:16
	ds_write2_b32 v20, v4, v5 offset0:32 offset1:48
	ds_write2_b32 v19, v2, v3 offset1:16
	ds_write2_b32 v19, v0, v1 offset0:32 offset1:48

.LBB0_899:
	s_or_b64 exec, exec, s[36:37]
	v_readlane_b32 s36, v254, 46
	v_mov_b32_e32 v3, s14
	v_readlane_b32 s37, v254, 47
	v_and_b32_e32 v5, 64, v133
	v_add_u32_e32 v6, -1, v133
	v_cmp_lt_i32_e32 vcc, v6, v5
	v_and_b32_e32 v2, 63, v80
	s_waitcnt vmcnt(0)
	v_mul_f32_e32 v0, 0xbfb8aa3b, v0
	global_load_dword v3, v3, s[36:37]
	v_cndmask_b32_e32 v6, v6, v133, vcc
	v_lshlrev_b32_e32 v6, 2, v6
	v_cmp_eq_u32_e32 vcc, 0, v2
	v_exp_f32_e32 v0, v0
	v_readlane_b32 s38, v254, 48
	v_readlane_b32 s39, v254, 49
	v_readlane_b32 s40, v254, 50
	v_add_f32_e32 v0, 1.0, v0
	v_readlane_b32 s41, v254, 51
	v_readlane_b32 s42, v254, 52
	v_readlane_b32 s43, v254, 53
	v_readlane_b32 s44, v254, 54
	v_readlane_b32 s45, v254, 55
	v_readlane_b32 s46, v254, 56
	v_readlane_b32 s47, v254, 57
	v_readlane_b32 s48, v254, 58
	v_readlane_b32 s49, v254, 59
	v_readlane_b32 s50, v254, 60
	v_readlane_b32 s51, v254, 61
	s_waitcnt vmcnt(0)
	v_mul_f32_e32 v3, 0x3fb8aa3b, v3
	v_exp_f32_e32 v3, v3
	s_nop 0
	v_mul_f32_e64 v4, v1, -v3
	ds_bpermute_b32 v6, v6, v4
	s_waitcnt lgkmcnt(0)
	v_fma_f32 v1, v1, -v3, v6
	v_add_u32_e32 v3, -2, v133
	v_cndmask_b32_e32 v1, v1, v4, vcc
	v_cmp_lt_i32_e32 vcc, v3, v5
	s_nop 1
	v_cndmask_b32_e32 v3, v3, v133, vcc
	v_lshlrev_b32_e32 v3, 2, v3
	ds_bpermute_b32 v3, v3, v1
	v_cmp_gt_u32_e32 vcc, 2, v2
	s_waitcnt lgkmcnt(0)
	v_add_f32_e32 v3, v1, v3
	v_cndmask_b32_e32 v1, v3, v1, vcc
	v_add_u32_e32 v3, -4, v133
	v_cmp_lt_i32_e32 vcc, v3, v5
	s_nop 1
	v_cndmask_b32_e32 v3, v3, v133, vcc
	v_lshlrev_b32_e32 v3, 2, v3
	ds_bpermute_b32 v3, v3, v1
	v_cmp_gt_u32_e32 vcc, 4, v2
	s_waitcnt lgkmcnt(0)
	v_add_f32_e32 v3, v1, v3
	v_cndmask_b32_e32 v1, v3, v1, vcc
	v_add_u32_e32 v3, -8, v133
	v_cmp_lt_i32_e32 vcc, v3, v5
	s_nop 1
	v_cndmask_b32_e32 v3, v3, v133, vcc
	v_lshlrev_b32_e32 v3, 2, v3
	ds_bpermute_b32 v3, v3, v1
	v_cmp_gt_u32_e32 vcc, 8, v2
	s_waitcnt lgkmcnt(0)
	v_add_f32_e32 v3, v1, v3
	v_cndmask_b32_e32 v1, v3, v1, vcc
	v_add_u32_e32 v3, -16, v133
	v_cmp_lt_i32_e32 vcc, v3, v5
	s_nop 1
	v_cndmask_b32_e32 v3, v3, v133, vcc
	v_lshlrev_b32_e32 v3, 2, v3
	ds_bpermute_b32 v3, v3, v1
	v_cmp_gt_u32_e32 vcc, 16, v2
	s_waitcnt lgkmcnt(0)
	v_add_f32_e32 v3, v1, v3
	v_cndmask_b32_e32 v1, v3, v1, vcc
	v_subrev_u32_e32 v3, 32, v133
	v_cmp_lt_i32_e32 vcc, v3, v5
	s_nop 1
	v_cndmask_b32_e32 v3, v3, v133, vcc
	v_lshlrev_b32_e32 v3, 2, v3
	ds_bpermute_b32 v3, v3, v1
	v_cmp_gt_u32_e32 vcc, 32, v2
	s_waitcnt lgkmcnt(0)
	v_add_f32_e32 v2, v1, v3
	v_cndmask_b32_e32 v1, v2, v1, vcc
	s_nop 0
	v_rcp_f32_e32 v0, v0
	s_nop 0
	v_lshl_add_u32 v2, v80, 2, 0
	ds_write2st64_b32 v2, v1, v0 offset1:1
.LBB0_900:
	s_or_b64 exec, exec, s[0:1]
	s_waitcnt vmcnt(0)
	v_lshlrev_b32_e32 v0, 4, v80
	v_ashrrev_i32_e32 v82, 3, v80
	v_and_b32_e32 v81, 0x70, v0
	v_cmp_gt_i32_e64 s[36:37], 64, v82
	v_mov_b32_e32 v122, 0
	v_lshlrev_b32_e32 v104, 1, v81
	v_mov_b32_e32 v123, 0
	v_mov_b32_e32 v118, 0
	v_mov_b32_e32 v119, 0
	v_mov_b32_e32 v120, 0
	v_mov_b32_e32 v121, 0
	v_mov_b32_e32 v116, 0
	v_mov_b32_e32 v117, 0
	v_mov_b32_e32 v114, 0
	v_mov_b32_e32 v115, 0
	v_mov_b32_e32 v102, 0
	v_mov_b32_e32 v103, 0
	v_mov_b32_e32 v112, 0
	v_mov_b32_e32 v113, 0
	v_mov_b32_e32 v100, 0
	v_mov_b32_e32 v101, 0
	v_mov_b32_e32 v92, 0
	v_mov_b32_e32 v93, 0
	v_mov_b32_e32 v90, 0
	v_mov_b32_e32 v91, 0
	v_mov_b32_e32 v94, 0
	v_mov_b32_e32 v95, 0
	v_mov_b32_e32 v88, 0
	v_mov_b32_e32 v89, 0
	v_mov_b32_e32 v96, 0
	v_mov_b32_e32 v97, 0
	v_mov_b32_e32 v86, 0
	v_mov_b32_e32 v87, 0
	v_mov_b32_e32 v98, 0
	v_mov_b32_e32 v99, 0
	v_mov_b32_e32 v84, 0
	v_mov_b32_e32 v85, 0
	s_waitcnt lgkmcnt(0)
	s_barrier
	s_and_saveexec_b64 s[0:1], s[36:37]
	s_cbranch_execz .LBB0_902
	v_mul_lo_u32 v0, v82, s23
	v_lshl_add_u32 v52, v81, 2, 0
	v_add3_u32 v72, 0, v104, v0
	v_add_u32_e32 v45, 0x1ca00, v52
	ds_read_b128 v[24:27], v72 offset:35328
	ds_read_b128 v[0:3], v72 offset:35344
	ds_read_b128 v[54:57], v45
	ds_read_b128 v[28:31], v45 offset:16
	ds_read_b128 v[12:15], v45 offset:32
	ds_read_b128 v[4:7], v45 offset:48
	s_waitcnt lgkmcnt(4)
	v_lshlrev_b32_e32 v8, 16, v3
	s_waitcnt lgkmcnt(0)
	v_mul_f32_e32 v44, v6, v8
	ds_read_b128 v[36:39], v72 offset:36112
	ds_read_b128 v[8:11], v72 offset:36128
	ds_read_b128 v[58:61], v45 offset:512
	ds_read_b128 v[40:43], v45 offset:528
	ds_read_b128 v[20:23], v45 offset:544
	ds_read_b128 v[16:19], v45 offset:560
	v_and_b32_e32 v32, 0xffff0000, v3
	s_waitcnt lgkmcnt(4)
	v_lshlrev_b32_e32 v6, 16, v11
	s_waitcnt lgkmcnt(0)
	v_mul_f32_e32 v46, v18, v6
	v_and_b32_e32 v33, 0xffff0000, v11
	v_mov_b32_e32 v18, v7
	v_pk_mul_f32 v[48:49], v[18:19], v[32:33]
	ds_read_b128 v[62:65], v72 offset:36896
	ds_read_b128 v[32:35], v72 offset:36912
	ds_read_b128 v[66:69], v45 offset:1024
	ds_read_b128 v[74:77], v45 offset:1040
	ds_read_b128 v[84:87], v45 offset:1056
	ds_read_b128 v[88:91], v45 offset:1072
	ds_read_b128 v[92:95], v72 offset:37680
	ds_read_b128 v[96:99], v72 offset:37696
	ds_read_b128 v[100:103], v45 offset:1536
	ds_read_b128 v[112:115], v45 offset:1552
	ds_read_b128 v[116:119], v45 offset:1568
	ds_read_b128 v[120:123], v45 offset:1584
	v_lshlrev_b32_e32 v18, 16, v36
	s_waitcnt lgkmcnt(10)
	v_lshlrev_b32_e32 v3, 16, v35
	s_waitcnt lgkmcnt(6)
	v_mul_f32_e32 v50, v90, v3
	s_waitcnt lgkmcnt(4)
	v_lshlrev_b32_e32 v3, 16, v99
	s_waitcnt lgkmcnt(0)
	v_mul_f32_e32 v70, v122, v3
	v_and_b32_e32 v7, 0xffff0000, v99
	v_and_b32_e32 v6, 0xffff0000, v35
	v_mov_b32_e32 v122, v91
	v_pk_mul_f32 v[78:79], v[122:123], v[6:7]
	v_lshlrev_b32_e32 v6, 16, v24
	v_and_b32_e32 v7, 0xffff0000, v24
	v_pk_fma_f32 v[6:7], v[54:55], v[6:7], 0 op_sel_hi:[1,1,0]
	v_and_b32_e32 v19, 0xffff0000, v36
	v_pk_fma_f32 v[6:7], v[58:59], v[18:19], v[6:7]
	v_lshlrev_b32_e32 v18, 16, v62
	v_and_b32_e32 v19, 0xffff0000, v62
	v_pk_fma_f32 v[6:7], v[66:67], v[18:19], v[6:7]
	v_lshlrev_b32_e32 v18, 16, v92
	v_and_b32_e32 v19, 0xffff0000, v92
	v_pk_fma_f32 v[6:7], v[100:101], v[18:19], v[6:7]
	v_lshlrev_b32_e32 v18, 16, v25
	v_and_b32_e32 v19, 0xffff0000, v25
	v_pk_fma_f32 v[18:19], v[56:57], v[18:19], 0 op_sel_hi:[1,1,0]
	v_lshlrev_b32_e32 v24, 16, v37
	v_and_b32_e32 v25, 0xffff0000, v37
	v_pk_fma_f32 v[18:19], v[60:61], v[24:25], v[18:19]
	v_lshlrev_b32_e32 v24, 16, v63
	v_and_b32_e32 v25, 0xffff0000, v63
	v_pk_fma_f32 v[18:19], v[68:69], v[24:25], v[18:19]
	v_lshlrev_b32_e32 v24, 16, v93
	v_and_b32_e32 v25, 0xffff0000, v93
	v_pk_fma_f32 v[18:19], v[102:103], v[24:25], v[18:19]
	v_lshlrev_b32_e32 v24, 16, v26
	v_and_b32_e32 v25, 0xffff0000, v26
	v_lshlrev_b32_e32 v26, 16, v27
	v_and_b32_e32 v27, 0xffff0000, v27
	v_pk_fma_f32 v[26:27], v[30:31], v[26:27], 0 op_sel_hi:[1,1,0]
	v_lshlrev_b32_e32 v30, 16, v39
	v_and_b32_e32 v31, 0xffff0000, v39
	v_pk_fma_f32 v[26:27], v[42:43], v[30:31], v[26:27]
	v_lshlrev_b32_e32 v30, 16, v65
	v_and_b32_e32 v31, 0xffff0000, v65
	v_pk_fma_f32 v[26:27], v[76:77], v[30:31], v[26:27]
	v_lshlrev_b32_e32 v30, 16, v95
	v_and_b32_e32 v31, 0xffff0000, v95
	v_pk_fma_f32 v[26:27], v[114:115], v[30:31], v[26:27]
	v_lshlrev_b32_e32 v30, 16, v0
	v_and_b32_e32 v31, 0xffff0000, v0
	v_pk_fma_f32 v[12:13], v[12:13], v[30:31], 0 op_sel_hi:[1,1,0]
	v_lshlrev_b32_e32 v30, 16, v8
	v_and_b32_e32 v31, 0xffff0000, v8
	v_pk_fma_f32 v[12:13], v[20:21], v[30:31], v[12:13]
	v_lshlrev_b32_e32 v20, 16, v32
	v_and_b32_e32 v21, 0xffff0000, v32
	v_pk_fma_f32 v[12:13], v[84:85], v[20:21], v[12:13]
	v_lshlrev_b32_e32 v20, 16, v96
	v_and_b32_e32 v21, 0xffff0000, v96
	v_mul_f32_e32 v3, 0xbfb8aa3b, v6
	v_pk_fma_f32 v[24:25], v[28:29], v[24:25], 0 op_sel_hi:[1,1,0]
	v_lshlrev_b32_e32 v28, 16, v38
	v_and_b32_e32 v29, 0xffff0000, v38
	v_pk_fma_f32 v[12:13], v[116:117], v[20:21], v[12:13]
	v_exp_f32_e32 v54, v3
	v_mul_f32_e32 v3, 0xbfb8aa3b, v7
	v_pk_fma_f32 v[24:25], v[40:41], v[28:29], v[24:25]
	v_lshlrev_b32_e32 v28, 16, v64
	v_and_b32_e32 v29, 0xffff0000, v64
	v_mul_f32_e32 v0, 0xbfb8aa3b, v12
	v_exp_f32_e32 v55, v3
	v_mul_f32_e32 v3, 0xbfb8aa3b, v18
	v_pk_fma_f32 v[24:25], v[74:75], v[28:29], v[24:25]
	v_lshlrev_b32_e32 v28, 16, v94
	v_and_b32_e32 v29, 0xffff0000, v94
	v_exp_f32_e32 v20, v0
	v_mul_f32_e32 v0, 0xbfb8aa3b, v13
	v_exp_f32_e32 v36, v3
	v_mul_f32_e32 v3, 0xbfb8aa3b, v19
	v_pk_fma_f32 v[24:25], v[112:113], v[28:29], v[24:25]
	v_exp_f32_e32 v21, v0
	v_lshlrev_b32_e32 v0, 16, v1
	v_and_b32_e32 v1, 0xffff0000, v1
	v_exp_f32_e32 v37, v3
	v_mul_f32_e32 v3, 0xbfb8aa3b, v24
	v_pk_fma_f32 v[0:1], v[14:15], v[0:1], 0 op_sel_hi:[1,1,0]
	v_lshlrev_b32_e32 v8, 16, v9
	v_and_b32_e32 v9, 0xffff0000, v9
	v_exp_f32_e32 v28, v3
	v_mul_f32_e32 v3, 0xbfb8aa3b, v25
	v_pk_fma_f32 v[0:1], v[22:23], v[8:9], v[0:1]
	v_lshlrev_b32_e32 v8, 16, v33
	v_and_b32_e32 v9, 0xffff0000, v33
	v_exp_f32_e32 v29, v3
	v_mul_f32_e32 v3, 0xbfb8aa3b, v26
	v_pk_fma_f32 v[0:1], v[86:87], v[8:9], v[0:1]
	v_lshlrev_b32_e32 v8, 16, v97
	v_and_b32_e32 v9, 0xffff0000, v97
	v_exp_f32_e32 v38, v3
	v_mul_f32_e32 v3, 0xbfb8aa3b, v27
	v_pk_fma_f32 v[0:1], v[118:119], v[8:9], v[0:1]
	v_exp_f32_e32 v39, v3
	v_mul_f32_e32 v3, 0xbfb8aa3b, v0
	v_exp_f32_e32 v8, v3
	v_mul_f32_e32 v3, 0xbfb8aa3b, v1
	v_lshlrev_b32_e32 v14, 16, v2
	v_and_b32_e32 v15, 0xffff0000, v2
	v_exp_f32_e32 v9, v3
	v_pk_fma_f32 v[2:3], v[4:5], v[14:15], 0 op_sel_hi:[1,1,0]
	v_lshlrev_b32_e32 v4, 16, v10
	v_and_b32_e32 v5, 0xffff0000, v10
	v_pk_fma_f32 v[2:3], v[16:17], v[4:5], v[2:3]
	v_lshlrev_b32_e32 v4, 16, v34
	v_and_b32_e32 v5, 0xffff0000, v34
	v_pk_fma_f32 v[2:3], v[88:89], v[4:5], v[2:3]
	v_lshlrev_b32_e32 v4, 16, v98
	v_and_b32_e32 v5, 0xffff0000, v98
	v_pk_fma_f32 v[2:3], v[120:121], v[4:5], v[2:3]
	v_mov_b32_e32 v45, v48
	v_mul_f32_e32 v4, 0xbfb8aa3b, v2
	v_exp_f32_e32 v10, v4
	v_mul_f32_e32 v4, 0xbfb8aa3b, v3
	v_exp_f32_e32 v11, v4
	v_pk_add_f32 v[4:5], v[44:45], 0 op_sel_hi:[1,0]
	v_mov_b32_e32 v47, v49
	v_pk_add_f32 v[4:5], v[4:5], v[46:47]
	v_mov_b32_e32 v51, v78
	v_pk_add_f32 v[4:5], v[4:5], v[50:51]
	v_mov_b32_e32 v71, v79
	v_pk_add_f32 v[4:5], v[4:5], v[70:71]
	v_pk_add_f32 v[30:31], v[8:9], 1.0 op_sel_hi:[1,0]
	v_mul_f32_e32 v14, 0xbfb8aa3b, v4
	v_mul_f32_e32 v15, 0xbfb8aa3b, v5
	v_exp_f32_e32 v14, v14
	v_exp_f32_e32 v15, v15
	v_pk_add_f32 v[8:9], v[10:11], 1.0 op_sel_hi:[1,0]
	v_pk_add_f32 v[32:33], v[36:37], 1.0 op_sel_hi:[1,0]
	v_pk_add_f32 v[22:23], v[38:39], 1.0 op_sel_hi:[1,0]
	v_pk_add_f32 v[16:17], v[14:15], 1.0 op_sel_hi:[1,0]
	v_pk_add_f32 v[14:15], v[20:21], 1.0 op_sel_hi:[1,0]
	v_pk_add_f32 v[20:21], v[28:29], 1.0 op_sel_hi:[1,0]
	v_pk_add_f32 v[28:29], v[54:55], 1.0 op_sel_hi:[1,0]
	v_add_u32_e32 v45, 0x1d200, v52
	v_rcp_f32_e32 v11, v17
	s_nop 0
	s_nop 0
	v_rcp_f32_e32 v10, v16
	s_nop 0
	v_pk_mul_f32 v[84:85], v[4:5], v[10:11]
	v_rcp_f32_e32 v17, v33
	s_nop 0
	s_nop 0
	v_rcp_f32_e32 v16, v32
	s_nop 0
	v_pk_mul_f32 v[90:91], v[18:19], v[16:17]
	v_rcp_f32_e32 v23, v23
	s_nop 0
	s_nop 0
	v_rcp_f32_e32 v22, v22
	s_nop 0
	v_pk_mul_f32 v[88:89], v[26:27], v[22:23]
	v_rcp_f32_e32 v31, v31
	s_nop 0
	s_nop 0
	v_rcp_f32_e32 v30, v30
	s_nop 0
	v_pk_mul_f32 v[86:87], v[0:1], v[30:31]
	v_rcp_f32_e32 v29, v29
	s_nop 0
	s_nop 0
	v_rcp_f32_e32 v28, v28
	s_nop 0
	v_pk_mul_f32 v[92:93], v[6:7], v[28:29]
	v_rcp_f32_e32 v21, v21
	s_nop 0
	s_nop 0
	v_rcp_f32_e32 v20, v20
	s_nop 0
	v_pk_mul_f32 v[94:95], v[24:25], v[20:21]
	v_rcp_f32_e32 v15, v15
	s_nop 0
	s_nop 0
	v_rcp_f32_e32 v14, v14
	s_nop 0
	v_pk_mul_f32 v[96:97], v[12:13], v[14:15]
	v_rcp_f32_e32 v9, v9
	s_nop 0
	s_nop 0
	v_rcp_f32_e32 v8, v8
	s_nop 0
	v_pk_mul_f32 v[98:99], v[2:3], v[8:9]
	ds_read_b128 v[20:23], v72 offset:35584
	ds_read_b128 v[0:3], v72 offset:35600
	ds_read_b128 v[54:57], v45
	ds_read_b128 v[32:35], v45 offset:16
	ds_read_b128 v[12:15], v45 offset:32
	ds_read_b128 v[4:7], v45 offset:48
	s_waitcnt lgkmcnt(4)
	v_lshlrev_b32_e32 v8, 16, v3
	s_waitcnt lgkmcnt(0)
	v_mul_f32_e32 v44, v6, v8
	ds_read_b128 v[36:39], v72 offset:36368
	ds_read_b128 v[8:11], v72 offset:36384
	ds_read_b128 v[58:61], v45 offset:512
	ds_read_b128 v[40:43], v45 offset:528
	ds_read_b128 v[24:27], v45 offset:544
	ds_read_b128 v[16:19], v45 offset:560
	v_and_b32_e32 v28, 0xffff0000, v3
	s_waitcnt lgkmcnt(4)
	v_lshlrev_b32_e32 v6, 16, v11
	s_waitcnt lgkmcnt(0)
	v_mul_f32_e32 v46, v18, v6
	v_and_b32_e32 v29, 0xffff0000, v11
	v_mov_b32_e32 v18, v7
	v_pk_mul_f32 v[48:49], v[18:19], v[28:29]
	ds_read_b128 v[62:65], v72 offset:37152
	ds_read_b128 v[28:31], v72 offset:37168
	ds_read_b128 v[66:69], v45 offset:1024
	ds_read_b128 v[74:77], v45 offset:1040
	ds_read_b128 v[100:103], v45 offset:1056
	ds_read_b128 v[112:115], v45 offset:1072
	ds_read_b128 v[116:119], v72 offset:37936
	ds_read_b128 v[120:123], v72 offset:37952
	ds_read_b128 v[134:137], v45 offset:1536
	ds_read_b128 v[138:141], v45 offset:1552
	ds_read_b128 v[142:145], v45 offset:1568
	ds_read_b128 v[146:149], v45 offset:1584
	v_lshlrev_b32_e32 v18, 16, v36
	s_waitcnt lgkmcnt(10)
	v_lshlrev_b32_e32 v3, 16, v31
	s_waitcnt lgkmcnt(6)
	v_mul_f32_e32 v50, v114, v3
	s_waitcnt lgkmcnt(4)
	v_lshlrev_b32_e32 v3, 16, v123
	s_waitcnt lgkmcnt(0)
	v_mul_f32_e32 v70, v148, v3
	v_and_b32_e32 v7, 0xffff0000, v123
	v_and_b32_e32 v6, 0xffff0000, v31
	v_mov_b32_e32 v148, v115
	v_pk_mul_f32 v[78:79], v[148:149], v[6:7]
	v_lshlrev_b32_e32 v6, 16, v20
	v_and_b32_e32 v7, 0xffff0000, v20
	v_pk_fma_f32 v[6:7], v[54:55], v[6:7], 0 op_sel_hi:[1,1,0]
	v_and_b32_e32 v19, 0xffff0000, v36
	v_pk_fma_f32 v[6:7], v[58:59], v[18:19], v[6:7]
	v_lshlrev_b32_e32 v18, 16, v62
	v_and_b32_e32 v19, 0xffff0000, v62
	v_pk_fma_f32 v[6:7], v[66:67], v[18:19], v[6:7]
	v_lshlrev_b32_e32 v18, 16, v116
	v_and_b32_e32 v19, 0xffff0000, v116
	v_pk_fma_f32 v[6:7], v[134:135], v[18:19], v[6:7]
	v_lshlrev_b32_e32 v18, 16, v21
	v_and_b32_e32 v19, 0xffff0000, v21
	v_pk_fma_f32 v[18:19], v[56:57], v[18:19], 0 op_sel_hi:[1,1,0]
	v_lshlrev_b32_e32 v20, 16, v37
	v_and_b32_e32 v21, 0xffff0000, v37
	v_pk_fma_f32 v[18:19], v[60:61], v[20:21], v[18:19]
	v_lshlrev_b32_e32 v20, 16, v63
	v_and_b32_e32 v21, 0xffff0000, v63
	v_pk_fma_f32 v[18:19], v[68:69], v[20:21], v[18:19]
	v_lshlrev_b32_e32 v20, 16, v117
	v_and_b32_e32 v21, 0xffff0000, v117
	v_pk_fma_f32 v[18:19], v[136:137], v[20:21], v[18:19]
	v_lshlrev_b32_e32 v20, 16, v22
	v_and_b32_e32 v21, 0xffff0000, v22
	v_lshlrev_b32_e32 v22, 16, v23
	v_and_b32_e32 v23, 0xffff0000, v23
	v_pk_fma_f32 v[20:21], v[32:33], v[20:21], 0 op_sel_hi:[1,1,0]
	v_lshlrev_b32_e32 v32, 16, v38
	v_and_b32_e32 v33, 0xffff0000, v38
	v_pk_fma_f32 v[22:23], v[34:35], v[22:23], 0 op_sel_hi:[1,1,0]
	v_lshlrev_b32_e32 v34, 16, v39
	v_and_b32_e32 v35, 0xffff0000, v39
	v_lshlrev_b32_e32 v38, 16, v0
	v_and_b32_e32 v39, 0xffff0000, v0
	v_pk_fma_f32 v[12:13], v[12:13], v[38:39], 0 op_sel_hi:[1,1,0]
	v_lshlrev_b32_e32 v38, 16, v8
	v_and_b32_e32 v39, 0xffff0000, v8
	v_pk_fma_f32 v[12:13], v[24:25], v[38:39], v[12:13]
	v_lshlrev_b32_e32 v24, 16, v28
	v_and_b32_e32 v25, 0xffff0000, v28
	v_pk_fma_f32 v[12:13], v[100:101], v[24:25], v[12:13]
	v_lshlrev_b32_e32 v24, 16, v120
	v_and_b32_e32 v25, 0xffff0000, v120
	v_mul_f32_e32 v3, 0xbfb8aa3b, v6
	v_pk_fma_f32 v[12:13], v[142:143], v[24:25], v[12:13]
	v_exp_f32_e32 v54, v3
	v_mul_f32_e32 v3, 0xbfb8aa3b, v7
	v_pk_fma_f32 v[20:21], v[40:41], v[32:33], v[20:21]
	v_lshlrev_b32_e32 v32, 16, v64
	v_and_b32_e32 v33, 0xffff0000, v64
	v_mul_f32_e32 v0, 0xbfb8aa3b, v12
	v_exp_f32_e32 v55, v3
	v_mul_f32_e32 v3, 0xbfb8aa3b, v18
	v_pk_fma_f32 v[20:21], v[74:75], v[32:33], v[20:21]
	v_lshlrev_b32_e32 v32, 16, v118
	v_and_b32_e32 v33, 0xffff0000, v118
	v_exp_f32_e32 v24, v0
	v_mul_f32_e32 v0, 0xbfb8aa3b, v13
	v_exp_f32_e32 v36, v3
	v_mul_f32_e32 v3, 0xbfb8aa3b, v19
	v_pk_fma_f32 v[20:21], v[138:139], v[32:33], v[20:21]
	v_pk_fma_f32 v[22:23], v[42:43], v[34:35], v[22:23]
	v_lshlrev_b32_e32 v34, 16, v65
	v_and_b32_e32 v35, 0xffff0000, v65
	v_exp_f32_e32 v25, v0
	v_lshlrev_b32_e32 v0, 16, v1
	v_and_b32_e32 v1, 0xffff0000, v1
	v_exp_f32_e32 v37, v3
	v_mul_f32_e32 v3, 0xbfb8aa3b, v20
	v_pk_fma_f32 v[22:23], v[76:77], v[34:35], v[22:23]
	v_lshlrev_b32_e32 v34, 16, v119
	v_and_b32_e32 v35, 0xffff0000, v119
	v_pk_fma_f32 v[0:1], v[14:15], v[0:1], 0 op_sel_hi:[1,1,0]
	v_lshlrev_b32_e32 v8, 16, v9
	v_and_b32_e32 v9, 0xffff0000, v9
	v_exp_f32_e32 v32, v3
	v_mul_f32_e32 v3, 0xbfb8aa3b, v21
	v_pk_fma_f32 v[22:23], v[140:141], v[34:35], v[22:23]
	v_pk_fma_f32 v[0:1], v[26:27], v[8:9], v[0:1]
	v_lshlrev_b32_e32 v8, 16, v29
	v_and_b32_e32 v9, 0xffff0000, v29
	v_exp_f32_e32 v33, v3
	v_mul_f32_e32 v3, 0xbfb8aa3b, v22
	v_pk_fma_f32 v[0:1], v[102:103], v[8:9], v[0:1]
	v_lshlrev_b32_e32 v8, 16, v121
	v_and_b32_e32 v9, 0xffff0000, v121
	v_exp_f32_e32 v34, v3
	v_mul_f32_e32 v3, 0xbfb8aa3b, v23
	v_pk_fma_f32 v[0:1], v[144:145], v[8:9], v[0:1]
	v_exp_f32_e32 v35, v3
	v_mul_f32_e32 v3, 0xbfb8aa3b, v0
	v_exp_f32_e32 v8, v3
	v_mul_f32_e32 v3, 0xbfb8aa3b, v1
	v_lshlrev_b32_e32 v14, 16, v2
	v_and_b32_e32 v15, 0xffff0000, v2
	v_exp_f32_e32 v9, v3
	v_pk_fma_f32 v[2:3], v[4:5], v[14:15], 0 op_sel_hi:[1,1,0]
	v_lshlrev_b32_e32 v4, 16, v10
	v_and_b32_e32 v5, 0xffff0000, v10
	v_pk_fma_f32 v[2:3], v[16:17], v[4:5], v[2:3]
	v_lshlrev_b32_e32 v4, 16, v30
	v_and_b32_e32 v5, 0xffff0000, v30
	v_pk_fma_f32 v[2:3], v[112:113], v[4:5], v[2:3]
	v_lshlrev_b32_e32 v4, 16, v122
	v_and_b32_e32 v5, 0xffff0000, v122
	v_pk_fma_f32 v[2:3], v[146:147], v[4:5], v[2:3]
	v_mov_b32_e32 v45, v48
	v_mul_f32_e32 v4, 0xbfb8aa3b, v2
	v_exp_f32_e32 v10, v4
	v_mul_f32_e32 v4, 0xbfb8aa3b, v3
	v_exp_f32_e32 v11, v4
	v_pk_add_f32 v[4:5], v[44:45], 0 op_sel_hi:[1,0]
	v_mov_b32_e32 v47, v49
	v_pk_add_f32 v[4:5], v[4:5], v[46:47]
	v_mov_b32_e32 v51, v78
	v_pk_add_f32 v[4:5], v[4:5], v[50:51]
	v_mov_b32_e32 v71, v79
	v_pk_add_f32 v[4:5], v[4:5], v[70:71]
	v_pk_add_f32 v[30:31], v[8:9], 1.0 op_sel_hi:[1,0]
	v_mul_f32_e32 v14, 0xbfb8aa3b, v4
	v_mul_f32_e32 v15, 0xbfb8aa3b, v5
	v_exp_f32_e32 v14, v14
	v_exp_f32_e32 v15, v15
	v_pk_add_f32 v[8:9], v[10:11], 1.0 op_sel_hi:[1,0]
	v_pk_add_f32 v[26:27], v[34:35], 1.0 op_sel_hi:[1,0]
	v_pk_add_f32 v[34:35], v[36:37], 1.0 op_sel_hi:[1,0]
	v_pk_add_f32 v[16:17], v[14:15], 1.0 op_sel_hi:[1,0]
	v_pk_add_f32 v[14:15], v[24:25], 1.0 op_sel_hi:[1,0]
	v_pk_add_f32 v[24:25], v[32:33], 1.0 op_sel_hi:[1,0]
	v_pk_add_f32 v[28:29], v[54:55], 1.0 op_sel_hi:[1,0]
	v_rcp_f32_e32 v11, v17
	s_nop 0
	s_nop 0
	v_rcp_f32_e32 v10, v16
	s_nop 0
	v_pk_mul_f32 v[100:101], v[4:5], v[10:11]
	v_rcp_f32_e32 v17, v35
	s_nop 0
	s_nop 0
	v_rcp_f32_e32 v16, v34
	s_nop 0
	v_pk_mul_f32 v[118:119], v[18:19], v[16:17]
	v_rcp_f32_e32 v27, v27
	s_nop 0
	s_nop 0
	v_rcp_f32_e32 v26, v26
	s_nop 0
	v_pk_mul_f32 v[116:117], v[22:23], v[26:27]
	v_rcp_f32_e32 v31, v31
	s_nop 0
	s_nop 0
	v_rcp_f32_e32 v30, v30
	s_nop 0
	v_pk_mul_f32 v[102:103], v[0:1], v[30:31]
	v_rcp_f32_e32 v29, v29
	s_nop 0
	s_nop 0
	v_rcp_f32_e32 v28, v28
	s_nop 0
	v_pk_mul_f32 v[122:123], v[6:7], v[28:29]
	v_add_u32_e32 v28, 0x1da00, v52
	v_rcp_f32_e32 v25, v25
	s_nop 0
	s_nop 0
	v_rcp_f32_e32 v24, v24
	s_nop 0
	v_pk_mul_f32 v[120:121], v[20:21], v[24:25]
	v_rcp_f32_e32 v15, v15
	s_nop 0
	s_nop 0
	v_rcp_f32_e32 v14, v14
	s_nop 0
	v_pk_mul_f32 v[114:115], v[12:13], v[14:15]
	v_rcp_f32_e32 v9, v9
	s_nop 0
	s_nop 0
	v_rcp_f32_e32 v8, v8
	s_nop 0
	v_pk_mul_f32 v[112:113], v[2:3], v[8:9]
	ds_read_b128 v[52:55], v72 offset:35840
	ds_read_b128 v[4:7], v72 offset:35856
	ds_read_b128 v[134:137], v28
	ds_read_b128 v[48:51], v28 offset:16
	ds_read_b128 v[32:35], v28 offset:32
	ds_read_b128 v[0:3], v28 offset:48
	ds_read_b128 v[60:63], v72 offset:36624
	ds_read_b128 v[12:15], v72 offset:36640
	ds_read_b128 v[138:141], v28 offset:512
	ds_read_b128 v[56:59], v28 offset:528
	ds_read_b128 v[36:39], v28 offset:544
	ds_read_b128 v[8:11], v28 offset:560
	ds_read_b128 v[68:71], v72 offset:37408
	ds_read_b128 v[20:23], v72 offset:37424
	ds_read_b128 v[142:145], v28 offset:1024
	ds_read_b128 v[64:67], v28 offset:1040
	ds_read_b128 v[40:43], v28 offset:1056
	ds_read_b128 v[16:19], v28 offset:1072
	ds_read_b128 v[76:79], v72 offset:38192
	ds_read_b128 v[24:27], v72 offset:38208
	ds_read_b128 v[146:149], v28 offset:1536
	ds_read_b128 v[72:75], v28 offset:1552
	ds_read_b128 v[44:47], v28 offset:1568
	ds_read_b128 v[28:31], v28 offset:1584
	s_waitcnt lgkmcnt(14)
	v_lshlrev_b32_e32 v124, 16, v52
	v_and_b32_e32 v125, 0xffff0000, v52
	v_pk_fma_f32 v[124:125], v[134:135], v[124:125], 0 op_sel_hi:[1,1,0]
	v_lshlrev_b32_e32 v134, 16, v60
	v_and_b32_e32 v135, 0xffff0000, v60
	v_pk_fma_f32 v[124:125], v[138:139], v[134:135], v[124:125]
	s_waitcnt lgkmcnt(11)
	v_lshlrev_b32_e32 v134, 16, v68
	v_and_b32_e32 v135, 0xffff0000, v68
	s_waitcnt lgkmcnt(9)
	v_pk_fma_f32 v[124:125], v[142:143], v[134:135], v[124:125]
	s_waitcnt lgkmcnt(5)
	v_lshlrev_b32_e32 v134, 16, v76
	v_and_b32_e32 v135, 0xffff0000, v76
	s_waitcnt lgkmcnt(3)
	v_pk_fma_f32 v[124:125], v[146:147], v[134:135], v[124:125]
	s_nop 0
	v_mul_f32_e32 v52, 0xbfb8aa3b, v124
	v_exp_f32_e32 v134, v52
	v_mul_f32_e32 v52, 0xbfb8aa3b, v125
	v_exp_f32_e32 v135, v52
	s_nop 0
	v_pk_add_f32 v[134:135], v[134:135], 1.0 op_sel_hi:[1,0]
	s_nop 0
	s_nop 0
	v_rcp_f32_e32 v135, v135
	s_nop 0
	s_nop 0
	v_rcp_f32_e32 v134, v134
	s_nop 0
	v_lshlrev_b32_e32 v52, 16, v53
	v_and_b32_e32 v53, 0xffff0000, v53
	v_pk_fma_f32 v[52:53], v[136:137], v[52:53], 0 op_sel_hi:[1,1,0]
	v_lshlrev_b32_e32 v60, 16, v61
	v_and_b32_e32 v61, 0xffff0000, v61
	v_pk_fma_f32 v[52:53], v[140:141], v[60:61], v[52:53]
	v_lshlrev_b32_e32 v60, 16, v69
	v_and_b32_e32 v61, 0xffff0000, v69
	v_pk_fma_f32 v[52:53], v[144:145], v[60:61], v[52:53]
	v_lshlrev_b32_e32 v60, 16, v77
	v_and_b32_e32 v61, 0xffff0000, v77
	v_pk_fma_f32 v[52:53], v[148:149], v[60:61], v[52:53]
	v_pk_mul_f32 v[124:125], v[124:125], v[134:135]
	v_mul_f32_e32 v60, 0xbfb8aa3b, v52
	v_mul_f32_e32 v61, 0xbfb8aa3b, v53
	v_exp_f32_e32 v60, v60
	v_exp_f32_e32 v61, v61
	s_nop 0
	v_pk_add_f32 v[60:61], v[60:61], 1.0 op_sel_hi:[1,0]
	s_nop 0
	s_nop 0
	v_rcp_f32_e32 v61, v61
	s_nop 0
	s_nop 0
	v_rcp_f32_e32 v60, v60
	s_nop 0
	v_pk_mul_f32 v[52:53], v[52:53], v[60:61]
	v_lshlrev_b32_e32 v60, 16, v54
	v_and_b32_e32 v61, 0xffff0000, v54
	v_pk_fma_f32 v[48:49], v[48:49], v[60:61], 0 op_sel_hi:[1,1,0]
	v_lshlrev_b32_e32 v60, 16, v62
	v_and_b32_e32 v61, 0xffff0000, v62
	v_pk_fma_f32 v[48:49], v[56:57], v[60:61], v[48:49]
	v_lshlrev_b32_e32 v56, 16, v70
	v_and_b32_e32 v57, 0xffff0000, v70
	v_pk_fma_f32 v[48:49], v[64:65], v[56:57], v[48:49]
	v_lshlrev_b32_e32 v56, 16, v78
	v_and_b32_e32 v57, 0xffff0000, v78
	s_waitcnt lgkmcnt(2)
	v_pk_fma_f32 v[48:49], v[72:73], v[56:57], v[48:49]
	s_nop 0
	v_mul_f32_e32 v54, 0xbfb8aa3b, v48
	v_exp_f32_e32 v56, v54
	v_mul_f32_e32 v54, 0xbfb8aa3b, v49
	v_exp_f32_e32 v57, v54
	s_nop 0
	v_pk_add_f32 v[56:57], v[56:57], 1.0 op_sel_hi:[1,0]
	s_nop 0
	s_nop 0
	v_rcp_f32_e32 v57, v57
	s_nop 0
	s_nop 0
	v_rcp_f32_e32 v56, v56
	s_nop 0
	v_lshlrev_b32_e32 v54, 16, v55
	v_and_b32_e32 v55, 0xffff0000, v55
	v_pk_fma_f32 v[50:51], v[50:51], v[54:55], 0 op_sel_hi:[1,1,0]
	v_lshlrev_b32_e32 v54, 16, v63
	v_and_b32_e32 v55, 0xffff0000, v63
	v_pk_fma_f32 v[50:51], v[58:59], v[54:55], v[50:51]
	v_lshlrev_b32_e32 v54, 16, v71
	v_and_b32_e32 v55, 0xffff0000, v71
	v_pk_fma_f32 v[50:51], v[66:67], v[54:55], v[50:51]
	v_lshlrev_b32_e32 v54, 16, v79
	v_and_b32_e32 v55, 0xffff0000, v79
	v_pk_fma_f32 v[50:51], v[74:75], v[54:55], v[50:51]
	v_pk_mul_f32 v[48:49], v[48:49], v[56:57]
	v_mul_f32_e32 v54, 0xbfb8aa3b, v50
	v_mul_f32_e32 v55, 0xbfb8aa3b, v51
	v_exp_f32_e32 v54, v54
	v_exp_f32_e32 v55, v55
	s_nop 0
	v_pk_add_f32 v[54:55], v[54:55], 1.0 op_sel_hi:[1,0]
	s_nop 0
	s_nop 0
	v_rcp_f32_e32 v55, v55
	s_nop 0
	s_nop 0
	v_rcp_f32_e32 v54, v54
	s_nop 0
	v_pk_mul_f32 v[50:51], v[50:51], v[54:55]
	v_lshlrev_b32_e32 v54, 16, v4
	v_and_b32_e32 v55, 0xffff0000, v4
	v_pk_fma_f32 v[32:33], v[32:33], v[54:55], 0 op_sel_hi:[1,1,0]
	v_lshlrev_b32_e32 v54, 16, v12
	v_and_b32_e32 v55, 0xffff0000, v12
	v_pk_fma_f32 v[32:33], v[36:37], v[54:55], v[32:33]
	v_lshlrev_b32_e32 v36, 16, v20
	v_and_b32_e32 v37, 0xffff0000, v20
	v_pk_fma_f32 v[32:33], v[40:41], v[36:37], v[32:33]
	v_lshlrev_b32_e32 v36, 16, v24
	v_and_b32_e32 v37, 0xffff0000, v24
	s_waitcnt lgkmcnt(1)
	v_pk_fma_f32 v[32:33], v[44:45], v[36:37], v[32:33]
	s_nop 0
	v_mul_f32_e32 v4, 0xbfb8aa3b, v32
	v_exp_f32_e32 v36, v4
	v_mul_f32_e32 v4, 0xbfb8aa3b, v33
	v_exp_f32_e32 v37, v4
	s_nop 0
	v_pk_add_f32 v[36:37], v[36:37], 1.0 op_sel_hi:[1,0]
	s_nop 0
	s_nop 0
	v_rcp_f32_e32 v37, v37
	s_nop 0
	s_nop 0
	v_rcp_f32_e32 v36, v36
	s_nop 0
	v_lshlrev_b32_e32 v4, 16, v5
	v_and_b32_e32 v5, 0xffff0000, v5
	v_pk_fma_f32 v[4:5], v[34:35], v[4:5], 0 op_sel_hi:[1,1,0]
	v_lshlrev_b32_e32 v12, 16, v13
	v_and_b32_e32 v13, 0xffff0000, v13
	v_pk_fma_f32 v[4:5], v[38:39], v[12:13], v[4:5]
	v_lshlrev_b32_e32 v12, 16, v21
	v_and_b32_e32 v13, 0xffff0000, v21
	v_pk_fma_f32 v[4:5], v[42:43], v[12:13], v[4:5]
	v_lshlrev_b32_e32 v12, 16, v25
	v_and_b32_e32 v13, 0xffff0000, v25
	v_pk_fma_f32 v[4:5], v[46:47], v[12:13], v[4:5]
	v_pk_mul_f32 v[32:33], v[32:33], v[36:37]
	v_mul_f32_e32 v12, 0xbfb8aa3b, v4
	v_mul_f32_e32 v13, 0xbfb8aa3b, v5
	v_exp_f32_e32 v12, v12
	v_exp_f32_e32 v13, v13
	s_nop 0
	v_pk_add_f32 v[12:13], v[12:13], 1.0 op_sel_hi:[1,0]
	s_nop 0
	s_nop 0
	v_rcp_f32_e32 v13, v13
	s_nop 0
	s_nop 0
	v_rcp_f32_e32 v12, v12
	s_nop 0
	v_pk_mul_f32 v[4:5], v[4:5], v[12:13]
	v_lshlrev_b32_e32 v12, 16, v6
	v_and_b32_e32 v13, 0xffff0000, v6
	v_pk_fma_f32 v[0:1], v[0:1], v[12:13], 0 op_sel_hi:[1,1,0]
	v_lshlrev_b32_e32 v12, 16, v14
	v_and_b32_e32 v13, 0xffff0000, v14
	v_pk_fma_f32 v[0:1], v[8:9], v[12:13], v[0:1]
	v_lshlrev_b32_e32 v8, 16, v22
	v_and_b32_e32 v9, 0xffff0000, v22
	v_pk_fma_f32 v[0:1], v[16:17], v[8:9], v[0:1]
	v_lshlrev_b32_e32 v8, 16, v26
	v_and_b32_e32 v9, 0xffff0000, v26
	s_waitcnt lgkmcnt(0)
	v_pk_fma_f32 v[0:1], v[28:29], v[8:9], v[0:1]
	s_nop 0
	v_mul_f32_e32 v6, 0xbfb8aa3b, v0
	v_exp_f32_e32 v8, v6
	v_mul_f32_e32 v6, 0xbfb8aa3b, v1
	v_exp_f32_e32 v9, v6
	s_nop 0
	v_pk_add_f32 v[8:9], v[8:9], 1.0 op_sel_hi:[1,0]
	s_nop 0
	s_nop 0
	v_rcp_f32_e32 v9, v9
	s_nop 0
	s_nop 0
	v_rcp_f32_e32 v8, v8
	s_nop 0
	v_lshlrev_b32_e32 v6, 16, v7
	v_and_b32_e32 v7, 0xffff0000, v7
	v_pk_fma_f32 v[2:3], v[2:3], v[6:7], 0 op_sel_hi:[1,1,0]
	v_lshlrev_b32_e32 v6, 16, v15
	v_and_b32_e32 v7, 0xffff0000, v15
	v_pk_fma_f32 v[2:3], v[10:11], v[6:7], v[2:3]
	v_lshlrev_b32_e32 v6, 16, v23
	v_and_b32_e32 v7, 0xffff0000, v23
	v_pk_fma_f32 v[2:3], v[18:19], v[6:7], v[2:3]
	v_lshlrev_b32_e32 v6, 16, v27
	v_and_b32_e32 v7, 0xffff0000, v27
	v_pk_fma_f32 v[2:3], v[30:31], v[6:7], v[2:3]
	v_pk_mul_f32 v[0:1], v[0:1], v[8:9]
	v_mul_f32_e32 v6, 0xbfb8aa3b, v2
	v_mul_f32_e32 v7, 0xbfb8aa3b, v3
	v_exp_f32_e32 v6, v6
	v_exp_f32_e32 v7, v7
	s_nop 0
	v_pk_add_f32 v[6:7], v[6:7], 1.0 op_sel_hi:[1,0]
	s_nop 0
	s_nop 0
	v_rcp_f32_e32 v7, v7
	s_nop 0
	s_nop 0
	v_rcp_f32_e32 v6, v6
	s_nop 0
	v_pk_mul_f32 v[2:3], v[2:3], v[6:7]

.LBB0_1075:
	s_or_b64 exec, exec, s[10:11]
	v_lshlrev_b64 v[30:31], 5, v[64:65]
	v_mov_b32_e32 v21, v125
	v_lshl_add_u64 v[30:31], s[30:31], 0, v[30:31]
	v_lshl_add_u64 v[30:31], v[30:31], 0, v[20:21]
	v_add_co_u32_e32 v30, vcc, 0x1000, v30
	v_lshlrev_b32_e32 v47, 4, v22
	s_nop 0
	v_addc_co_u32_e32 v31, vcc, 0, v31, vcc
	global_load_dwordx2 v[122:123], v[30:31], off
	v_add_u32_e32 v73, 0, v47
	v_add_u32_e32 v26, v73, v28
	s_waitcnt lgkmcnt(0)
	s_barrier
	ds_read_b128 v[28:31], v26
	v_add_u32_e32 v21, v25, v47
	ds_read_b128 v[48:51], v26 offset:64
	ds_read_b128 v[52:55], v21 offset:62464
	ds_read_b128 v[56:59], v21 offset:62528
	s_waitcnt lgkmcnt(1)
	v_mfma_f32_16x16x32_bf16 v[28:31], v[28:31], v[52:55], 0
	ds_read_b128 v[60:63], v26 offset:128
	ds_read_b128 v[130:133], v26 offset:192
	s_movk_i32 s10, 0x50
	v_add_u32_e32 v73, v73, v24
	s_waitcnt lgkmcnt(2)
	v_mfma_f32_16x16x32_bf16 v[28:31], v[48:51], v[56:59], v[28:31]
	ds_read_b128 v[48:51], v21 offset:62592
	ds_read_b128 v[134:137], v21 offset:62656
	v_mul_lo_u32 v21, v64, s10
	v_add_u32_e32 v25, s8, v21
	s_waitcnt lgkmcnt(1)
	v_mfma_f32_16x16x32_bf16 v[28:31], v[60:63], v[48:51], v[28:31]
	v_add_u32_e32 v62, v25, v20
	s_movk_i32 s10, 0x440
	s_waitcnt vmcnt(1)
	v_pk_mul_f32 v[4:5], v[4:5], v[44:45] op_sel_hi:[1,0]
	s_waitcnt lgkmcnt(0)
	v_mfma_f32_16x16x32_bf16 v[28:31], v[130:133], v[134:137], v[28:31]
	v_mul_f32_e64 v2, v2, v44
	v_mul_f32_e64 v3, v3, v44
	v_pk_mul_f32 v[14:15], v[14:15], v[44:45] op_sel_hi:[1,0]
	v_pk_mul_f32 v[12:13], v[12:13], v[44:45] op_sel_hi:[1,0]
	s_waitcnt vmcnt(0)
	v_lshlrev_b32_e32 v20, 16, v122
	v_and_b32_e32 v21, 0xffff0000, v122
	v_lshlrev_b32_e32 v60, 16, v123
	v_and_b32_e32 v61, 0xffff0000, v123
	v_pk_add_f32 v[20:21], v[20:21], v[28:29] neg_lo:[0,1] neg_hi:[0,1]
	v_pk_add_f32 v[28:29], v[60:61], v[30:31] neg_lo:[0,1] neg_hi:[0,1]
	v_cvt_pk_bf16_f32 v20, v20, v21
	v_cvt_pk_bf16_f32 v21, v28, v29
	ds_write_b64 v62, v[20:21]
	s_waitcnt lgkmcnt(0)
	s_barrier
	ds_read_b128 v[28:31], v26 offset:17408
	ds_read_b128 v[60:63], v26 offset:17472
	s_waitcnt lgkmcnt(1)
	v_mfma_f32_16x16x32_bf16 v[28:31], v[28:31], v[52:55], 0
	ds_read_b128 v[52:55], v26 offset:17536
	v_add_u32_e32 v20, v26, v27
	v_add_u32_e32 v21, v25, v47
	s_waitcnt lgkmcnt(1)
	v_mfma_f32_16x16x32_bf16 v[28:31], v[60:63], v[56:59], v[28:31]
	ds_read_b128 v[56:59], v26 offset:17600
	ds_read_b128 v[60:63], v20 offset:34816
	v_ashrrev_i32_e32 v47, 3, v45
	s_waitcnt lgkmcnt(2)
	v_mfma_f32_16x16x32_bf16 v[26:29], v[52:55], v[48:51], v[28:31]
	ds_read_b128 v[48:51], v21
	v_lshl_add_u32 v20, v64, 1, 0
	v_mad_u32_u24 v25, v22, s10, v20
	s_waitcnt lgkmcnt(2)
	v_mfma_f32_16x16x32_bf16 v[26:29], v[56:59], v[134:137], v[26:29]
	v_mad_u32_u24 v30, v23, s15, v20
	v_cmp_gt_i32_e32 vcc, 16, v47
	s_waitcnt lgkmcnt(0)
	v_mfma_f32_16x16x32_bf16 v[20:23], v[60:63], v[48:51], v[26:29]
	s_nop 3
	v_mul_f32_e64 v26, v6, v44
	v_mul_f32_e64 v27, v7, v44
	s_nop 1
	v_cvt_pk_bf16_f32 v20, v20, s0
	v_cvt_pk_bf16_f32 v21, v21, s0
	v_cvt_pk_bf16_f32 v22, v22, s0
	v_cvt_pk_bf16_f32 v23, v23, s0
	ds_write_b16 v25, v20
	ds_write_b16 v30, v21
	ds_write_b16 v30, v22 offset:272
	ds_write_b16 v30, v23 offset:544
	ds_read_b128 v[20:23], v73 offset:44032
	ds_read_b128 v[52:55], v73 offset:45312
	v_pk_mul_f32 v[24:25], v[0:1], v[44:45] op_sel_hi:[1,0]
	ds_read_b128 v[56:59], v73 offset:46592
	ds_read_b128 v[60:63], v73 offset:47872
	s_waitcnt lgkmcnt(3)
	v_mfma_f32_16x16x32_bf16 v[28:31], v[20:23], v[48:51], v[24:27]
	v_mul_f32_e64 v0, v8, v44
	v_mul_f32_e64 v1, v9, v44
	v_pk_mul_f32 v[8:9], v[16:17], v[44:45] op_sel_hi:[1,0]
	s_waitcnt lgkmcnt(2)
	v_mfma_f32_16x16x32_bf16 v[24:27], v[52:55], v[48:51], v[2:5]
	ds_read_b128 v[52:55], v73 offset:50432
	s_nop 1
	ds_read_b128 v[4:7], v73 offset:49152
	v_pk_mul_f32 v[2:3], v[10:11], v[44:45] op_sel_hi:[1,0]
	v_pk_mul_f32 v[10:11], v[18:19], v[44:45] op_sel_hi:[1,0]
	s_waitcnt lgkmcnt(3)
	v_mfma_f32_16x16x32_bf16 v[20:23], v[56:59], v[48:51], v[12:15]
	s_waitcnt lgkmcnt(2)
	v_mfma_f32_16x16x32_bf16 v[16:19], v[60:63], v[48:51], v[0:3]
	s_nop 2
	v_mul_f32_e64 v2, v34, v44
	v_mul_f32_e64 v3, v35, v44
	v_pk_mul_f32 v[0:1], v[32:33], v[44:45] op_sel_hi:[1,0]
	ds_read_b128 v[32:35], v73 offset:51712
	s_waitcnt lgkmcnt(1)
	v_mfma_f32_16x16x32_bf16 v[12:15], v[4:7], v[48:51], v[8:11]
	v_mul_f32_e64 v6, v42, v44
	v_mul_f32_e64 v7, v43, v44
	v_pk_mul_f32 v[4:5], v[40:41], v[44:45] op_sel_hi:[1,0]
	ds_read_b128 v[40:43], v73 offset:52992
	v_mfma_f32_16x16x32_bf16 v[8:11], v[52:55], v[48:51], v[0:3]
	s_waitcnt lgkmcnt(0)
	s_barrier
	s_nop 0
	v_pk_mul_f32 v[2:3], v[38:39], v[44:45] op_sel_hi:[1,0]
	v_pk_mul_f32 v[0:1], v[36:37], v[44:45] op_sel_hi:[1,0]
	v_mfma_f32_16x16x32_bf16 v[4:7], v[32:35], v[48:51], v[4:7]
	v_cvt_pk_bf16_f32 v32, v28, v29
	v_cvt_pk_bf16_f32 v33, v30, v31
	v_cvt_pk_bf16_f32 v34, v24, v25
	v_mfma_f32_16x16x32_bf16 v[0:3], v[40:43], v[48:51], v[0:3]
	v_cvt_pk_bf16_f32 v35, v26, v27
	v_cvt_pk_bf16_f32 v36, v20, v21
	v_cvt_pk_bf16_f32 v37, v22, v23
	v_cvt_pk_bf16_f32 v38, v16, v17
	v_cvt_pk_bf16_f32 v39, v18, v19
	v_cvt_pk_bf16_f32 v40, v12, v13
	v_cvt_pk_bf16_f32 v41, v14, v15
	v_cvt_pk_bf16_f32 v42, v8, v9
	v_cvt_pk_bf16_f32 v43, v10, v11
	v_cvt_pk_bf16_f32 v48, v4, v5
	v_cvt_pk_bf16_f32 v49, v6, v7
	v_cvt_pk_bf16_f32 v50, v0, v1
	v_cvt_pk_bf16_f32 v51, v2, v3
	ds_write2_b64 v46, v[32:33], v[34:35] offset0:128 offset1:132
	ds_write2_b64 v46, v[36:37], v[38:39] offset0:136 offset1:140
	ds_write2_b64 v46, v[40:41], v[42:43] offset0:144 offset1:148
	ds_write2_b64 v46, v[48:49], v[50:51] offset0:152 offset1:156
	s_and_saveexec_b64 s[30:31], vcc
	s_cbranch_execz .LBB0_1077
	s_and_b32 s10, s36, 0xffffdff0
	v_add_u32_e32 v32, s10, v47
	v_add_u32_e32 v32, 0x2000, v32
	v_and_b32_e32 v36, 7, v45
	v_ashrrev_i32_e32 v33, 31, v32
	v_lshlrev_b64 v[32:33], 11, v[32:33]
	s_lshl_b32 s10, s29, 7
	v_lshlrev_b32_e32 v34, 4, v36
	v_or3_b32 v32, v32, s10, v34
	v_mul_lo_u32 v37, v47, s15
	v_lshlrev_b32_e32 v38, 5, v36
	v_lshlrev_b64 v[32:33], 1, v[32:33]
	v_lshl_add_u64 v[34:35], s[46:47], 0, v[32:33]
	v_lshl_add_u64 v[122:123], s[48:49], 0, v[32:33]
	v_add3_u32 v32, 0, v37, v38
	ds_read_b128 v[56:59], v32
	ds_read_b128 v[60:63], v32 offset:16
	v_and_b32_e32 v32, 64, v164
	v_add_u32_e32 v32, 64, v32
	v_xor_b32_e32 v33, 1, v164
	v_cmp_lt_i32_e32 vcc, v33, v32
	v_readlane_b32 s64, v254, 46
	v_lshlrev_b32_e32 v48, 6, v36
	v_cndmask_b32_e32 v33, v164, v33, vcc
	v_lshlrev_b32_e32 v77, 2, v33
	v_xor_b32_e32 v33, 2, v164
	v_cmp_lt_i32_e32 vcc, v33, v32
	v_readlane_b32 s68, v254, 50
	v_readlane_b32 s69, v254, 51
	v_cndmask_b32_e32 v33, v164, v33, vcc
	v_lshlrev_b32_e32 v75, 2, v33
	v_xor_b32_e32 v33, 4, v164
	v_cmp_lt_i32_e32 vcc, v33, v32
	s_waitcnt lgkmcnt(0)
	v_lshlrev_b32_e32 v132, 16, v62
	v_and_b32_e32 v133, 0xffff0000, v62
	v_cndmask_b32_e32 v32, v164, v33, vcc
	v_lshlrev_b32_e32 v73, 2, v32
	global_load_dwordx4 v[52:55], v[34:35], off
	s_nop 0
	global_load_dwordx4 v[32:35], v[34:35], off offset:16
	s_nop 0
	global_load_dwordx4 v[36:39], v48, s[68:69] offset:48
	global_load_dwordx4 v[40:43], v48, s[68:69] offset:32
	global_load_dwordx4 v[44:47], v48, s[68:69] offset:16
	s_nop 0
	global_load_dwordx4 v[48:51], v48, s[68:69]
	v_lshlrev_b32_e32 v130, 16, v63
	v_and_b32_e32 v131, 0xffff0000, v63
	v_pk_mul_f32 v[62:63], v[132:133], v[132:133]
	v_pk_mul_f32 v[134:135], v[130:131], v[130:131]
	v_readlane_b32 s65, v254, 47
	v_readlane_b32 s66, v254, 48
	v_readlane_b32 s67, v254, 49
	v_readlane_b32 s70, v254, 52
	v_readlane_b32 s71, v254, 53
	v_readlane_b32 s72, v254, 54
	v_readlane_b32 s73, v254, 55
	v_readlane_b32 s74, v254, 56
	v_readlane_b32 s75, v254, 57
	v_readlane_b32 s76, v254, 58
	v_readlane_b32 s77, v254, 59
	v_readlane_b32 s78, v254, 60
	v_readlane_b32 s79, v254, 61
	s_waitcnt vmcnt(5)
	v_lshlrev_b32_e32 v150, 16, v55
	s_waitcnt vmcnt(4)
	v_lshlrev_b32_e32 v136, 16, v34
	v_and_b32_e32 v137, 0xffff0000, v34
	v_mul_f32_e32 v34, 0xbfb8aa3b, v136
	v_exp_f32_e32 v138, v34
	v_mul_f32_e32 v34, 0xbfb8aa3b, v137
	v_exp_f32_e32 v139, v34
	v_lshlrev_b32_e32 v142, 16, v33
	v_and_b32_e32 v143, 0xffff0000, v33
	v_mul_f32_e32 v33, 0xbfb8aa3b, v142
	v_pk_add_f32 v[138:139], v[138:139], 1.0 op_sel_hi:[1,0]
	v_exp_f32_e32 v144, v33
	v_mul_f32_e32 v33, 0xbfb8aa3b, v143
	v_exp_f32_e32 v145, v33
	v_lshlrev_b32_e32 v146, 16, v32
	v_rcp_f32_e32 v139, v139
	s_nop 0
	v_pk_add_f32 v[144:145], v[144:145], 1.0 op_sel_hi:[1,0]
	v_and_b32_e32 v147, 0xffff0000, v32
	v_rcp_f32_e32 v138, v138
	s_nop 0
	v_pk_mul_f32 v[136:137], v[138:139], v[136:137]
	v_lshlrev_b32_e32 v138, 16, v61
	v_and_b32_e32 v139, 0xffff0000, v61
	v_rcp_f32_e32 v145, v145
	s_nop 0
	v_mul_f32_e32 v32, 0xbfb8aa3b, v146
	v_exp_f32_e32 v32, v32
	v_and_b32_e32 v151, 0xffff0000, v55
	v_rcp_f32_e32 v144, v144
	s_nop 0
	v_mul_f32_e32 v33, 0xbfb8aa3b, v147
	v_exp_f32_e32 v33, v33
	v_lshlrev_b32_e32 v154, 16, v54
	v_and_b32_e32 v155, 0xffff0000, v54
	v_lshlrev_b32_e32 v158, 16, v53
	v_pk_add_f32 v[32:33], v[32:33], 1.0 op_sel_hi:[1,0]
	v_and_b32_e32 v159, 0xffff0000, v53
	v_lshlrev_b32_e32 v168, 16, v52
	v_and_b32_e32 v169, 0xffff0000, v52
	v_pk_mul_f32 v[142:143], v[144:145], v[142:143]
	v_rcp_f32_e32 v33, v33
	s_nop 0
	v_lshlrev_b32_e32 v144, 16, v60
	v_and_b32_e32 v145, 0xffff0000, v60
	v_pk_mul_f32 v[60:61], v[144:145], v[144:145]
	v_rcp_f32_e32 v32, v32
	s_nop 0
	v_mul_f32_e32 v34, 0xbfb8aa3b, v150
	v_exp_f32_e32 v152, v34
	v_mul_f32_e32 v34, 0xbfb8aa3b, v151
	v_exp_f32_e32 v153, v34
	v_pk_mul_f32 v[32:33], v[32:33], v[146:147]
	v_lshlrev_b32_e32 v146, 16, v59
	v_and_b32_e32 v147, 0xffff0000, v59
	v_pk_add_f32 v[152:153], v[152:153], 1.0 op_sel_hi:[1,0]
	v_pk_mul_f32 v[148:149], v[146:147], v[146:147]
	v_pk_mul_f32 v[140:141], v[138:139], v[138:139]
	v_rcp_f32_e32 v153, v153
	s_nop 0
	s_nop 0
	v_rcp_f32_e32 v152, v152
	s_nop 0
	v_mul_f32_e32 v34, 0xbfb8aa3b, v154
	v_exp_f32_e32 v54, v34
	v_mul_f32_e32 v34, 0xbfb8aa3b, v155
	v_exp_f32_e32 v55, v34
	v_pk_mul_f32 v[150:151], v[152:153], v[150:151]
	v_lshlrev_b32_e32 v152, 16, v58
	v_and_b32_e32 v153, 0xffff0000, v58
	v_pk_add_f32 v[54:55], v[54:55], 1.0 op_sel_hi:[1,0]
	v_pk_mul_f32 v[58:59], v[152:153], v[152:153]
	s_nop 0
	v_rcp_f32_e32 v55, v55
	s_nop 0
	s_nop 0
	v_rcp_f32_e32 v54, v54
	s_nop 0
	v_mul_f32_e32 v34, 0xbfb8aa3b, v158
	v_exp_f32_e32 v166, v34
	v_mul_f32_e32 v34, 0xbfb8aa3b, v159
	v_exp_f32_e32 v167, v34
	v_pk_mul_f32 v[54:55], v[54:55], v[154:155]
	v_lshlrev_b32_e32 v154, 16, v57
	v_and_b32_e32 v155, 0xffff0000, v57
	v_pk_add_f32 v[166:167], v[166:167], 1.0 op_sel_hi:[1,0]
	v_pk_mul_f32 v[156:157], v[154:155], v[154:155]
	s_nop 0
	v_rcp_f32_e32 v167, v167
	s_nop 0
	s_nop 0
	v_rcp_f32_e32 v166, v166
	s_nop 0
	v_mul_f32_e32 v34, 0xbfb8aa3b, v168
	v_exp_f32_e32 v52, v34
	v_mul_f32_e32 v34, 0xbfb8aa3b, v169
	v_exp_f32_e32 v53, v34
	v_pk_mul_f32 v[158:159], v[166:167], v[158:159]
	v_lshlrev_b32_e32 v166, 16, v56
	v_and_b32_e32 v167, 0xffff0000, v56
	v_pk_add_f32 v[52:53], v[52:53], 1.0 op_sel_hi:[1,0]
	v_pk_mul_f32 v[56:57], v[166:167], v[166:167]
	s_nop 0
	v_rcp_f32_e32 v53, v53
	s_nop 0
	s_nop 0
	v_rcp_f32_e32 v52, v52
	s_nop 0
	v_add_f32_e32 v34, v56, v57
	v_add_f32_e32 v34, v156, v34
	v_add_f32_e32 v34, v157, v34
	v_add_f32_e32 v34, v58, v34
	v_add_f32_e32 v34, v59, v34
	v_add_f32_e32 v34, v148, v34
	v_add_f32_e32 v34, v149, v34
	v_add_f32_e32 v34, v60, v34
	v_add_f32_e32 v34, v61, v34
	v_add_f32_e32 v34, v140, v34
	v_add_f32_e32 v34, v141, v34
	v_add_f32_e32 v34, v62, v34
	v_add_f32_e32 v34, v63, v34
	v_add_f32_e32 v34, v134, v34
	v_add_f32_e32 v34, v135, v34
	ds_bpermute_b32 v56, v77, v34
	v_pk_mul_f32 v[52:53], v[52:53], v[168:169]
	s_waitcnt lgkmcnt(0)
	v_add_f32_e32 v34, v34, v56
	ds_bpermute_b32 v56, v75, v34
	s_waitcnt lgkmcnt(0)
	v_add_f32_e32 v34, v34, v56
	ds_bpermute_b32 v56, v73, v34
	s_waitcnt lgkmcnt(0)
	v_add_f32_e32 v34, v34, v56
	v_fmamk_f32 v34, v34, 0x3c000000, v162
	v_cmp_gt_f32_e32 vcc, s6, v34
	v_mul_f32_e32 v56, 0x4b800000, v34
	s_nop 0
	v_cndmask_b32_e32 v34, v34, v56, vcc
	v_rsq_f32_e32 v34, v34
	s_nop 0
	v_mul_f32_e32 v56, 0x45800000, v34
	v_cndmask_b32_e32 v56, v34, v56, vcc
	v_pk_mul_f32 v[58:59], v[56:57], v[166:167] op_sel_hi:[0,1]
	s_waitcnt vmcnt(0)
	v_pk_mul_f32 v[48:49], v[48:49], v[58:59]
	s_nop 0
	v_pk_mul_f32 v[48:49], v[52:53], v[48:49]
	v_pk_mul_f32 v[52:53], v[56:57], v[154:155] op_sel_hi:[0,1]
	v_pk_mul_f32 v[50:51], v[50:51], v[52:53]
	v_cvt_pk_bf16_f32 v48, v48, v49
	v_pk_mul_f32 v[50:51], v[158:159], v[50:51]
	s_nop 0
	v_cvt_pk_bf16_f32 v49, v50, v51
	v_pk_mul_f32 v[50:51], v[56:57], v[152:153] op_sel_hi:[0,1]
	v_pk_mul_f32 v[44:45], v[44:45], v[50:51]
	s_nop 0
	v_pk_mul_f32 v[44:45], v[54:55], v[44:45]
	s_nop 0
	v_cvt_pk_bf16_f32 v50, v44, v45
	v_pk_mul_f32 v[44:45], v[56:57], v[146:147] op_sel_hi:[0,1]
	v_pk_mul_f32 v[44:45], v[46:47], v[44:45]
	s_nop 0
	v_pk_mul_f32 v[44:45], v[150:151], v[44:45]
	s_nop 0
	v_cvt_pk_bf16_f32 v51, v44, v45
	v_pk_mul_f32 v[44:45], v[56:57], v[144:145] op_sel_hi:[0,1]
	v_pk_mul_f32 v[40:41], v[40:41], v[44:45]
	s_nop 0
	v_pk_mul_f32 v[32:33], v[32:33], v[40:41]
	v_pk_mul_f32 v[40:41], v[56:57], v[138:139] op_sel_hi:[0,1]
	v_pk_mul_f32 v[40:41], v[42:43], v[40:41]
	v_cvt_pk_bf16_f32 v32, v32, v33
	v_pk_mul_f32 v[40:41], v[142:143], v[40:41]
	v_pk_mul_f32 v[42:43], v[56:57], v[130:131] op_sel_hi:[0,1]
	v_cvt_pk_bf16_f32 v33, v40, v41
	v_pk_mul_f32 v[40:41], v[56:57], v[132:133] op_sel_hi:[0,1]
	v_pk_mul_f32 v[36:37], v[36:37], v[40:41]
	v_pk_mul_f32 v[38:39], v[38:39], v[42:43]
	v_pk_mul_f32 v[36:37], v[136:137], v[36:37]
	s_nop 0
	v_cvt_pk_bf16_f32 v34, v36, v37
	v_lshlrev_b32_e32 v36, 16, v35
	v_and_b32_e32 v37, 0xffff0000, v35
	v_mul_f32_e32 v35, 0xbfb8aa3b, v36
	v_exp_f32_e32 v40, v35
	v_mul_f32_e32 v35, 0xbfb8aa3b, v37
	v_exp_f32_e32 v41, v35
	s_nop 0
	v_pk_add_f32 v[40:41], v[40:41], 1.0 op_sel_hi:[1,0]
	s_nop 0
	s_nop 0
	v_rcp_f32_e32 v41, v41
	s_nop 0
	s_nop 0
	v_rcp_f32_e32 v40, v40
	s_nop 0
	v_pk_mul_f32 v[36:37], v[40:41], v[36:37]
	s_nop 0
	v_pk_mul_f32 v[36:37], v[36:37], v[38:39]
	s_nop 0
	v_cvt_pk_bf16_f32 v35, v36, v37
	global_store_dwordx4 v[122:123], v[48:51], off
	global_store_dwordx4 v[122:123], v[32:35], off offset:16

.LBB0_1107:
	s_or_b64 exec, exec, s[10:11]
	v_lshl_add_u64 v[32:33], s[30:31], 0, v[72:73]
	v_lshl_add_u64 v[32:33], v[32:33], 0, v[68:69]
	s_mov_b64 s[10:11], 0x4000
	v_lshl_add_u64 v[36:37], v[32:33], 0, s[10:11]
	v_add_co_u32_e32 v32, vcc, 0x4000, v32
	v_add_u32_e32 v57, v110, v68
	s_nop 0
	v_addc_co_u32_e32 v33, vcc, 0, v33, vcc
	global_load_dwordx2 v[62:63], v[32:33], off
	global_load_dwordx2 v[76:77], v[36:37], off offset:32
	global_load_dwordx2 v[34:35], v[36:37], off offset:64
	s_nop 0
	global_load_dwordx2 v[32:33], v[36:37], off offset:96
	v_add_u32_e32 v36, v66, v109
	s_waitcnt lgkmcnt(0)
	s_barrier
	ds_read_b128 v[52:55], v36 offset:62464
	ds_read_b128 v[48:51], v36 offset:62528
	ds_read_b128 v[44:47], v36 offset:62592
	ds_read_b128 v[40:43], v36 offset:62656
	ds_read_b128 v[36:39], v114
	ds_read_b128 v[58:61], v114 offset:64
	s_waitcnt lgkmcnt(1)
	v_mfma_f32_16x16x32_bf16 v[36:39], v[36:39], v[52:55], 0
	s_waitcnt lgkmcnt(0)
	v_mfma_f32_16x16x32_bf16 v[36:39], v[58:61], v[48:51], v[36:39]
	ds_read_b128 v[58:61], v114 offset:128
	s_waitcnt lgkmcnt(0)
	v_mfma_f32_16x16x32_bf16 v[36:39], v[58:61], v[44:47], v[36:39]
	ds_read_b128 v[58:61], v114 offset:192
	s_waitcnt lgkmcnt(0)
	v_mfma_f32_16x16x32_bf16 v[36:39], v[58:61], v[40:43], v[36:39]
	s_waitcnt vmcnt(3)
	v_lshlrev_b32_e32 v58, 16, v62
	v_and_b32_e32 v59, 0xffff0000, v62
	s_nop 4
	v_pk_add_f32 v[36:37], v[58:59], v[36:37] neg_lo:[0,1] neg_hi:[0,1]
	v_lshlrev_b32_e32 v58, 16, v63
	v_and_b32_e32 v59, 0xffff0000, v63
	v_pk_add_f32 v[38:39], v[58:59], v[38:39] neg_lo:[0,1] neg_hi:[0,1]
	v_cvt_pk_bf16_f32 v36, v36, v37
	v_cvt_pk_bf16_f32 v37, v38, v39
	ds_write_b64 v57, v[36:37]
	ds_read_b128 v[36:39], v114 offset:4352
	ds_read_b128 v[58:61], v114 offset:4416
	s_waitcnt lgkmcnt(1)
	v_mfma_f32_16x16x32_bf16 v[36:39], v[36:39], v[52:55], 0
	s_waitcnt lgkmcnt(0)
	v_mfma_f32_16x16x32_bf16 v[36:39], v[58:61], v[48:51], v[36:39]
	ds_read_b128 v[58:61], v114 offset:4480
	s_waitcnt lgkmcnt(0)
	v_mfma_f32_16x16x32_bf16 v[36:39], v[58:61], v[44:47], v[36:39]
	ds_read_b128 v[58:61], v114 offset:4544
	s_waitcnt lgkmcnt(0)
	v_mfma_f32_16x16x32_bf16 v[36:39], v[58:61], v[40:43], v[36:39]
	s_waitcnt vmcnt(2)
	v_lshlrev_b32_e32 v58, 16, v76
	v_and_b32_e32 v59, 0xffff0000, v76
	s_nop 4
	v_pk_add_f32 v[36:37], v[58:59], v[36:37] neg_lo:[0,1] neg_hi:[0,1]
	v_lshlrev_b32_e32 v58, 16, v77
	v_and_b32_e32 v59, 0xffff0000, v77
	v_pk_add_f32 v[38:39], v[58:59], v[38:39] neg_lo:[0,1] neg_hi:[0,1]
	v_cvt_pk_bf16_f32 v36, v36, v37
	v_cvt_pk_bf16_f32 v37, v38, v39
	ds_write_b64 v57, v[36:37] offset:32
	ds_read_b128 v[36:39], v114 offset:8704
	ds_read_b128 v[58:61], v114 offset:8768
	s_waitcnt lgkmcnt(1)
	v_mfma_f32_16x16x32_bf16 v[36:39], v[36:39], v[52:55], 0
	s_waitcnt lgkmcnt(0)
	v_mfma_f32_16x16x32_bf16 v[36:39], v[58:61], v[48:51], v[36:39]
	ds_read_b128 v[58:61], v114 offset:8832
	s_waitcnt lgkmcnt(0)
	v_mfma_f32_16x16x32_bf16 v[36:39], v[58:61], v[44:47], v[36:39]
	ds_read_b128 v[58:61], v114 offset:8896
	s_waitcnt lgkmcnt(0)
	v_mfma_f32_16x16x32_bf16 v[36:39], v[58:61], v[40:43], v[36:39]
	s_waitcnt vmcnt(1)
	v_lshlrev_b32_e32 v58, 16, v34
	v_and_b32_e32 v59, 0xffff0000, v34
	v_lshlrev_b32_e32 v34, 16, v35
	v_and_b32_e32 v35, 0xffff0000, v35
	s_nop 2
	v_pk_add_f32 v[36:37], v[58:59], v[36:37] neg_lo:[0,1] neg_hi:[0,1]
	v_pk_add_f32 v[34:35], v[34:35], v[38:39] neg_lo:[0,1] neg_hi:[0,1]
	v_cvt_pk_bf16_f32 v36, v36, v37
	v_cvt_pk_bf16_f32 v37, v34, v35
	ds_write_b64 v57, v[36:37] offset:64
	ds_read_b128 v[34:37], v114 offset:13056
	ds_read_b128 v[58:61], v114 offset:13120
	s_waitcnt lgkmcnt(1)
	v_mfma_f32_16x16x32_bf16 v[34:37], v[34:37], v[52:55], 0
	s_waitcnt vmcnt(0)
	v_lshlrev_b32_e32 v38, 16, v32
	v_and_b32_e32 v39, 0xffff0000, v32
	v_lshlrev_b32_e32 v32, 16, v33
	s_waitcnt lgkmcnt(0)
	v_mfma_f32_16x16x32_bf16 v[34:37], v[58:61], v[48:51], v[34:37]
	ds_read_b128 v[58:61], v114 offset:13184
	v_and_b32_e32 v33, 0xffff0000, v33
	s_waitcnt lgkmcnt(0)
	v_mfma_f32_16x16x32_bf16 v[34:37], v[58:61], v[44:47], v[34:37]
	ds_read_b128 v[58:61], v114 offset:13248
	s_waitcnt lgkmcnt(0)
	v_mfma_f32_16x16x32_bf16 v[34:37], v[58:61], v[40:43], v[34:37]
	s_nop 7
	v_pk_add_f32 v[34:35], v[38:39], v[34:35] neg_lo:[0,1] neg_hi:[0,1]
	v_pk_add_f32 v[32:33], v[32:33], v[36:37] neg_lo:[0,1] neg_hi:[0,1]
	v_cvt_pk_bf16_f32 v34, v34, v35
	v_cvt_pk_bf16_f32 v35, v32, v33
	v_add_u32_e32 v32, v110, v109
	ds_write_b64 v57, v[34:35] offset:96
	s_waitcnt lgkmcnt(0)
	s_barrier
	ds_read_b128 v[36:39], v32
	ds_read_b128 v[32:35], v32 offset:64
	ds_read_b128 v[58:61], v114 offset:17408
	ds_read_b128 v[76:79], v114 offset:17472
	s_waitcnt lgkmcnt(1)
	v_mfma_f32_16x16x32_bf16 v[58:61], v[58:61], v[52:55], 0
	s_waitcnt lgkmcnt(0)
	v_mfma_f32_16x16x32_bf16 v[58:61], v[76:79], v[48:51], v[58:61]
	ds_read_b128 v[76:79], v114 offset:17536
	s_waitcnt lgkmcnt(0)
	v_mfma_f32_16x16x32_bf16 v[58:61], v[76:79], v[44:47], v[58:61]
	ds_read_b128 v[76:79], v114 offset:17600
	s_waitcnt lgkmcnt(0)
	v_mfma_f32_16x16x32_bf16 v[58:61], v[76:79], v[40:43], v[58:61]
	ds_read_b128 v[76:79], v115 offset:34816
	s_waitcnt lgkmcnt(0)
	v_mfma_f32_16x16x32_bf16 v[58:61], v[76:79], v[36:39], v[58:61]
	ds_read_b128 v[76:79], v115 offset:34880
	s_waitcnt lgkmcnt(0)
	v_mfma_f32_16x16x32_bf16 v[58:61], v[76:79], v[32:35], v[58:61]
	s_nop 7
	v_cvt_pk_bf16_f32 v57, v58, s0
	ds_write_b16 v116, v57
	v_cvt_pk_bf16_f32 v57, v59, s0
	ds_write_b16 v117, v57
	v_cvt_pk_bf16_f32 v57, v60, s0
	ds_write_b16 v117, v57 offset:272
	v_cvt_pk_bf16_f32 v57, v61, s0
	ds_write_b16 v117, v57 offset:544
	ds_read_b128 v[58:61], v114 offset:21760
	ds_read_b128 v[76:79], v114 offset:21824
	s_waitcnt lgkmcnt(1)
	v_mfma_f32_16x16x32_bf16 v[58:61], v[58:61], v[52:55], 0
	s_waitcnt lgkmcnt(0)
	v_mfma_f32_16x16x32_bf16 v[58:61], v[76:79], v[48:51], v[58:61]
	ds_read_b128 v[76:79], v114 offset:21888
	s_waitcnt lgkmcnt(0)
	v_mfma_f32_16x16x32_bf16 v[58:61], v[76:79], v[44:47], v[58:61]
	ds_read_b128 v[76:79], v114 offset:21952
	s_waitcnt lgkmcnt(0)
	v_mfma_f32_16x16x32_bf16 v[58:61], v[76:79], v[40:43], v[58:61]
	ds_read_b128 v[76:79], v115 offset:37120
	s_waitcnt lgkmcnt(0)
	v_mfma_f32_16x16x32_bf16 v[58:61], v[76:79], v[36:39], v[58:61]
	ds_read_b128 v[76:79], v115 offset:37184
	s_waitcnt lgkmcnt(0)
	v_mfma_f32_16x16x32_bf16 v[58:61], v[76:79], v[32:35], v[58:61]
	s_nop 7
	v_cvt_pk_bf16_f32 v57, v58, s0
	ds_write_b16 v117, v57 offset:4080
	v_cvt_pk_bf16_f32 v57, v59, s0
	ds_write_b16 v117, v57 offset:4352
	v_cvt_pk_bf16_f32 v57, v60, s0
	ds_write_b16 v117, v57 offset:4624
	v_cvt_pk_bf16_f32 v57, v61, s0
	ds_write_b16 v117, v57 offset:4896
	ds_read_b128 v[58:61], v114 offset:26112
	ds_read_b128 v[76:79], v114 offset:26176
	s_waitcnt lgkmcnt(1)
	v_mfma_f32_16x16x32_bf16 v[58:61], v[58:61], v[52:55], 0
	s_waitcnt lgkmcnt(0)
	v_mfma_f32_16x16x32_bf16 v[58:61], v[76:79], v[48:51], v[58:61]
	ds_read_b128 v[76:79], v114 offset:26240
	s_waitcnt lgkmcnt(0)
	v_mfma_f32_16x16x32_bf16 v[58:61], v[76:79], v[44:47], v[58:61]
	ds_read_b128 v[76:79], v114 offset:26304
	s_waitcnt lgkmcnt(0)
	v_mfma_f32_16x16x32_bf16 v[58:61], v[76:79], v[40:43], v[58:61]
	ds_read_b128 v[76:79], v115 offset:39424
	s_waitcnt lgkmcnt(0)
	v_mfma_f32_16x16x32_bf16 v[58:61], v[76:79], v[36:39], v[58:61]
	ds_read_b128 v[76:79], v115 offset:39488
	s_waitcnt lgkmcnt(0)
	v_mfma_f32_16x16x32_bf16 v[58:61], v[76:79], v[32:35], v[58:61]
	s_nop 7
	v_cvt_pk_bf16_f32 v57, v58, s0
	ds_write_b16 v117, v57 offset:8432
	v_cvt_pk_bf16_f32 v57, v59, s0
	ds_write_b16 v117, v57 offset:8704
	v_cvt_pk_bf16_f32 v57, v60, s0
	ds_write_b16 v117, v57 offset:8976
	v_cvt_pk_bf16_f32 v57, v61, s0
	ds_write_b16 v117, v57 offset:9248
	ds_read_b128 v[58:61], v114 offset:30464
	s_waitcnt lgkmcnt(0)
	v_mfma_f32_16x16x32_bf16 v[52:55], v[58:61], v[52:55], 0
	ds_read_b128 v[58:61], v114 offset:30528
	v_pk_mul_f32 v[30:31], v[30:31], v[56:57] op_sel_hi:[1,0]
	v_pk_mul_f32 v[28:29], v[28:29], v[56:57] op_sel_hi:[1,0]
	s_waitcnt lgkmcnt(0)
	v_mfma_f32_16x16x32_bf16 v[48:51], v[58:61], v[48:51], v[52:55]
	s_nop 2
	ds_read_b128 v[52:55], v114 offset:30592
	v_pk_mul_f32 v[22:23], v[22:23], v[56:57] op_sel_hi:[1,0]
	v_pk_mul_f32 v[20:21], v[20:21], v[56:57] op_sel_hi:[1,0]
	s_waitcnt lgkmcnt(0)
	v_mfma_f32_16x16x32_bf16 v[44:47], v[52:55], v[44:47], v[48:51]
	s_nop 2
	ds_read_b128 v[48:51], v114 offset:30656
	v_pk_mul_f32 v[2:3], v[2:3], v[56:57] op_sel_hi:[1,0]
	v_pk_mul_f32 v[0:1], v[0:1], v[56:57] op_sel_hi:[1,0]
	s_waitcnt lgkmcnt(0)
	v_mfma_f32_16x16x32_bf16 v[40:43], v[48:51], v[40:43], v[44:47]
	s_nop 2
	ds_read_b128 v[44:47], v115 offset:41728
	v_pk_mul_f32 v[18:19], v[18:19], v[56:57] op_sel_hi:[1,0]
	v_pk_mul_f32 v[16:17], v[16:17], v[56:57] op_sel_hi:[1,0]
	s_waitcnt lgkmcnt(0)
	v_mfma_f32_16x16x32_bf16 v[40:43], v[44:47], v[36:39], v[40:43]
	ds_read_b128 v[44:47], v115 offset:41792
	v_pk_mul_f32 v[6:7], v[6:7], v[56:57] op_sel_hi:[1,0]
	v_pk_mul_f32 v[4:5], v[4:5], v[56:57] op_sel_hi:[1,0]
	s_waitcnt lgkmcnt(0)
	v_mfma_f32_16x16x32_bf16 v[40:43], v[44:47], v[32:35], v[40:43]
	v_mul_f32_e64 v14, v14, v56
	v_mul_f32_e64 v15, v15, v56
	v_pk_mul_f32 v[12:13], v[12:13], v[56:57] op_sel_hi:[1,0]
	v_pk_mul_f32 v[10:11], v[10:11], v[56:57] op_sel_hi:[1,0]
	s_nop 3
	v_cvt_pk_bf16_f32 v40, v40, s0
	ds_write_b16 v117, v40 offset:12784
	v_cvt_pk_bf16_f32 v40, v41, s0
	ds_write_b16 v117, v40 offset:13056
	v_cvt_pk_bf16_f32 v40, v42, s0
	ds_write_b16 v117, v40 offset:13328
	v_cvt_pk_bf16_f32 v40, v43, s0
	ds_write_b16 v117, v40 offset:13600
	ds_read_b128 v[40:43], v115 offset:44032
	s_waitcnt lgkmcnt(0)
	v_mfma_f32_16x16x32_bf16 v[28:31], v[40:43], v[36:39], v[28:31]
	ds_read_b128 v[40:43], v115 offset:44096
	v_pk_mul_f32 v[8:9], v[8:9], v[56:57] op_sel_hi:[1,0]
	v_pk_mul_f32 v[26:27], v[26:27], v[56:57] op_sel_hi:[1,0]
	s_waitcnt lgkmcnt(0)
	v_mfma_f32_16x16x32_bf16 v[28:31], v[40:43], v[32:35], v[28:31]
	ds_read_b128 v[40:43], v115 offset:46336
	v_pk_mul_f32 v[24:25], v[24:25], v[56:57] op_sel_hi:[1,0]
	s_waitcnt lgkmcnt(0)
	v_mfma_f32_16x16x32_bf16 v[20:23], v[40:43], v[36:39], v[20:23]
	ds_read_b128 v[40:43], v115 offset:46400
	s_waitcnt lgkmcnt(0)
	v_mfma_f32_16x16x32_bf16 v[20:23], v[40:43], v[32:35], v[20:23]
	ds_read_b128 v[40:43], v115 offset:48640
	s_waitcnt lgkmcnt(0)
	v_mfma_f32_16x16x32_bf16 v[0:3], v[40:43], v[36:39], v[0:3]
	ds_read_b128 v[40:43], v115 offset:48704
	s_waitcnt lgkmcnt(0)
	v_mfma_f32_16x16x32_bf16 v[0:3], v[40:43], v[32:35], v[0:3]
	ds_read_b128 v[40:43], v115 offset:50944
	s_waitcnt lgkmcnt(0)
	v_mfma_f32_16x16x32_bf16 v[16:19], v[40:43], v[36:39], v[16:19]
	ds_read_b128 v[40:43], v115 offset:51008
	s_waitcnt lgkmcnt(0)
	v_mfma_f32_16x16x32_bf16 v[16:19], v[40:43], v[32:35], v[16:19]
	ds_read_b128 v[40:43], v115 offset:53248
	s_waitcnt lgkmcnt(0)
	v_mfma_f32_16x16x32_bf16 v[4:7], v[40:43], v[36:39], v[4:7]
	ds_read_b128 v[40:43], v115 offset:53312
	s_waitcnt lgkmcnt(0)
	v_mfma_f32_16x16x32_bf16 v[4:7], v[40:43], v[32:35], v[4:7]
	ds_read_b128 v[40:43], v115 offset:55552
	s_waitcnt lgkmcnt(0)
	v_mfma_f32_16x16x32_bf16 v[12:15], v[40:43], v[36:39], v[12:15]
	ds_read_b128 v[40:43], v115 offset:55616
	s_waitcnt lgkmcnt(0)
	v_mfma_f32_16x16x32_bf16 v[12:15], v[40:43], v[32:35], v[12:15]
	ds_read_b128 v[40:43], v115 offset:57856
	s_waitcnt lgkmcnt(0)
	v_mfma_f32_16x16x32_bf16 v[8:11], v[40:43], v[36:39], v[8:11]
	ds_read_b128 v[40:43], v115 offset:57920
	s_waitcnt lgkmcnt(0)
	v_mfma_f32_16x16x32_bf16 v[8:11], v[40:43], v[32:35], v[8:11]
	ds_read_b128 v[40:43], v115 offset:60160
	s_waitcnt lgkmcnt(0)
	v_mfma_f32_16x16x32_bf16 v[24:27], v[40:43], v[36:39], v[24:27]
	ds_read_b128 v[36:39], v115 offset:60224
	s_waitcnt lgkmcnt(0)
	s_barrier
	v_mfma_f32_16x16x32_bf16 v[24:27], v[36:39], v[32:35], v[24:27]
	v_add_u32_e32 v36, v66, v68
	v_cvt_pk_bf16_f32 v32, v28, v29
	v_cvt_pk_bf16_f32 v33, v30, v31
	v_cvt_pk_bf16_f32 v34, v20, v21
	v_cvt_pk_bf16_f32 v35, v22, v23
	v_add_u32_e32 v36, 0xf000, v36
	ds_write2_b64 v36, v[32:33], v[34:35] offset0:128 offset1:132
	v_cvt_pk_bf16_f32 v32, v0, v1
	v_cvt_pk_bf16_f32 v33, v2, v3
	v_cvt_pk_bf16_f32 v34, v16, v17
	v_cvt_pk_bf16_f32 v35, v18, v19
	ds_write2_b64 v36, v[32:33], v[34:35] offset0:136 offset1:140
	v_cvt_pk_bf16_f32 v32, v4, v5
	v_cvt_pk_bf16_f32 v33, v6, v7
	v_cvt_pk_bf16_f32 v34, v12, v13
	v_cvt_pk_bf16_f32 v35, v14, v15
	ds_write2_b64 v36, v[32:33], v[34:35] offset0:144 offset1:148
	v_cvt_pk_bf16_f32 v32, v8, v9
	v_cvt_pk_bf16_f32 v33, v10, v11
	v_cvt_pk_bf16_f32 v34, v24, v25
	v_cvt_pk_bf16_f32 v35, v26, v27
	ds_write2_b64 v36, v[32:33], v[34:35] offset0:152 offset1:156
	s_and_saveexec_b64 s[30:31], s[40:41]
	s_cbranch_execz .LBB0_1097
	v_and_b32_e32 v32, 64, v164
	v_add_u32_e32 v32, 64, v32
	v_xor_b32_e32 v33, 1, v164
	v_cmp_lt_i32_e32 vcc, v33, v32
	ds_read_b128 v[52:55], v118
	ds_read_b128 v[60:63], v118 offset:16
	v_cndmask_b32_e32 v33, v164, v33, vcc
	v_lshlrev_b32_e32 v121, 2, v33
	v_xor_b32_e32 v33, 2, v164
	v_cmp_lt_i32_e32 vcc, v33, v32
	s_waitcnt lgkmcnt(0)
	v_lshlrev_b32_e32 v80, 16, v62
	v_and_b32_e32 v81, 0xffff0000, v62
	v_cndmask_b32_e32 v33, v164, v33, vcc
	v_lshlrev_b32_e32 v120, 2, v33
	v_xor_b32_e32 v33, 4, v164
	v_cmp_lt_i32_e32 vcc, v33, v32
	v_lshlrev_b32_e32 v78, 16, v63
	v_and_b32_e32 v79, 0xffff0000, v63
	v_cndmask_b32_e32 v32, v164, v33, vcc
	v_lshlrev_b32_e32 v119, 2, v32
	v_lshl_add_u32 v32, s0, 6, v112
	v_ashrrev_i32_e32 v33, 31, v32
	v_lshlrev_b64 v[76:77], 12, v[32:33]
	v_lshl_or_b32 v76, v70, 1, v76
	v_lshl_add_u64 v[32:33], s[46:47], 0, v[76:77]
	global_load_dwordx4 v[56:59], v[32:33], off
	s_nop 0
	global_load_dwordx4 v[32:35], v[32:33], off offset:16
	s_nop 0
	global_load_dwordx4 v[36:39], v[74:75], off offset:48
	global_load_dwordx4 v[40:43], v[74:75], off offset:32
	global_load_dwordx4 v[44:47], v[74:75], off offset:16
	global_load_dwordx4 v[48:51], v[74:75], off
	v_pk_mul_f32 v[62:63], v[80:81], v[80:81]
	v_pk_mul_f32 v[82:83], v[78:79], v[78:79]
	s_waitcnt vmcnt(5)
	v_lshlrev_b32_e32 v130, 16, v56
	s_waitcnt vmcnt(4)
	v_lshlrev_b32_e32 v84, 16, v34
	v_and_b32_e32 v85, 0xffff0000, v34
	v_mul_f32_e32 v34, 0xbfb8aa3b, v84
	v_exp_f32_e32 v86, v34
	v_mul_f32_e32 v34, 0xbfb8aa3b, v85
	v_exp_f32_e32 v87, v34
	v_and_b32_e32 v131, 0xffff0000, v56
	v_pk_add_f32 v[86:87], v[86:87], 1.0 op_sel_hi:[1,0]
	s_nop 0
	s_nop 0
	v_rcp_f32_e32 v87, v87
	s_nop 0
	s_nop 0
	v_lshlrev_b32_e32 v88, 16, v33
	v_and_b32_e32 v89, 0xffff0000, v33
	v_mul_f32_e32 v33, 0xbfb8aa3b, v88
	v_exp_f32_e32 v90, v33
	v_mul_f32_e32 v33, 0xbfb8aa3b, v89
	v_exp_f32_e32 v91, v33
	v_rcp_f32_e32 v86, v86
	s_nop 0
	v_pk_mul_f32 v[84:85], v[86:87], v[84:85]
	v_lshlrev_b32_e32 v86, 16, v61
	v_pk_add_f32 v[90:91], v[90:91], 1.0 op_sel_hi:[1,0]
	v_and_b32_e32 v87, 0xffff0000, v61
	v_pk_mul_f32 v[92:93], v[86:87], v[86:87]
	v_rcp_f32_e32 v91, v91
	s_nop 0
	s_nop 0
	v_lshlrev_b32_e32 v94, 16, v32
	v_and_b32_e32 v95, 0xffff0000, v32
	v_rcp_f32_e32 v90, v90
	s_nop 0
	v_mul_f32_e32 v32, 0xbfb8aa3b, v94
	v_mul_f32_e32 v33, 0xbfb8aa3b, v95
	v_exp_f32_e32 v32, v32
	v_exp_f32_e32 v33, v33
	v_pk_mul_f32 v[88:89], v[90:91], v[88:89]
	v_lshlrev_b32_e32 v90, 16, v60
	v_and_b32_e32 v91, 0xffff0000, v60
	v_pk_add_f32 v[32:33], v[32:33], 1.0 op_sel_hi:[1,0]
	v_pk_mul_f32 v[60:61], v[90:91], v[90:91]
	s_nop 0
	v_rcp_f32_e32 v33, v33
	s_nop 0
	s_nop 0
	v_lshlrev_b32_e32 v98, 16, v59
	v_rcp_f32_e32 v32, v32
	s_nop 0
	v_and_b32_e32 v99, 0xffff0000, v59
	v_mul_f32_e32 v34, 0xbfb8aa3b, v98
	v_exp_f32_e32 v100, v34
	v_mul_f32_e32 v34, 0xbfb8aa3b, v99
	v_exp_f32_e32 v101, v34
	v_pk_mul_f32 v[32:33], v[32:33], v[94:95]
	v_lshlrev_b32_e32 v94, 16, v55
	v_and_b32_e32 v95, 0xffff0000, v55
	v_pk_add_f32 v[100:101], v[100:101], 1.0 op_sel_hi:[1,0]
	v_pk_mul_f32 v[96:97], v[94:95], v[94:95]
	s_nop 0
	v_rcp_f32_e32 v101, v101
	s_nop 0
	s_nop 0
	v_lshlrev_b32_e32 v102, 16, v58
	v_rcp_f32_e32 v100, v100
	s_nop 0
	v_and_b32_e32 v103, 0xffff0000, v58
	v_mul_f32_e32 v34, 0xbfb8aa3b, v102
	v_exp_f32_e32 v58, v34
	v_mul_f32_e32 v34, 0xbfb8aa3b, v103
	v_exp_f32_e32 v59, v34
	v_pk_mul_f32 v[98:99], v[100:101], v[98:99]
	v_lshlrev_b32_e32 v100, 16, v54
	v_and_b32_e32 v101, 0xffff0000, v54
	v_pk_add_f32 v[58:59], v[58:59], 1.0 op_sel_hi:[1,0]
	v_pk_mul_f32 v[54:55], v[100:101], v[100:101]
	s_nop 0
	v_rcp_f32_e32 v59, v59
	s_nop 0
	s_nop 0
	v_lshlrev_b32_e32 v106, 16, v57
	v_rcp_f32_e32 v58, v58
	s_nop 0
	v_and_b32_e32 v107, 0xffff0000, v57
	v_mul_f32_e32 v34, 0xbfb8aa3b, v106
	v_exp_f32_e32 v122, v34
	v_mul_f32_e32 v34, 0xbfb8aa3b, v107
	v_exp_f32_e32 v123, v34
	v_pk_mul_f32 v[58:59], v[58:59], v[102:103]
	v_lshlrev_b32_e32 v102, 16, v53
	v_and_b32_e32 v103, 0xffff0000, v53
	v_pk_add_f32 v[122:123], v[122:123], 1.0 op_sel_hi:[1,0]
	v_pk_mul_f32 v[104:105], v[102:103], v[102:103]
	s_nop 0
	v_rcp_f32_e32 v123, v123
	s_nop 0
	s_nop 0
	v_rcp_f32_e32 v122, v122
	s_nop 0
	v_mul_f32_e32 v34, 0xbfb8aa3b, v130
	v_exp_f32_e32 v56, v34
	v_mul_f32_e32 v34, 0xbfb8aa3b, v131
	v_exp_f32_e32 v57, v34
	v_pk_mul_f32 v[106:107], v[122:123], v[106:107]
	v_lshlrev_b32_e32 v122, 16, v52
	v_and_b32_e32 v123, 0xffff0000, v52
	v_pk_add_f32 v[56:57], v[56:57], 1.0 op_sel_hi:[1,0]
	v_pk_mul_f32 v[52:53], v[122:123], v[122:123]
	s_nop 0
	v_rcp_f32_e32 v57, v57
	s_nop 0
	s_nop 0
	v_rcp_f32_e32 v56, v56
	s_nop 0
	v_add_f32_e32 v34, v52, v53
	v_add_f32_e32 v34, v104, v34
	v_add_f32_e32 v34, v105, v34
	v_add_f32_e32 v34, v54, v34
	v_add_f32_e32 v34, v55, v34
	v_add_f32_e32 v34, v96, v34
	v_add_f32_e32 v34, v97, v34
	v_add_f32_e32 v34, v60, v34
	v_add_f32_e32 v34, v61, v34
	v_add_f32_e32 v34, v92, v34
	v_add_f32_e32 v34, v93, v34
	v_add_f32_e32 v34, v62, v34
	v_add_f32_e32 v34, v63, v34
	v_add_f32_e32 v34, v82, v34
	v_add_f32_e32 v34, v83, v34
	ds_bpermute_b32 v52, v121, v34
	v_pk_mul_f32 v[56:57], v[56:57], v[130:131]
	s_waitcnt lgkmcnt(0)
	v_add_f32_e32 v34, v34, v52
	ds_bpermute_b32 v52, v120, v34
	s_waitcnt lgkmcnt(0)
	v_add_f32_e32 v34, v34, v52
	ds_bpermute_b32 v52, v119, v34
	s_waitcnt lgkmcnt(0)
	v_add_f32_e32 v34, v34, v52
	v_fmamk_f32 v34, v34, 0x3c000000, v162
	v_cmp_gt_f32_e32 vcc, s6, v34
	v_mul_f32_e32 v52, 0x4b800000, v34
	s_nop 0
	v_cndmask_b32_e32 v34, v34, v52, vcc
	v_rsq_f32_e32 v34, v34
	s_nop 0
	v_mul_f32_e32 v52, 0x45800000, v34
	v_cndmask_b32_e32 v52, v34, v52, vcc
	v_pk_mul_f32 v[54:55], v[52:53], v[122:123] op_sel_hi:[0,1]
	s_waitcnt vmcnt(0)
	v_pk_mul_f32 v[48:49], v[48:49], v[54:55]
	v_pk_mul_f32 v[54:55], v[52:53], v[102:103] op_sel_hi:[0,1]
	v_pk_mul_f32 v[50:51], v[50:51], v[54:55]
	v_pk_mul_f32 v[48:49], v[56:57], v[48:49]
	v_pk_mul_f32 v[50:51], v[106:107], v[50:51]
	v_cvt_pk_bf16_f32 v48, v48, v49
	v_cvt_pk_bf16_f32 v49, v50, v51
	v_pk_mul_f32 v[50:51], v[52:53], v[100:101] op_sel_hi:[0,1]
	v_pk_mul_f32 v[44:45], v[44:45], v[50:51]
	s_nop 0
	v_pk_mul_f32 v[44:45], v[58:59], v[44:45]
	s_nop 0
	v_cvt_pk_bf16_f32 v50, v44, v45
	v_pk_mul_f32 v[44:45], v[52:53], v[94:95] op_sel_hi:[0,1]
	v_pk_mul_f32 v[44:45], v[46:47], v[44:45]
	s_nop 0
	v_pk_mul_f32 v[44:45], v[98:99], v[44:45]
	s_nop 0
	v_cvt_pk_bf16_f32 v51, v44, v45
	v_pk_mul_f32 v[44:45], v[52:53], v[90:91] op_sel_hi:[0,1]
	v_pk_mul_f32 v[40:41], v[40:41], v[44:45]
	s_nop 0
	v_pk_mul_f32 v[32:33], v[32:33], v[40:41]
	v_pk_mul_f32 v[40:41], v[52:53], v[86:87] op_sel_hi:[0,1]
	v_pk_mul_f32 v[40:41], v[42:43], v[40:41]
	v_cvt_pk_bf16_f32 v32, v32, v33
	v_pk_mul_f32 v[40:41], v[88:89], v[40:41]
	v_pk_mul_f32 v[42:43], v[52:53], v[78:79] op_sel_hi:[0,1]
	v_cvt_pk_bf16_f32 v33, v40, v41
	v_pk_mul_f32 v[40:41], v[52:53], v[80:81] op_sel_hi:[0,1]
	v_pk_mul_f32 v[36:37], v[36:37], v[40:41]
	v_pk_mul_f32 v[38:39], v[38:39], v[42:43]
	v_pk_mul_f32 v[36:37], v[84:85], v[36:37]
	s_nop 0
	v_cvt_pk_bf16_f32 v34, v36, v37
	v_lshlrev_b32_e32 v36, 16, v35
	v_and_b32_e32 v37, 0xffff0000, v35
	v_mul_f32_e32 v35, 0xbfb8aa3b, v36
	v_exp_f32_e32 v40, v35
	v_mul_f32_e32 v35, 0xbfb8aa3b, v37
	v_exp_f32_e32 v41, v35
	s_nop 0
	v_pk_add_f32 v[40:41], v[40:41], 1.0 op_sel_hi:[1,0]
	s_nop 0
	s_nop 0
	v_rcp_f32_e32 v41, v41
	s_nop 0
	s_nop 0
	v_rcp_f32_e32 v40, v40
	s_nop 0
	v_pk_mul_f32 v[36:37], v[40:41], v[36:37]
	s_nop 0
	v_pk_mul_f32 v[36:37], v[36:37], v[38:39]
	s_nop 0
	v_cvt_pk_bf16_f32 v35, v36, v37
	v_lshl_add_u64 v[36:37], s[48:49], 0, v[76:77]
	global_store_dwordx4 v[36:37], v[48:51], off
	global_store_dwordx4 v[36:37], v[32:35], off offset:16
	s_branch .LBB0_1097

.LBB0_2229:
	s_add_u32 s31, vcc_lo, 0xfff80080
	s_addc_u32 s34, vcc_hi, -1
	s_add_i32 s35, 0, 0x10000
	v_add_u32_e32 v149, s35, v146
	ds_read_b128 v[150:153], v149
	ds_read_b128 v[154:157], v149 offset:1024
	ds_read_b128 v[158:161], v149 offset:2048
	ds_read_b128 v[162:165], v149 offset:3072
	s_cmp_eq_u32 s30, 28
	s_cselect_b32 s93, s89, s34
	s_cselect_b32 s92, s26, s31
	s_cselect_b32 s91, s27, s29
	s_cselect_b32 s90, s87, s28
	v_lshl_add_u64 v[198:199], vcc, 0, v[140:141]
	s_add_i32 m0, s19, 0xc000
	ds_read_b128 v[166:169], v148
	ds_read_b128 v[170:173], v148 offset:1024
	ds_read_b128 v[174:177], v148 offset:2048
	ds_read_b128 v[178:181], v148 offset:3072
	ds_read_b128 v[182:185], v148 offset:4096
	ds_read_b128 v[186:189], v148 offset:5120
	ds_read_b128 v[190:193], v148 offset:6144
	ds_read_b128 v[194:197], v148 offset:7168
	global_load_lds_dwordx4 v[198:199], off
	v_lshl_add_u64 v[198:199], vcc, 0, v[142:143]
	s_add_i32 m0, s19, 0xe000
	s_nop 0
	global_load_lds_dwordx4 v[198:199], off
	s_waitcnt lgkmcnt(8)
	s_barrier
	s_waitcnt lgkmcnt(0)
	s_setprio 1
	s_waitcnt lgkmcnt(0)
	v_mfma_f32_16x16x32_bf16 v[124:127], v[150:153], v[166:169], v[124:127]
	v_mfma_f32_16x16x32_bf16 v[116:119], v[158:161], v[166:169], v[116:119]
	v_mfma_f32_16x16x32_bf16 v[108:111], v[150:153], v[174:177], v[108:111]
	v_mfma_f32_16x16x32_bf16 v[100:103], v[158:161], v[174:177], v[100:103]
	v_mfma_f32_16x16x32_bf16 v[92:95], v[150:153], v[182:185], v[92:95]
	v_mfma_f32_16x16x32_bf16 v[84:87], v[158:161], v[182:185], v[84:87]
	v_mfma_f32_16x16x32_bf16 v[76:79], v[150:153], v[190:193], v[76:79]
	v_mfma_f32_16x16x32_bf16 v[68:71], v[158:161], v[190:193], v[68:71]
	v_mfma_f32_16x16x32_bf16 v[124:127], v[154:157], v[170:173], v[124:127]
	v_mfma_f32_16x16x32_bf16 v[116:119], v[162:165], v[170:173], v[116:119]
	v_mfma_f32_16x16x32_bf16 v[108:111], v[154:157], v[178:181], v[108:111]
	v_mfma_f32_16x16x32_bf16 v[100:103], v[162:165], v[178:181], v[100:103]
	v_mfma_f32_16x16x32_bf16 v[92:95], v[154:157], v[186:189], v[92:95]
	v_mfma_f32_16x16x32_bf16 v[84:87], v[162:165], v[186:189], v[84:87]
	v_mfma_f32_16x16x32_bf16 v[76:79], v[154:157], v[194:197], v[76:79]
	v_mfma_f32_16x16x32_bf16 v[68:71], v[162:165], v[194:197], v[68:71]
	s_setprio 0
	s_barrier
	s_add_i32 s31, 0, 0x14000
	s_add_i32 s34, s35, s18
	v_add_u32_e32 v149, s31, v146
	v_lshl_add_u64 v[214:215], s[90:91], 0, v[128:129]
	s_mov_b32 m0, s34
	ds_read_b128 v[198:201], v149
	ds_read_b128 v[202:205], v149 offset:1024
	ds_read_b128 v[206:209], v149 offset:2048
	ds_read_b128 v[210:213], v149 offset:3072
	global_load_lds_dwordx4 v[214:215], off
	v_lshl_add_u64 v[216:217], s[90:91], 0, v[138:139]
	s_add_i32 m0, s34, 0x2000
	s_nop 0
	global_load_lds_dwordx4 v[216:217], off
	s_barrier
	s_waitcnt lgkmcnt(0)
	s_setprio 1
	s_waitcnt lgkmcnt(0)
	v_mfma_f32_16x16x32_bf16 v[120:123], v[198:201], v[166:169], v[120:123]
	v_mfma_f32_16x16x32_bf16 v[112:115], v[206:209], v[166:169], v[112:115]
	v_mfma_f32_16x16x32_bf16 v[104:107], v[198:201], v[174:177], v[104:107]
	v_mfma_f32_16x16x32_bf16 v[96:99], v[206:209], v[174:177], v[96:99]
	v_mfma_f32_16x16x32_bf16 v[88:91], v[198:201], v[182:185], v[88:91]
	v_mfma_f32_16x16x32_bf16 v[80:83], v[206:209], v[182:185], v[80:83]
	v_mfma_f32_16x16x32_bf16 v[72:75], v[198:201], v[190:193], v[72:75]
	v_mfma_f32_16x16x32_bf16 v[64:67], v[206:209], v[190:193], v[64:67]
	v_mfma_f32_16x16x32_bf16 v[120:123], v[202:205], v[170:173], v[120:123]
	v_mfma_f32_16x16x32_bf16 v[112:115], v[210:213], v[170:173], v[112:115]
	v_mfma_f32_16x16x32_bf16 v[104:107], v[202:205], v[178:181], v[104:107]
	v_mfma_f32_16x16x32_bf16 v[96:99], v[210:213], v[178:181], v[96:99]
	v_mfma_f32_16x16x32_bf16 v[88:91], v[202:205], v[186:189], v[88:91]
	v_mfma_f32_16x16x32_bf16 v[80:83], v[210:213], v[186:189], v[80:83]
	v_mfma_f32_16x16x32_bf16 v[72:75], v[202:205], v[194:197], v[72:75]
	v_mfma_f32_16x16x32_bf16 v[64:67], v[210:213], v[194:197], v[64:67]
	s_setprio 0
	s_mov_b32 m0, s19
	v_lshl_add_u64 v[218:219], s[92:93], 0, v[134:135]
	s_barrier
	ds_read_b128 v[166:169], v148 offset:16384
	ds_read_b128 v[170:173], v148 offset:17408
	ds_read_b128 v[174:177], v148 offset:18432
	ds_read_b128 v[178:181], v148 offset:19456
	ds_read_b128 v[182:185], v148 offset:20480
	ds_read_b128 v[186:189], v148 offset:21504
	ds_read_b128 v[190:193], v148 offset:22528
	ds_read_b128 v[194:197], v148 offset:23552
	global_load_lds_dwordx4 v[218:219], off
	v_lshl_add_u64 v[220:221], s[92:93], 0, v[136:137]
	s_mov_b32 m0, s95
	s_nop 0
	global_load_lds_dwordx4 v[220:221], off
	s_barrier
	s_waitcnt lgkmcnt(0)
	s_setprio 1
	s_waitcnt lgkmcnt(0)
	v_mfma_f32_16x16x32_bf16 v[60:63], v[150:153], v[166:169], v[60:63]
	v_mfma_f32_16x16x32_bf16 v[52:55], v[158:161], v[166:169], v[52:55]
	v_mfma_f32_16x16x32_bf16 v[44:47], v[150:153], v[174:177], v[44:47]
	v_mfma_f32_16x16x32_bf16 v[36:39], v[158:161], v[174:177], v[36:39]
	v_mfma_f32_16x16x32_bf16 v[28:31], v[150:153], v[182:185], v[28:31]
	v_mfma_f32_16x16x32_bf16 v[20:23], v[158:161], v[182:185], v[20:23]
	v_mfma_f32_16x16x32_bf16 v[12:15], v[150:153], v[190:193], v[12:15]
	v_mfma_f32_16x16x32_bf16 v[4:7], v[158:161], v[190:193], v[4:7]
	v_mfma_f32_16x16x32_bf16 v[60:63], v[154:157], v[170:173], v[60:63]
	v_mfma_f32_16x16x32_bf16 v[52:55], v[162:165], v[170:173], v[52:55]
	v_mfma_f32_16x16x32_bf16 v[44:47], v[154:157], v[178:181], v[44:47]
	v_mfma_f32_16x16x32_bf16 v[36:39], v[162:165], v[178:181], v[36:39]
	v_mfma_f32_16x16x32_bf16 v[28:31], v[154:157], v[186:189], v[28:31]
	v_mfma_f32_16x16x32_bf16 v[20:23], v[162:165], v[186:189], v[20:23]
	v_mfma_f32_16x16x32_bf16 v[12:15], v[154:157], v[194:197], v[12:15]
	v_mfma_f32_16x16x32_bf16 v[4:7], v[162:165], v[194:197], v[4:7]
	s_setprio 0
	s_barrier
	s_add_u32 s34, s90, 0x80000
	s_addc_u32 s35, s91, 0
	s_add_i32 s31, s31, s18
	v_lshl_add_u64 v[150:151], s[34:35], 0, v[128:129]
	s_mov_b32 m0, s31
	s_nop 0
	global_load_lds_dwordx4 v[150:151], off
	v_lshl_add_u64 v[150:151], s[34:35], 0, v[138:139]
	s_add_i32 m0, s31, 0x2000
	s_nop 0
	global_load_lds_dwordx4 v[150:151], off
	s_waitcnt vmcnt(6)
	s_barrier
	s_setprio 1
	v_mfma_f32_16x16x32_bf16 v[56:59], v[198:201], v[166:169], v[56:59]
	v_mfma_f32_16x16x32_bf16 v[48:51], v[206:209], v[166:169], v[48:51]
	v_mfma_f32_16x16x32_bf16 v[40:43], v[198:201], v[174:177], v[40:43]
	v_mfma_f32_16x16x32_bf16 v[32:35], v[206:209], v[174:177], v[32:35]
	v_mfma_f32_16x16x32_bf16 v[24:27], v[198:201], v[182:185], v[24:27]
	v_mfma_f32_16x16x32_bf16 v[16:19], v[206:209], v[182:185], v[16:19]
	v_mfma_f32_16x16x32_bf16 v[8:11], v[198:201], v[190:193], v[8:11]
	v_mfma_f32_16x16x32_bf16 v[0:3], v[206:209], v[190:193], v[0:3]
	v_mfma_f32_16x16x32_bf16 v[56:59], v[202:205], v[170:173], v[56:59]
	v_mfma_f32_16x16x32_bf16 v[48:51], v[210:213], v[170:173], v[48:51]
	v_mfma_f32_16x16x32_bf16 v[40:43], v[202:205], v[178:181], v[40:43]
	v_mfma_f32_16x16x32_bf16 v[32:35], v[210:213], v[178:181], v[32:35]
	v_mfma_f32_16x16x32_bf16 v[24:27], v[202:205], v[186:189], v[24:27]
	v_mfma_f32_16x16x32_bf16 v[16:19], v[210:213], v[186:189], v[16:19]
	v_mfma_f32_16x16x32_bf16 v[8:11], v[202:205], v[194:197], v[8:11]
	v_mfma_f32_16x16x32_bf16 v[0:3], v[210:213], v[194:197], v[0:3]
	s_setprio 0
	s_add_i32 s31, 0, 0x18000
	v_add_u32_e32 v149, s31, v146
	s_barrier
	ds_read_b128 v[150:153], v149
	ds_read_b128 v[154:157], v149 offset:1024
	ds_read_b128 v[158:161], v149 offset:2048
	ds_read_b128 v[162:165], v149 offset:3072
	s_add_u32 s34, s92, 0x80000
	s_addc_u32 s35, s93, 0
	s_mov_b32 m0, s20
	v_lshl_add_u64 v[198:199], s[34:35], 0, v[134:135]
	ds_read_b128 v[166:169], v148 offset:32768
	ds_read_b128 v[170:173], v148 offset:33792
	ds_read_b128 v[174:177], v148 offset:34816
	ds_read_b128 v[178:181], v148 offset:35840
	ds_read_b128 v[182:185], v148 offset:36864
	ds_read_b128 v[186:189], v148 offset:37888
	ds_read_b128 v[190:193], v148 offset:38912
	ds_read_b128 v[194:197], v148 offset:39936
	global_load_lds_dwordx4 v[198:199], off
	v_lshl_add_u64 v[198:199], s[34:35], 0, v[136:137]
	s_mov_b32 m0, s21
	s_nop 0
	global_load_lds_dwordx4 v[198:199], off
	s_waitcnt lgkmcnt(8)
	s_barrier
	s_waitcnt lgkmcnt(0)
	s_setprio 1
	s_waitcnt lgkmcnt(0)
	v_mfma_f32_16x16x32_bf16 v[124:127], v[150:153], v[166:169], v[124:127]
	v_mfma_f32_16x16x32_bf16 v[116:119], v[158:161], v[166:169], v[116:119]
	v_mfma_f32_16x16x32_bf16 v[108:111], v[150:153], v[174:177], v[108:111]
	v_mfma_f32_16x16x32_bf16 v[100:103], v[158:161], v[174:177], v[100:103]
	v_mfma_f32_16x16x32_bf16 v[92:95], v[150:153], v[182:185], v[92:95]
	v_mfma_f32_16x16x32_bf16 v[84:87], v[158:161], v[182:185], v[84:87]
	v_mfma_f32_16x16x32_bf16 v[76:79], v[150:153], v[190:193], v[76:79]
	v_mfma_f32_16x16x32_bf16 v[68:71], v[158:161], v[190:193], v[68:71]
	v_mfma_f32_16x16x32_bf16 v[124:127], v[154:157], v[170:173], v[124:127]
	v_mfma_f32_16x16x32_bf16 v[116:119], v[162:165], v[170:173], v[116:119]
	v_mfma_f32_16x16x32_bf16 v[108:111], v[154:157], v[178:181], v[108:111]
	v_mfma_f32_16x16x32_bf16 v[100:103], v[162:165], v[178:181], v[100:103]
	v_mfma_f32_16x16x32_bf16 v[92:95], v[154:157], v[186:189], v[92:95]
	v_mfma_f32_16x16x32_bf16 v[84:87], v[162:165], v[186:189], v[84:87]
	v_mfma_f32_16x16x32_bf16 v[76:79], v[154:157], v[194:197], v[76:79]
	v_mfma_f32_16x16x32_bf16 v[68:71], v[162:165], v[194:197], v[68:71]
	s_setprio 0
	s_barrier
	s_add_i32 s92, 0, 0x1c000
	s_add_i32 s31, s31, s18
	v_add_u32_e32 v149, s92, v146
	v_lshl_add_u64 v[214:215], v[214:215], 0, s[84:85]
	s_mov_b32 m0, s31
	ds_read_b128 v[198:201], v149
	ds_read_b128 v[202:205], v149 offset:1024
	ds_read_b128 v[206:209], v149 offset:2048
	ds_read_b128 v[210:213], v149 offset:3072
	global_load_lds_dwordx4 v[214:215], off
	v_lshl_add_u64 v[214:215], v[216:217], 0, s[84:85]
	s_add_i32 m0, s31, 0x2000
	s_nop 0
	global_load_lds_dwordx4 v[214:215], off
	s_barrier
	s_waitcnt lgkmcnt(0)
	s_setprio 1
	s_waitcnt lgkmcnt(0)
	v_mfma_f32_16x16x32_bf16 v[120:123], v[198:201], v[166:169], v[120:123]
	v_mfma_f32_16x16x32_bf16 v[112:115], v[206:209], v[166:169], v[112:115]
	v_mfma_f32_16x16x32_bf16 v[104:107], v[198:201], v[174:177], v[104:107]
	v_mfma_f32_16x16x32_bf16 v[96:99], v[206:209], v[174:177], v[96:99]
	v_mfma_f32_16x16x32_bf16 v[88:91], v[198:201], v[182:185], v[88:91]
	v_mfma_f32_16x16x32_bf16 v[80:83], v[206:209], v[182:185], v[80:83]
	v_mfma_f32_16x16x32_bf16 v[72:75], v[198:201], v[190:193], v[72:75]
	v_mfma_f32_16x16x32_bf16 v[64:67], v[206:209], v[190:193], v[64:67]
	v_mfma_f32_16x16x32_bf16 v[120:123], v[202:205], v[170:173], v[120:123]
	v_mfma_f32_16x16x32_bf16 v[112:115], v[210:213], v[170:173], v[112:115]
	v_mfma_f32_16x16x32_bf16 v[104:107], v[202:205], v[178:181], v[104:107]
	v_mfma_f32_16x16x32_bf16 v[96:99], v[210:213], v[178:181], v[96:99]
	v_mfma_f32_16x16x32_bf16 v[88:91], v[202:205], v[186:189], v[88:91]
	v_mfma_f32_16x16x32_bf16 v[80:83], v[210:213], v[186:189], v[80:83]
	v_mfma_f32_16x16x32_bf16 v[72:75], v[202:205], v[194:197], v[72:75]
	v_mfma_f32_16x16x32_bf16 v[64:67], v[210:213], v[194:197], v[64:67]
	s_setprio 0
	s_mov_b32 m0, s22
	v_lshl_add_u64 v[214:215], v[218:219], 0, s[84:85]
	s_barrier
	ds_read_b128 v[166:169], v148 offset:49152
	ds_read_b128 v[170:173], v148 offset:50176
	ds_read_b128 v[174:177], v148 offset:51200
	ds_read_b128 v[178:181], v148 offset:52224
	ds_read_b128 v[182:185], v148 offset:53248
	ds_read_b128 v[186:189], v148 offset:54272
	ds_read_b128 v[190:193], v148 offset:55296
	ds_read_b128 v[194:197], v148 offset:56320
	global_load_lds_dwordx4 v[214:215], off
	v_lshl_add_u64 v[214:215], v[220:221], 0, s[84:85]
	s_mov_b32 m0, s23
	s_nop 0
	global_load_lds_dwordx4 v[214:215], off
	s_barrier
	s_waitcnt lgkmcnt(0)
	s_setprio 1
	s_waitcnt lgkmcnt(0)
	v_mfma_f32_16x16x32_bf16 v[60:63], v[150:153], v[166:169], v[60:63]
	v_mfma_f32_16x16x32_bf16 v[52:55], v[158:161], v[166:169], v[52:55]
	v_mfma_f32_16x16x32_bf16 v[44:47], v[150:153], v[174:177], v[44:47]
	v_mfma_f32_16x16x32_bf16 v[36:39], v[158:161], v[174:177], v[36:39]
	v_mfma_f32_16x16x32_bf16 v[28:31], v[150:153], v[182:185], v[28:31]
	v_mfma_f32_16x16x32_bf16 v[20:23], v[158:161], v[182:185], v[20:23]
	v_mfma_f32_16x16x32_bf16 v[12:15], v[150:153], v[190:193], v[12:15]
	v_mfma_f32_16x16x32_bf16 v[4:7], v[158:161], v[190:193], v[4:7]
	v_mfma_f32_16x16x32_bf16 v[60:63], v[154:157], v[170:173], v[60:63]
	v_mfma_f32_16x16x32_bf16 v[52:55], v[162:165], v[170:173], v[52:55]
	v_mfma_f32_16x16x32_bf16 v[44:47], v[154:157], v[178:181], v[44:47]
	v_mfma_f32_16x16x32_bf16 v[36:39], v[162:165], v[178:181], v[36:39]
	v_mfma_f32_16x16x32_bf16 v[28:31], v[154:157], v[186:189], v[28:31]
	v_mfma_f32_16x16x32_bf16 v[20:23], v[162:165], v[186:189], v[20:23]
	v_mfma_f32_16x16x32_bf16 v[12:15], v[154:157], v[194:197], v[12:15]
	v_mfma_f32_16x16x32_bf16 v[4:7], v[162:165], v[194:197], v[4:7]
	s_setprio 0
	s_barrier
	s_add_u32 s34, s90, 0x80080
	s_addc_u32 s35, s91, 0
	s_add_i32 s31, s92, s18
	v_lshl_add_u64 v[150:151], s[34:35], 0, v[128:129]
	s_mov_b32 m0, s31
	s_nop 0
	global_load_lds_dwordx4 v[150:151], off
	v_lshl_add_u64 v[150:151], s[34:35], 0, v[138:139]
	s_add_i32 m0, s31, 0x2000
	s_nop 0
	global_load_lds_dwordx4 v[150:151], off
	s_waitcnt vmcnt(6)
	s_barrier
	s_setprio 1
	v_mfma_f32_16x16x32_bf16 v[56:59], v[198:201], v[166:169], v[56:59]
	v_mfma_f32_16x16x32_bf16 v[48:51], v[206:209], v[166:169], v[48:51]
	v_mfma_f32_16x16x32_bf16 v[40:43], v[198:201], v[174:177], v[40:43]
	v_mfma_f32_16x16x32_bf16 v[32:35], v[206:209], v[174:177], v[32:35]
	v_mfma_f32_16x16x32_bf16 v[24:27], v[198:201], v[182:185], v[24:27]
	v_mfma_f32_16x16x32_bf16 v[16:19], v[206:209], v[182:185], v[16:19]
	v_mfma_f32_16x16x32_bf16 v[8:11], v[198:201], v[190:193], v[8:11]
	v_mfma_f32_16x16x32_bf16 v[0:3], v[206:209], v[190:193], v[0:3]
	v_mfma_f32_16x16x32_bf16 v[56:59], v[202:205], v[170:173], v[56:59]
	v_mfma_f32_16x16x32_bf16 v[48:51], v[210:213], v[170:173], v[48:51]
	v_mfma_f32_16x16x32_bf16 v[40:43], v[202:205], v[178:181], v[40:43]
	v_mfma_f32_16x16x32_bf16 v[32:35], v[210:213], v[178:181], v[32:35]
	v_mfma_f32_16x16x32_bf16 v[24:27], v[202:205], v[186:189], v[24:27]
	v_mfma_f32_16x16x32_bf16 v[16:19], v[210:213], v[186:189], v[16:19]
	v_mfma_f32_16x16x32_bf16 v[8:11], v[202:205], v[194:197], v[8:11]
	v_mfma_f32_16x16x32_bf16 v[0:3], v[210:213], v[194:197], v[0:3]
	s_setprio 0
	s_add_i32 s30, s30, 2
	s_add_u32 vcc_lo, vcc_lo, 0x100
	s_addc_u32 vcc_hi, vcc_hi, 0
	s_add_u32 s28, s28, 0x100
	s_addc_u32 s29, s29, 0
	s_cmp_gt_u32 s30, 29
	s_barrier
	s_cbranch_scc0 .LBB0_2229
	v_mul_f32_e32 v151, 0xbfb8aa3b, v124
	v_exp_f32_e32 v152, v151
	v_mul_f32_e32 v151, 0xbfb8aa3b, v125
	v_exp_f32_e32 v153, v151
	v_lshl_or_b32 v150, s25, 7, v147
	v_lshl_add_u32 v149, s94, 8, v145
	s_mov_b32 s25, s86
	v_pk_add_f32 v[152:153], v[152:153], 1.0 op_sel_hi:[1,0]
	s_mov_b32 s94, s88
	s_mov_b64 s[92:93], s[2:3]
	s_mov_b64 s[90:91], s[4:5]
	v_rcp_f32_e32 v153, v153
	s_nop 0
	s_nop 0
	v_rcp_f32_e32 v152, v152
	s_nop 0
	v_pk_mul_f32 v[124:125], v[124:125], v[152:153]
	s_nop 0
	v_pk_mul_f32 v[120:121], v[124:125], v[120:121]
	v_mul_f32_e32 v124, 0xbfb8aa3b, v126
	v_mul_f32_e32 v125, 0xbfb8aa3b, v127
	v_exp_f32_e32 v124, v124
	v_exp_f32_e32 v125, v125
	s_nop 0
	v_pk_add_f32 v[124:125], v[124:125], 1.0 op_sel_hi:[1,0]
	s_nop 0
	s_nop 0
	v_rcp_f32_e32 v125, v125
	s_nop 0
	s_nop 0
	v_rcp_f32_e32 v124, v124
	s_nop 0
	v_pk_mul_f32 v[124:125], v[126:127], v[124:125]
	v_ashrrev_i32_e32 v151, 31, v150
	v_pk_mul_f32 v[122:123], v[124:125], v[122:123]
	v_cvt_pk_bf16_f32 v124, v120, v121
	v_mov_b64_e32 v[120:121], s[82:83]
	v_cvt_pk_bf16_f32 v125, v122, v123
	v_mad_i64_i32 v[126:127], s[26:27], v149, s15, v[120:121]
	v_lshlrev_b64 v[122:123], 1, v[150:151]
	v_lshl_add_u64 v[150:151], v[126:127], 0, v[122:123]
	v_mul_f32_e32 v126, 0xbfb8aa3b, v116
	v_mul_f32_e32 v127, 0xbfb8aa3b, v117
	v_exp_f32_e32 v126, v126
	v_exp_f32_e32 v127, v127
	s_nop 0
	v_pk_add_f32 v[126:127], v[126:127], 1.0 op_sel_hi:[1,0]
	s_nop 0
	s_nop 0
	v_rcp_f32_e32 v127, v127
	s_nop 0
	s_nop 0
	v_rcp_f32_e32 v126, v126
	s_nop 0
	v_pk_mul_f32 v[116:117], v[116:117], v[126:127]
	s_nop 0
	v_pk_mul_f32 v[112:113], v[116:117], v[112:113]
	v_mul_f32_e32 v116, 0xbfb8aa3b, v118
	v_mul_f32_e32 v117, 0xbfb8aa3b, v119
	v_exp_f32_e32 v116, v116
	v_exp_f32_e32 v117, v117
	s_nop 0
	v_pk_add_f32 v[116:117], v[116:117], 1.0 op_sel_hi:[1,0]
	s_nop 0
	s_nop 0
	v_rcp_f32_e32 v117, v117
	s_nop 0
	s_nop 0
	v_rcp_f32_e32 v116, v116
	s_nop 0
	v_cvt_pk_bf16_f32 v126, v112, v113
	v_mul_f32_e32 v112, 0xbfb8aa3b, v108
	v_mul_f32_e32 v113, 0xbfb8aa3b, v109
	v_exp_f32_e32 v112, v112
	v_exp_f32_e32 v113, v113
	v_pk_mul_f32 v[116:117], v[118:119], v[116:117]
	v_pk_add_f32 v[112:113], v[112:113], 1.0 op_sel_hi:[1,0]
	v_pk_mul_f32 v[114:115], v[116:117], v[114:115]
	s_nop 0
	v_cvt_pk_bf16_f32 v127, v114, v115
	v_or_b32_e32 v114, 16, v149
	global_store_dwordx4 v[150:151], v[124:127], off
	v_rcp_f32_e32 v113, v113
	s_nop 0
	s_nop 0
	v_rcp_f32_e32 v112, v112
	s_nop 0
	v_pk_mul_f32 v[108:109], v[108:109], v[112:113]
	s_nop 0
	v_pk_mul_f32 v[104:105], v[108:109], v[104:105]
	v_mul_f32_e32 v108, 0xbfb8aa3b, v110
	v_mul_f32_e32 v109, 0xbfb8aa3b, v111
	v_exp_f32_e32 v108, v108
	v_exp_f32_e32 v109, v109
	v_cvt_pk_bf16_f32 v104, v104, v105
	v_pk_add_f32 v[108:109], v[108:109], 1.0 op_sel_hi:[1,0]
	s_nop 0
	s_nop 0
	v_rcp_f32_e32 v109, v109
	s_nop 0
	s_nop 0
	v_rcp_f32_e32 v108, v108
	s_nop 0
	v_pk_mul_f32 v[108:109], v[110:111], v[108:109]
	s_nop 0
	v_pk_mul_f32 v[106:107], v[108:109], v[106:107]
	s_nop 0
	v_cvt_pk_bf16_f32 v105, v106, v107
	v_mad_i64_i32 v[106:107], s[26:27], v114, s15, v[120:121]
	v_lshl_add_u64 v[108:109], v[106:107], 0, v[122:123]
	v_mul_f32_e32 v106, 0xbfb8aa3b, v100
	v_mul_f32_e32 v107, 0xbfb8aa3b, v101
	v_exp_f32_e32 v106, v106
	v_exp_f32_e32 v107, v107
	s_nop 0
	v_pk_add_f32 v[106:107], v[106:107], 1.0 op_sel_hi:[1,0]
	s_nop 0
	s_nop 0
	v_rcp_f32_e32 v107, v107
	s_nop 0
	s_nop 0
	v_rcp_f32_e32 v106, v106
	s_nop 0
	v_pk_mul_f32 v[100:101], v[100:101], v[106:107]
	s_nop 0
	v_pk_mul_f32 v[96:97], v[100:101], v[96:97]
	v_mul_f32_e32 v100, 0xbfb8aa3b, v102
	v_mul_f32_e32 v101, 0xbfb8aa3b, v103
	v_exp_f32_e32 v100, v100
	v_exp_f32_e32 v101, v101
	s_nop 0
	v_pk_add_f32 v[100:101], v[100:101], 1.0 op_sel_hi:[1,0]
	s_nop 0
	s_nop 0
	v_rcp_f32_e32 v101, v101
	s_nop 0
	s_nop 0
	v_rcp_f32_e32 v100, v100
	s_nop 0
	v_cvt_pk_bf16_f32 v106, v96, v97
	v_mul_f32_e32 v96, 0xbfb8aa3b, v92
	v_mul_f32_e32 v97, 0xbfb8aa3b, v93
	v_exp_f32_e32 v96, v96
	v_exp_f32_e32 v97, v97
	v_pk_mul_f32 v[100:101], v[102:103], v[100:101]
	v_pk_add_f32 v[96:97], v[96:97], 1.0 op_sel_hi:[1,0]
	v_pk_mul_f32 v[98:99], v[100:101], v[98:99]
	s_nop 0
	v_cvt_pk_bf16_f32 v107, v98, v99
	v_or_b32_e32 v98, 32, v149
	global_store_dwordx4 v[108:109], v[104:107], off
	v_rcp_f32_e32 v97, v97
	s_nop 0
	s_nop 0
	v_rcp_f32_e32 v96, v96
	s_nop 0
	v_pk_mul_f32 v[92:93], v[92:93], v[96:97]
	s_nop 0
	v_pk_mul_f32 v[88:89], v[92:93], v[88:89]
	v_mul_f32_e32 v92, 0xbfb8aa3b, v94
	v_mul_f32_e32 v93, 0xbfb8aa3b, v95
	v_exp_f32_e32 v92, v92
	v_exp_f32_e32 v93, v93
	v_cvt_pk_bf16_f32 v88, v88, v89
	v_pk_add_f32 v[92:93], v[92:93], 1.0 op_sel_hi:[1,0]
	s_nop 0
	s_nop 0
	v_rcp_f32_e32 v93, v93
	s_nop 0
	s_nop 0
	v_rcp_f32_e32 v92, v92
	s_nop 0
	v_pk_mul_f32 v[92:93], v[94:95], v[92:93]
	s_nop 0
	v_pk_mul_f32 v[90:91], v[92:93], v[90:91]
	s_nop 0
	v_cvt_pk_bf16_f32 v89, v90, v91
	v_mad_i64_i32 v[90:91], s[26:27], v98, s15, v[120:121]
	v_lshl_add_u64 v[92:93], v[90:91], 0, v[122:123]
	v_mul_f32_e32 v90, 0xbfb8aa3b, v84
	v_mul_f32_e32 v91, 0xbfb8aa3b, v85
	v_exp_f32_e32 v90, v90
	v_exp_f32_e32 v91, v91
	s_nop 0
	v_pk_add_f32 v[90:91], v[90:91], 1.0 op_sel_hi:[1,0]
	s_nop 0
	s_nop 0
	v_rcp_f32_e32 v91, v91
	s_nop 0
	s_nop 0
	v_rcp_f32_e32 v90, v90
	s_nop 0
	v_pk_mul_f32 v[84:85], v[84:85], v[90:91]
	s_nop 0
	v_pk_mul_f32 v[80:81], v[84:85], v[80:81]
	v_mul_f32_e32 v84, 0xbfb8aa3b, v86
	v_mul_f32_e32 v85, 0xbfb8aa3b, v87
	v_exp_f32_e32 v84, v84
	v_exp_f32_e32 v85, v85
	s_nop 0
	v_pk_add_f32 v[84:85], v[84:85], 1.0 op_sel_hi:[1,0]
	s_nop 0
	s_nop 0
	v_rcp_f32_e32 v85, v85
	s_nop 0
	s_nop 0
	v_rcp_f32_e32 v84, v84
	s_nop 0
	v_cvt_pk_bf16_f32 v90, v80, v81
	v_mul_f32_e32 v80, 0xbfb8aa3b, v76
	v_mul_f32_e32 v81, 0xbfb8aa3b, v77
	v_exp_f32_e32 v80, v80
	v_exp_f32_e32 v81, v81
	v_pk_mul_f32 v[84:85], v[86:87], v[84:85]
	v_pk_add_f32 v[80:81], v[80:81], 1.0 op_sel_hi:[1,0]
	v_pk_mul_f32 v[82:83], v[84:85], v[82:83]
	s_nop 0
	v_cvt_pk_bf16_f32 v91, v82, v83
	v_or_b32_e32 v82, 48, v149
	global_store_dwordx4 v[92:93], v[88:91], off
	v_rcp_f32_e32 v81, v81
	s_nop 0
	s_nop 0
	v_rcp_f32_e32 v80, v80
	s_nop 0
	v_pk_mul_f32 v[76:77], v[76:77], v[80:81]
	s_nop 0
	v_pk_mul_f32 v[72:73], v[76:77], v[72:73]
	v_mul_f32_e32 v76, 0xbfb8aa3b, v78
	v_mul_f32_e32 v77, 0xbfb8aa3b, v79
	v_exp_f32_e32 v76, v76
	v_exp_f32_e32 v77, v77
	v_cvt_pk_bf16_f32 v72, v72, v73
	v_pk_add_f32 v[76:77], v[76:77], 1.0 op_sel_hi:[1,0]
	s_nop 0
	s_nop 0
	v_rcp_f32_e32 v77, v77
	s_nop 0
	s_nop 0
	v_rcp_f32_e32 v76, v76
	s_nop 0
	v_pk_mul_f32 v[76:77], v[78:79], v[76:77]
	s_nop 0
	v_pk_mul_f32 v[74:75], v[76:77], v[74:75]
	s_nop 0
	v_cvt_pk_bf16_f32 v73, v74, v75
	v_mad_i64_i32 v[74:75], s[26:27], v82, s15, v[120:121]
	v_lshl_add_u64 v[76:77], v[74:75], 0, v[122:123]
	v_mul_f32_e32 v74, 0xbfb8aa3b, v68
	v_mul_f32_e32 v75, 0xbfb8aa3b, v69
	v_exp_f32_e32 v74, v74
	v_exp_f32_e32 v75, v75
	s_nop 0
	v_pk_add_f32 v[74:75], v[74:75], 1.0 op_sel_hi:[1,0]
	s_nop 0
	s_nop 0
	v_rcp_f32_e32 v75, v75
	s_nop 0
	s_nop 0
	v_rcp_f32_e32 v74, v74
	s_nop 0
	v_pk_mul_f32 v[68:69], v[68:69], v[74:75]
	s_nop 0
	v_pk_mul_f32 v[64:65], v[68:69], v[64:65]
	v_mul_f32_e32 v68, 0xbfb8aa3b, v70
	v_mul_f32_e32 v69, 0xbfb8aa3b, v71
	v_exp_f32_e32 v68, v68
	v_exp_f32_e32 v69, v69
	s_nop 0
	v_pk_add_f32 v[68:69], v[68:69], 1.0 op_sel_hi:[1,0]
	s_nop 0
	s_nop 0
	v_rcp_f32_e32 v69, v69
	s_nop 0
	s_nop 0
	v_rcp_f32_e32 v68, v68
	s_nop 0
	v_cvt_pk_bf16_f32 v74, v64, v65
	v_mul_f32_e32 v64, 0xbfb8aa3b, v60
	v_mul_f32_e32 v65, 0xbfb8aa3b, v61
	v_exp_f32_e32 v64, v64
	v_exp_f32_e32 v65, v65
	v_pk_mul_f32 v[68:69], v[70:71], v[68:69]
	v_pk_add_f32 v[64:65], v[64:65], 1.0 op_sel_hi:[1,0]
	v_pk_mul_f32 v[66:67], v[68:69], v[66:67]
	s_nop 0
	v_cvt_pk_bf16_f32 v75, v66, v67
	v_add_u32_e32 v66, 0x80, v149
	global_store_dwordx4 v[76:77], v[72:75], off
	v_rcp_f32_e32 v65, v65
	s_nop 0
	s_nop 0
	v_rcp_f32_e32 v64, v64
	s_nop 0
	v_pk_mul_f32 v[60:61], v[60:61], v[64:65]
	s_nop 0
	v_pk_mul_f32 v[56:57], v[60:61], v[56:57]
	v_mul_f32_e32 v60, 0xbfb8aa3b, v62
	v_mul_f32_e32 v61, 0xbfb8aa3b, v63
	v_exp_f32_e32 v60, v60
	v_exp_f32_e32 v61, v61
	v_cvt_pk_bf16_f32 v56, v56, v57
	v_pk_add_f32 v[60:61], v[60:61], 1.0 op_sel_hi:[1,0]
	s_nop 0
	s_nop 0
	v_rcp_f32_e32 v61, v61
	s_nop 0
	s_nop 0
	v_rcp_f32_e32 v60, v60
	s_nop 0
	v_pk_mul_f32 v[60:61], v[62:63], v[60:61]
	s_nop 0
	v_pk_mul_f32 v[58:59], v[60:61], v[58:59]
	s_nop 0
	v_cvt_pk_bf16_f32 v57, v58, v59
	v_mad_i64_i32 v[58:59], s[26:27], v66, s15, v[120:121]
	v_lshl_add_u64 v[60:61], v[58:59], 0, v[122:123]
	v_mul_f32_e32 v58, 0xbfb8aa3b, v52
	v_mul_f32_e32 v59, 0xbfb8aa3b, v53
	v_exp_f32_e32 v58, v58
	v_exp_f32_e32 v59, v59
	s_nop 0
	v_pk_add_f32 v[58:59], v[58:59], 1.0 op_sel_hi:[1,0]
	s_nop 0
	s_nop 0
	v_rcp_f32_e32 v59, v59
	s_nop 0
	s_nop 0
	v_rcp_f32_e32 v58, v58
	s_nop 0
	v_pk_mul_f32 v[52:53], v[52:53], v[58:59]
	s_nop 0
	v_pk_mul_f32 v[48:49], v[52:53], v[48:49]
	v_mul_f32_e32 v52, 0xbfb8aa3b, v54
	v_mul_f32_e32 v53, 0xbfb8aa3b, v55
	v_exp_f32_e32 v52, v52
	v_exp_f32_e32 v53, v53
	s_nop 0
	v_pk_add_f32 v[52:53], v[52:53], 1.0 op_sel_hi:[1,0]
	s_nop 0
	s_nop 0
	v_rcp_f32_e32 v53, v53
	s_nop 0
	s_nop 0
	v_rcp_f32_e32 v52, v52
	s_nop 0
	v_cvt_pk_bf16_f32 v58, v48, v49
	v_mul_f32_e32 v48, 0xbfb8aa3b, v44
	v_mul_f32_e32 v49, 0xbfb8aa3b, v45
	v_exp_f32_e32 v48, v48
	v_exp_f32_e32 v49, v49
	v_pk_mul_f32 v[52:53], v[54:55], v[52:53]
	v_pk_add_f32 v[48:49], v[48:49], 1.0 op_sel_hi:[1,0]
	v_pk_mul_f32 v[50:51], v[52:53], v[50:51]
	s_nop 0
	v_cvt_pk_bf16_f32 v59, v50, v51
	v_add_u32_e32 v50, 0x90, v149
	global_store_dwordx4 v[60:61], v[56:59], off
	v_rcp_f32_e32 v49, v49
	s_nop 0
	s_nop 0
	v_rcp_f32_e32 v48, v48
	s_nop 0
	v_pk_mul_f32 v[44:45], v[44:45], v[48:49]
	s_nop 0
	v_pk_mul_f32 v[40:41], v[44:45], v[40:41]
	v_mul_f32_e32 v44, 0xbfb8aa3b, v46
	v_mul_f32_e32 v45, 0xbfb8aa3b, v47
	v_exp_f32_e32 v44, v44
	v_exp_f32_e32 v45, v45
	v_cvt_pk_bf16_f32 v40, v40, v41
	v_pk_add_f32 v[44:45], v[44:45], 1.0 op_sel_hi:[1,0]
	s_nop 0
	s_nop 0
	v_rcp_f32_e32 v45, v45
	s_nop 0
	s_nop 0
	v_rcp_f32_e32 v44, v44
	s_nop 0
	v_pk_mul_f32 v[44:45], v[46:47], v[44:45]
	s_nop 0
	v_pk_mul_f32 v[42:43], v[44:45], v[42:43]
	s_nop 0
	v_cvt_pk_bf16_f32 v41, v42, v43
	v_mad_i64_i32 v[42:43], s[26:27], v50, s15, v[120:121]
	v_lshl_add_u64 v[44:45], v[42:43], 0, v[122:123]
	v_mul_f32_e32 v42, 0xbfb8aa3b, v36
	v_mul_f32_e32 v43, 0xbfb8aa3b, v37
	v_exp_f32_e32 v42, v42
	v_exp_f32_e32 v43, v43
	s_nop 0
	v_pk_add_f32 v[42:43], v[42:43], 1.0 op_sel_hi:[1,0]
	s_nop 0
	s_nop 0
	v_rcp_f32_e32 v43, v43
	s_nop 0
	s_nop 0
	v_rcp_f32_e32 v42, v42
	s_nop 0
	v_pk_mul_f32 v[36:37], v[36:37], v[42:43]
	s_nop 0
	v_pk_mul_f32 v[32:33], v[36:37], v[32:33]
	v_mul_f32_e32 v36, 0xbfb8aa3b, v38
	v_mul_f32_e32 v37, 0xbfb8aa3b, v39
	v_exp_f32_e32 v36, v36
	v_exp_f32_e32 v37, v37
	s_nop 0
	v_pk_add_f32 v[36:37], v[36:37], 1.0 op_sel_hi:[1,0]
	s_nop 0
	s_nop 0
	v_rcp_f32_e32 v37, v37
	s_nop 0
	s_nop 0
	v_rcp_f32_e32 v36, v36
	s_nop 0
	v_cvt_pk_bf16_f32 v42, v32, v33
	v_mul_f32_e32 v32, 0xbfb8aa3b, v28
	v_mul_f32_e32 v33, 0xbfb8aa3b, v29
	v_exp_f32_e32 v32, v32
	v_exp_f32_e32 v33, v33
	v_pk_mul_f32 v[36:37], v[38:39], v[36:37]
	v_pk_add_f32 v[32:33], v[32:33], 1.0 op_sel_hi:[1,0]
	v_pk_mul_f32 v[34:35], v[36:37], v[34:35]
	s_nop 0
	v_cvt_pk_bf16_f32 v43, v34, v35
	v_add_u32_e32 v34, 0xa0, v149
	global_store_dwordx4 v[44:45], v[40:43], off
	v_rcp_f32_e32 v33, v33
	s_nop 0
	s_nop 0
	v_rcp_f32_e32 v32, v32
	s_nop 0
	v_pk_mul_f32 v[28:29], v[28:29], v[32:33]
	s_nop 0
	v_pk_mul_f32 v[24:25], v[28:29], v[24:25]
	v_mul_f32_e32 v28, 0xbfb8aa3b, v30
	v_mul_f32_e32 v29, 0xbfb8aa3b, v31
	v_exp_f32_e32 v28, v28
	v_exp_f32_e32 v29, v29
	v_cvt_pk_bf16_f32 v24, v24, v25
	v_pk_add_f32 v[28:29], v[28:29], 1.0 op_sel_hi:[1,0]
	s_nop 0
	s_nop 0
	v_rcp_f32_e32 v29, v29
	s_nop 0
	s_nop 0
	v_rcp_f32_e32 v28, v28
	s_nop 0
	v_pk_mul_f32 v[28:29], v[30:31], v[28:29]
	s_nop 0
	v_pk_mul_f32 v[26:27], v[28:29], v[26:27]
	s_nop 0
	v_cvt_pk_bf16_f32 v25, v26, v27
	v_mad_i64_i32 v[26:27], s[26:27], v34, s15, v[120:121]
	v_lshl_add_u64 v[28:29], v[26:27], 0, v[122:123]
	v_mul_f32_e32 v26, 0xbfb8aa3b, v20
	v_mul_f32_e32 v27, 0xbfb8aa3b, v21
	v_exp_f32_e32 v26, v26
	v_exp_f32_e32 v27, v27
	s_nop 0
	v_pk_add_f32 v[26:27], v[26:27], 1.0 op_sel_hi:[1,0]
	s_nop 0
	s_nop 0
	v_rcp_f32_e32 v27, v27
	s_nop 0
	s_nop 0
	v_rcp_f32_e32 v26, v26
	s_nop 0
	v_pk_mul_f32 v[20:21], v[20:21], v[26:27]
	s_nop 0
	v_pk_mul_f32 v[16:17], v[20:21], v[16:17]
	v_mul_f32_e32 v20, 0xbfb8aa3b, v22
	v_mul_f32_e32 v21, 0xbfb8aa3b, v23
	v_exp_f32_e32 v20, v20
	v_exp_f32_e32 v21, v21
	s_nop 0
	v_pk_add_f32 v[20:21], v[20:21], 1.0 op_sel_hi:[1,0]
	s_nop 0
	s_nop 0
	v_rcp_f32_e32 v21, v21
	s_nop 0
	s_nop 0
	v_rcp_f32_e32 v20, v20
	s_nop 0
	v_cvt_pk_bf16_f32 v26, v16, v17
	v_mul_f32_e32 v16, 0xbfb8aa3b, v12
	v_mul_f32_e32 v17, 0xbfb8aa3b, v13
	v_exp_f32_e32 v16, v16
	v_exp_f32_e32 v17, v17
	v_pk_mul_f32 v[20:21], v[22:23], v[20:21]
	v_pk_add_f32 v[16:17], v[16:17], 1.0 op_sel_hi:[1,0]
	v_pk_mul_f32 v[18:19], v[20:21], v[18:19]
	s_nop 0
	v_cvt_pk_bf16_f32 v27, v18, v19
	v_add_u32_e32 v18, 0xb0, v149
	global_store_dwordx4 v[28:29], v[24:27], off
	v_rcp_f32_e32 v17, v17
	s_nop 0
	s_nop 0
	v_rcp_f32_e32 v16, v16
	s_nop 0
	v_pk_mul_f32 v[12:13], v[12:13], v[16:17]
	s_nop 0
	v_pk_mul_f32 v[8:9], v[12:13], v[8:9]
	v_mul_f32_e32 v12, 0xbfb8aa3b, v14
	v_mul_f32_e32 v13, 0xbfb8aa3b, v15
	v_exp_f32_e32 v12, v12
	v_exp_f32_e32 v13, v13
	v_cvt_pk_bf16_f32 v8, v8, v9
	v_pk_add_f32 v[12:13], v[12:13], 1.0 op_sel_hi:[1,0]
	s_nop 0
	s_nop 0
	v_rcp_f32_e32 v13, v13
	s_nop 0
	s_nop 0
	v_rcp_f32_e32 v12, v12
	s_nop 0
	v_pk_mul_f32 v[12:13], v[14:15], v[12:13]
	s_nop 0
	v_pk_mul_f32 v[10:11], v[12:13], v[10:11]
	s_nop 0
	v_cvt_pk_bf16_f32 v9, v10, v11
	v_mad_i64_i32 v[10:11], s[26:27], v18, s15, v[120:121]
	v_lshl_add_u64 v[12:13], v[10:11], 0, v[122:123]
	v_mul_f32_e32 v10, 0xbfb8aa3b, v4
	v_mul_f32_e32 v11, 0xbfb8aa3b, v5
	v_exp_f32_e32 v10, v10
	v_exp_f32_e32 v11, v11
	s_nop 0
	v_pk_add_f32 v[10:11], v[10:11], 1.0 op_sel_hi:[1,0]
	s_nop 0
	s_nop 0
	v_rcp_f32_e32 v11, v11
	s_nop 0
	s_nop 0
	v_rcp_f32_e32 v10, v10
	s_nop 0
	v_pk_mul_f32 v[4:5], v[4:5], v[10:11]
	s_nop 0
	v_pk_mul_f32 v[0:1], v[4:5], v[0:1]
	v_mul_f32_e32 v4, 0xbfb8aa3b, v6
	v_mul_f32_e32 v5, 0xbfb8aa3b, v7
	v_exp_f32_e32 v4, v4
	v_exp_f32_e32 v5, v5
	s_nop 0
	v_pk_add_f32 v[4:5], v[4:5], 1.0 op_sel_hi:[1,0]
	s_nop 0
	s_nop 0
	v_rcp_f32_e32 v5, v5
	s_nop 0
	s_nop 0
	v_rcp_f32_e32 v4, v4
	s_nop 0
	v_pk_mul_f32 v[4:5], v[6:7], v[4:5]
	v_cvt_pk_bf16_f32 v10, v0, v1
	v_pk_mul_f32 v[2:3], v[4:5], v[2:3]
	s_and_b64 vcc, exec, s[36:37]
	v_cvt_pk_bf16_f32 v11, v2, v3
	global_store_dwordx4 v[12:13], v[8:11], off
	s_cbranch_vccz .LBB0_2222
	s_waitcnt vmcnt(0)
	s_cmpk_gt_u32 s16, 0xff
	s_cbranch_scc1 .LBB0_2158
	s_barrier
	s_branch .LBB0_2158
